# all s_setprio removed from the GEMM K-loops (A/B against the version that keeps one raise per 32-MFMA block)
# baseline (speedup 1.0000x reference)
; #define PG8_STAGE(bufoff, gbase, voff) do { _Pragma("unroll") for (int _i = 0; _i < 2; ++_i) \
;         __builtin_amdgcn_global_load_lds((const unsigned*)((const char*)(gbase) + (voff)[_i]), (PG8_LAS unsigned*)(lds + (bufoff) + ldsw + _i * 8192), 16, 0, 0); } while (0)
; #define PG8_LDA(dst, b, h) do { _Pragma("unroll") for (int m = 0; m < 4; ++m) _Pragma("unroll") for (int k = 0; k < 2; ++k) dst[m][k] = *(const PG8_LAS bf16x8*)(lds + PG8_SA(b, h) + aoff + m * 2048 + k * 1024); } while (0)
; #define PG8_LDB(dst, b, h) do { _Pragma("unroll") for (int n = 0; n < 2; ++n) _Pragma("unroll") for (int k = 0; k < 2; ++k) dst[n][k] = *(const PG8_LAS bf16x8*)(lds + PG8_SB(b, h) + boff + n * 2048 + k * 1024); } while (0)
; #define PG8_MMA(ai, bj, At, Bt) do { __builtin_amdgcn_s_setprio(1); _Pragma("unroll") for (int m = 0; m < 4; ++m) _Pragma("unroll") for (int n = 0; n < 2; ++n) _Pragma("unroll") for (int k = 0; k < 2; ++k) \
;         acc[ai][bj][m][n] = __builtin_amdgcn_mfma_f32_16x16x32_bf16(Bt[n][k], At[m][k], acc[ai][bj][m][n], 0, 0, 0); __builtin_amdgcn_s_setprio(0); } while (0)
; #define PG8_WAIT_V(n) asm volatile("s_waitcnt vmcnt(" #n ")" ::: "memory")
; #define PG8_WAIT_L(n) asm volatile("s_waitcnt lgkmcnt(" #n ")" ::: "memory")
; #define PG8_BAR __builtin_amdgcn_s_barrier()
; #define PG8_SCHED __builtin_amdgcn_sched_barrier(0)
; template <class Epi, class Sched, bool ALIGN_EPI = false, bool SP2 = false>
; __device__ __forceinline__ void gemm_phase(PG8_LAS unsigned char* lds, const Gemm g, const Sched& S, const Epi& E) {
;     ...
;             PG8_LDB(B0, 0, 0); PG8_LDB(B1, 0, 1); PG8_SCHED; PG8_LDA(At, 0, 0); PG8_STAGE(PG8_SA(1, 1), a1 + hstep, voffA);
;             PG8_WAIT_V(8); PG8_WAIT_L(0); PG8_BAR; PG8_MMA(0, 0, At, B0); PG8_MMA(0, 1, At, B1); PG8_BAR; PG8_SCHED;
;             PG8_LDA(At, 0, 1); PG8_STAGE(PG8_SB(0, 0), b2, voffB); PG8_STAGE(PG8_SB(0, 1), b2 + hstep, voffB); PG8_STAGE(PG8_SA(0, 0), a2, voffA);
;             PG8_WAIT_V(8); PG8_WAIT_L(0); PG8_BAR; PG8_MMA(1, 0, At, B0); PG8_MMA(1, 1, At, B1); PG8_BAR; PG8_SCHED;
.LBB0_96:
	ds_read_b128 v[128:131], v178
	ds_read_b128 v[132:135], v178 offset:1024
	ds_read_b128 v[136:139], v178 offset:2048
	ds_read_b128 v[140:143], v178 offset:3072
	ds_read_b128 v[166:169], v179
	ds_read_b128 v[170:173], v179 offset:1024
	ds_read_b128 v[190:193], v179 offset:2048
	ds_read_b128 v[194:197], v179 offset:3072
	s_add_u32 s36, s80, 0xfffc0080
	s_addc_u32 s37, s81, -1
	s_cmp_eq_u32 s35, 12
	s_cselect_b32 s87, s8, s37
	s_cselect_b32 s86, s55, s36
	s_cselect_b32 s83, s49, s34
	s_cselect_b32 s82, vcc_lo, vcc_hi
	s_add_i32 m0, s93, 0xc000
	ds_read_b128 v[198:201], v181
	ds_read_b128 v[202:205], v181 offset:1024
	ds_read_b128 v[206:209], v181 offset:2048
	ds_read_b128 v[210:213], v181 offset:3072
	ds_read_b128 v[214:217], v181 offset:4096
	ds_read_b128 v[218:221], v181 offset:5120
	ds_read_b128 v[222:225], v181 offset:6144
	ds_read_b128 v[226:229], v181 offset:7168
	global_load_lds_dwordx4 v158, s[80:81]
	s_add_i32 m0, s93, 0xe000
	s_nop 0
	global_load_lds_dwordx4 v160, s[80:81]
	s_waitcnt vmcnt(8)
	s_waitcnt lgkmcnt(0)
	s_barrier
	v_mfma_f32_16x16x32_bf16 v[124:127], v[128:131], v[198:201], v[124:127]
	v_mfma_f32_16x16x32_bf16 v[120:123], v[136:139], v[198:201], v[120:123]
	v_mfma_f32_16x16x32_bf16 v[108:111], v[128:131], v[206:209], v[108:111]
	v_mfma_f32_16x16x32_bf16 v[104:107], v[136:139], v[206:209], v[104:107]
	v_mfma_f32_16x16x32_bf16 v[92:95], v[128:131], v[214:217], v[92:95]
	v_mfma_f32_16x16x32_bf16 v[88:91], v[136:139], v[214:217], v[88:91]
	v_mfma_f32_16x16x32_bf16 v[76:79], v[128:131], v[222:225], v[76:79]
	v_mfma_f32_16x16x32_bf16 v[72:75], v[136:139], v[222:225], v[72:75]
	v_mfma_f32_16x16x32_bf16 v[124:127], v[132:135], v[202:205], v[124:127]
	v_mfma_f32_16x16x32_bf16 v[120:123], v[140:143], v[202:205], v[120:123]
	v_mfma_f32_16x16x32_bf16 v[108:111], v[132:135], v[210:213], v[108:111]
	v_mfma_f32_16x16x32_bf16 v[104:107], v[140:143], v[210:213], v[104:107]
	v_mfma_f32_16x16x32_bf16 v[92:95], v[132:135], v[218:221], v[92:95]
	v_mfma_f32_16x16x32_bf16 v[88:91], v[140:143], v[218:221], v[88:91]
	v_mfma_f32_16x16x32_bf16 v[76:79], v[132:135], v[226:229], v[76:79]
	v_mfma_f32_16x16x32_bf16 v[72:75], v[140:143], v[226:229], v[72:75]
	v_mfma_f32_16x16x32_bf16 v[116:119], v[166:169], v[198:201], v[116:119]
	v_mfma_f32_16x16x32_bf16 v[112:115], v[190:193], v[198:201], v[112:115]
	v_mfma_f32_16x16x32_bf16 v[100:103], v[166:169], v[206:209], v[100:103]
	v_mfma_f32_16x16x32_bf16 v[96:99], v[190:193], v[206:209], v[96:99]
	v_mfma_f32_16x16x32_bf16 v[84:87], v[166:169], v[214:217], v[84:87]
	v_mfma_f32_16x16x32_bf16 v[80:83], v[190:193], v[214:217], v[80:83]
	v_mfma_f32_16x16x32_bf16 v[68:71], v[166:169], v[222:225], v[68:71]
	v_mfma_f32_16x16x32_bf16 v[64:67], v[190:193], v[222:225], v[64:67]
	v_mfma_f32_16x16x32_bf16 v[116:119], v[170:173], v[202:205], v[116:119]
	v_mfma_f32_16x16x32_bf16 v[112:115], v[194:197], v[202:205], v[112:115]
	v_mfma_f32_16x16x32_bf16 v[100:103], v[170:173], v[210:213], v[100:103]
	v_mfma_f32_16x16x32_bf16 v[96:99], v[194:197], v[210:213], v[96:99]
	v_mfma_f32_16x16x32_bf16 v[84:87], v[170:173], v[218:221], v[84:87]
	v_mfma_f32_16x16x32_bf16 v[80:83], v[194:197], v[218:221], v[80:83]
	v_mfma_f32_16x16x32_bf16 v[68:71], v[170:173], v[226:229], v[68:71]
	v_mfma_f32_16x16x32_bf16 v[64:67], v[194:197], v[226:229], v[64:67]
	s_barrier
	s_add_i32 s36, s23, s90
	v_lshl_add_u64 v[174:175], s[82:83], 0, v[148:149]
	s_mov_b32 m0, s36
	ds_read_b128 v[198:201], v181 offset:16384
	ds_read_b128 v[202:205], v181 offset:17408
	ds_read_b128 v[206:209], v181 offset:18432
	ds_read_b128 v[210:213], v181 offset:19456
	ds_read_b128 v[214:217], v181 offset:20480
	ds_read_b128 v[218:221], v181 offset:21504
	ds_read_b128 v[222:225], v181 offset:22528
	ds_read_b128 v[226:229], v181 offset:23552
	global_load_lds_dwordx4 v[174:175], off
	s_add_i32 m0, s36, 0x2000
	s_add_u32 s36, s82, 0x40000
	v_lshl_add_u64 v[186:187], s[82:83], 0, v[144:145]
	s_addc_u32 s37, s83, 0
	s_add_i32 s20, s41, s90
	global_load_lds_dwordx4 v[186:187], off
	s_mov_b32 m0, s20
	v_lshl_add_u64 v[232:233], s[86:87], 0, v[146:147]
	global_load_lds_dwordx4 v148, s[36:37]
	s_add_i32 m0, s20, 0x2000
	s_nop 0
	global_load_lds_dwordx4 v144, s[36:37]
	v_lshl_add_u64 v[230:231], s[86:87], 0, v[150:151]
	s_mov_b32 m0, s93
	s_nop 0
	global_load_lds_dwordx4 v[230:231], off
	s_mov_b32 m0, s94
	s_nop 0
	global_load_lds_dwordx4 v[232:233], off
	s_waitcnt vmcnt(8)
	s_waitcnt lgkmcnt(0)
	s_barrier
	v_mfma_f32_16x16x32_bf16 v[60:63], v[128:131], v[198:201], v[60:63]
	v_mfma_f32_16x16x32_bf16 v[56:59], v[136:139], v[198:201], v[56:59]
	v_mfma_f32_16x16x32_bf16 v[44:47], v[128:131], v[206:209], v[44:47]
	v_mfma_f32_16x16x32_bf16 v[40:43], v[136:139], v[206:209], v[40:43]
	v_mfma_f32_16x16x32_bf16 v[28:31], v[128:131], v[214:217], v[28:31]
	v_mfma_f32_16x16x32_bf16 v[24:27], v[136:139], v[214:217], v[24:27]
	v_mfma_f32_16x16x32_bf16 v[12:15], v[128:131], v[222:225], v[12:15]
	v_mfma_f32_16x16x32_bf16 v[8:11], v[136:139], v[222:225], v[8:11]
	v_mfma_f32_16x16x32_bf16 v[60:63], v[132:135], v[202:205], v[60:63]
	v_mfma_f32_16x16x32_bf16 v[56:59], v[140:143], v[202:205], v[56:59]
	v_mfma_f32_16x16x32_bf16 v[44:47], v[132:135], v[210:213], v[44:47]
	v_mfma_f32_16x16x32_bf16 v[40:43], v[140:143], v[210:213], v[40:43]
	v_mfma_f32_16x16x32_bf16 v[28:31], v[132:135], v[218:221], v[28:31]
	v_mfma_f32_16x16x32_bf16 v[24:27], v[140:143], v[218:221], v[24:27]
	v_mfma_f32_16x16x32_bf16 v[12:15], v[132:135], v[226:229], v[12:15]
	v_mfma_f32_16x16x32_bf16 v[8:11], v[140:143], v[226:229], v[8:11]
	v_mfma_f32_16x16x32_bf16 v[52:55], v[166:169], v[198:201], v[52:55]
	v_mfma_f32_16x16x32_bf16 v[48:51], v[190:193], v[198:201], v[48:51]
	v_mfma_f32_16x16x32_bf16 v[36:39], v[166:169], v[206:209], v[36:39]
	v_mfma_f32_16x16x32_bf16 v[32:35], v[190:193], v[206:209], v[32:35]
	v_mfma_f32_16x16x32_bf16 v[20:23], v[166:169], v[214:217], v[20:23]
	v_mfma_f32_16x16x32_bf16 v[16:19], v[190:193], v[214:217], v[16:19]
	v_mfma_f32_16x16x32_bf16 v[4:7], v[166:169], v[222:225], v[4:7]
	v_mfma_f32_16x16x32_bf16 v[0:3], v[190:193], v[222:225], v[0:3]
	v_mfma_f32_16x16x32_bf16 v[52:55], v[170:173], v[202:205], v[52:55]
	v_mfma_f32_16x16x32_bf16 v[48:51], v[194:197], v[202:205], v[48:51]
	v_mfma_f32_16x16x32_bf16 v[36:39], v[170:173], v[210:213], v[36:39]
	v_mfma_f32_16x16x32_bf16 v[32:35], v[194:197], v[210:213], v[32:35]
	v_mfma_f32_16x16x32_bf16 v[20:23], v[170:173], v[218:221], v[20:23]
	v_mfma_f32_16x16x32_bf16 v[16:19], v[194:197], v[218:221], v[16:19]
	v_mfma_f32_16x16x32_bf16 v[4:7], v[170:173], v[226:229], v[4:7]
	v_mfma_f32_16x16x32_bf16 v[0:3], v[194:197], v[226:229], v[0:3]
	s_barrier
; #define PG8_STAGE(bufoff, gbase, voff) do { _Pragma("unroll") for (int _i = 0; _i < 2; ++_i) \
;         __builtin_amdgcn_global_load_lds((const unsigned*)((const char*)(gbase) + (voff)[_i]), (PG8_LAS unsigned*)(lds + (bufoff) + ldsw + _i * 8192), 16, 0, 0); } while (0)
; #define PG8_LDA(dst, b, h) do { _Pragma("unroll") for (int m = 0; m < 4; ++m) _Pragma("unroll") for (int k = 0; k < 2; ++k) dst[m][k] = *(const PG8_LAS bf16x8*)(lds + PG8_SA(b, h) + aoff + m * 2048 + k * 1024); } while (0)
; #define PG8_LDB(dst, b, h) do { _Pragma("unroll") for (int n = 0; n < 2; ++n) _Pragma("unroll") for (int k = 0; k < 2; ++k) dst[n][k] = *(const PG8_LAS bf16x8*)(lds + PG8_SB(b, h) + boff + n * 2048 + k * 1024); } while (0)
; #define PG8_MMA(ai, bj, At, Bt) do { __builtin_amdgcn_s_setprio(1); _Pragma("unroll") for (int m = 0; m < 4; ++m) _Pragma("unroll") for (int n = 0; n < 2; ++n) _Pragma("unroll") for (int k = 0; k < 2; ++k) \
;         acc[ai][bj][m][n] = __builtin_amdgcn_mfma_f32_16x16x32_bf16(Bt[n][k], At[m][k], acc[ai][bj][m][n], 0, 0, 0); __builtin_amdgcn_s_setprio(0); } while (0)
; #define PG8_WAIT_V(n) asm volatile("s_waitcnt vmcnt(" #n ")" ::: "memory")
; #define PG8_WAIT_L(n) asm volatile("s_waitcnt lgkmcnt(" #n ")" ::: "memory")
; #define PG8_BAR __builtin_amdgcn_s_barrier()
; #define PG8_SCHED __builtin_amdgcn_sched_barrier(0)
; template <class Epi, class Sched, bool ALIGN_EPI = false, bool SP2 = false>
; __device__ __forceinline__ void gemm_phase(PG8_LAS unsigned char* lds, const Gemm g, const Sched& S, const Epi& E) {
;     ...
;             PG8_LDB(B0, 1, 0); PG8_LDB(B1, 1, 1); PG8_SCHED; PG8_LDA(At, 1, 0); PG8_STAGE(PG8_SA(0, 1), a2 + hstep, voffA);
;             PG8_WAIT_V(8); PG8_WAIT_L(0); PG8_BAR; PG8_MMA(0, 0, At, B0); PG8_MMA(0, 1, At, B1); PG8_BAR; PG8_SCHED;
;             PG8_LDA(At, 1, 1); PG8_STAGE(PG8_SB(1, 0), b3, voffB); PG8_STAGE(PG8_SB(1, 1), b3 + hstep, voffB); PG8_STAGE(PG8_SA(1, 0), a3, voffA);
;             PG8_WAIT_V(8); PG8_WAIT_L(0); PG8_BAR; PG8_MMA(1, 0, At, B0); PG8_MMA(1, 1, At, B1); PG8_BAR; PG8_SCHED;
;     ...
;         if constexpr (ALIGN_EPI) { if (wr == 0) PG8_BAR; }
	s_add_i32 s20, 0, 0x18000
	s_add_i32 s21, 0, 0x1c000
	v_add_u32_e32 v140, s20, v176
	v_add_u32_e32 v152, s21, v176
	ds_read_b128 v[128:131], v140
	ds_read_b128 v[132:135], v140 offset:1024
	ds_read_b128 v[136:139], v140 offset:2048
	ds_read_b128 v[140:143], v140 offset:3072
	ds_read_b128 v[166:169], v152
	ds_read_b128 v[170:173], v152 offset:1024
	ds_read_b128 v[190:193], v152 offset:2048
	ds_read_b128 v[194:197], v152 offset:3072
	s_add_u32 s36, s86, 0x40000
	s_addc_u32 s37, s87, 0
	s_mov_b32 m0, s95
	ds_read_b128 v[198:201], v181 offset:32768
	ds_read_b128 v[202:205], v181 offset:33792
	ds_read_b128 v[206:209], v181 offset:34816
	ds_read_b128 v[210:213], v181 offset:35840
	ds_read_b128 v[214:217], v181 offset:36864
	ds_read_b128 v[218:221], v181 offset:37888
	ds_read_b128 v[222:225], v181 offset:38912
	ds_read_b128 v[226:229], v181 offset:39936
	global_load_lds_dwordx4 v150, s[36:37]
	s_mov_b32 m0, s97
	s_nop 0
	global_load_lds_dwordx4 v146, s[36:37]
	s_waitcnt vmcnt(8)
	s_waitcnt lgkmcnt(0)
	s_barrier
	v_mfma_f32_16x16x32_bf16 v[124:127], v[128:131], v[198:201], v[124:127]
	v_mfma_f32_16x16x32_bf16 v[120:123], v[136:139], v[198:201], v[120:123]
	v_mfma_f32_16x16x32_bf16 v[108:111], v[128:131], v[206:209], v[108:111]
	v_mfma_f32_16x16x32_bf16 v[104:107], v[136:139], v[206:209], v[104:107]
	v_mfma_f32_16x16x32_bf16 v[92:95], v[128:131], v[214:217], v[92:95]
	v_mfma_f32_16x16x32_bf16 v[88:91], v[136:139], v[214:217], v[88:91]
	v_mfma_f32_16x16x32_bf16 v[76:79], v[128:131], v[222:225], v[76:79]
	v_mfma_f32_16x16x32_bf16 v[72:75], v[136:139], v[222:225], v[72:75]
	v_mfma_f32_16x16x32_bf16 v[124:127], v[132:135], v[202:205], v[124:127]
	v_mfma_f32_16x16x32_bf16 v[120:123], v[140:143], v[202:205], v[120:123]
	v_mfma_f32_16x16x32_bf16 v[108:111], v[132:135], v[210:213], v[108:111]
	v_mfma_f32_16x16x32_bf16 v[104:107], v[140:143], v[210:213], v[104:107]
	v_mfma_f32_16x16x32_bf16 v[92:95], v[132:135], v[218:221], v[92:95]
	v_mfma_f32_16x16x32_bf16 v[88:91], v[140:143], v[218:221], v[88:91]
	v_mfma_f32_16x16x32_bf16 v[76:79], v[132:135], v[226:229], v[76:79]
	v_mfma_f32_16x16x32_bf16 v[72:75], v[140:143], v[226:229], v[72:75]
	v_mfma_f32_16x16x32_bf16 v[116:119], v[166:169], v[198:201], v[116:119]
	v_mfma_f32_16x16x32_bf16 v[112:115], v[190:193], v[198:201], v[112:115]
	v_mfma_f32_16x16x32_bf16 v[100:103], v[166:169], v[206:209], v[100:103]
	v_mfma_f32_16x16x32_bf16 v[96:99], v[190:193], v[206:209], v[96:99]
	v_mfma_f32_16x16x32_bf16 v[84:87], v[166:169], v[214:217], v[84:87]
	v_mfma_f32_16x16x32_bf16 v[80:83], v[190:193], v[214:217], v[80:83]
	v_mfma_f32_16x16x32_bf16 v[68:71], v[166:169], v[222:225], v[68:71]
	v_mfma_f32_16x16x32_bf16 v[64:67], v[190:193], v[222:225], v[64:67]
	v_mfma_f32_16x16x32_bf16 v[116:119], v[170:173], v[202:205], v[116:119]
	v_mfma_f32_16x16x32_bf16 v[112:115], v[194:197], v[202:205], v[112:115]
	v_mfma_f32_16x16x32_bf16 v[100:103], v[170:173], v[210:213], v[100:103]
	v_mfma_f32_16x16x32_bf16 v[96:99], v[194:197], v[210:213], v[96:99]
	v_mfma_f32_16x16x32_bf16 v[84:87], v[170:173], v[218:221], v[84:87]
	v_mfma_f32_16x16x32_bf16 v[80:83], v[194:197], v[218:221], v[80:83]
	v_mfma_f32_16x16x32_bf16 v[68:71], v[170:173], v[226:229], v[68:71]
	v_mfma_f32_16x16x32_bf16 v[64:67], v[194:197], v[226:229], v[64:67]
	s_barrier
	s_add_i32 s20, s20, s90
	v_lshl_add_u64 v[174:175], v[174:175], 0, s[26:27]
	s_mov_b32 m0, s20
	ds_read_b128 v[198:201], v181 offset:49152
	ds_read_b128 v[202:205], v181 offset:50176
	ds_read_b128 v[206:209], v181 offset:51200
	ds_read_b128 v[210:213], v181 offset:52224
	ds_read_b128 v[214:217], v181 offset:53248
	ds_read_b128 v[218:221], v181 offset:54272
	ds_read_b128 v[222:225], v181 offset:55296
	ds_read_b128 v[226:229], v181 offset:56320
	global_load_lds_dwordx4 v[174:175], off
	s_add_i32 m0, s20, 0x2000
	s_add_u32 s36, s82, 0x40080
	v_lshl_add_u64 v[174:175], v[186:187], 0, s[26:27]
	s_addc_u32 s37, s83, 0
	s_add_i32 s20, s21, s90
	global_load_lds_dwordx4 v[174:175], off
	s_mov_b32 m0, s20
	s_nop 0
	global_load_lds_dwordx4 v148, s[36:37]
	s_add_i32 m0, s20, 0x2000
	s_nop 0
	global_load_lds_dwordx4 v144, s[36:37]
	v_lshl_add_u64 v[174:175], v[230:231], 0, s[26:27]
	s_mov_b32 m0, s42
	s_nop 0
	global_load_lds_dwordx4 v[174:175], off
	v_lshl_add_u64 v[174:175], v[232:233], 0, s[26:27]
	s_mov_b32 m0, s43
	s_nop 0
	global_load_lds_dwordx4 v[174:175], off
	s_waitcnt vmcnt(8)
	s_waitcnt lgkmcnt(0)
	s_barrier
	v_mfma_f32_16x16x32_bf16 v[60:63], v[128:131], v[198:201], v[60:63]
	v_mfma_f32_16x16x32_bf16 v[56:59], v[136:139], v[198:201], v[56:59]
	v_mfma_f32_16x16x32_bf16 v[44:47], v[128:131], v[206:209], v[44:47]
	v_mfma_f32_16x16x32_bf16 v[40:43], v[136:139], v[206:209], v[40:43]
	v_mfma_f32_16x16x32_bf16 v[28:31], v[128:131], v[214:217], v[28:31]
	v_mfma_f32_16x16x32_bf16 v[24:27], v[136:139], v[214:217], v[24:27]
	v_mfma_f32_16x16x32_bf16 v[12:15], v[128:131], v[222:225], v[12:15]
	v_mfma_f32_16x16x32_bf16 v[8:11], v[136:139], v[222:225], v[8:11]
	v_mfma_f32_16x16x32_bf16 v[60:63], v[132:135], v[202:205], v[60:63]
	v_mfma_f32_16x16x32_bf16 v[56:59], v[140:143], v[202:205], v[56:59]
	v_mfma_f32_16x16x32_bf16 v[44:47], v[132:135], v[210:213], v[44:47]
	v_mfma_f32_16x16x32_bf16 v[40:43], v[140:143], v[210:213], v[40:43]
	v_mfma_f32_16x16x32_bf16 v[28:31], v[132:135], v[218:221], v[28:31]
	v_mfma_f32_16x16x32_bf16 v[24:27], v[140:143], v[218:221], v[24:27]
	v_mfma_f32_16x16x32_bf16 v[12:15], v[132:135], v[226:229], v[12:15]
	v_mfma_f32_16x16x32_bf16 v[8:11], v[140:143], v[226:229], v[8:11]
	v_mfma_f32_16x16x32_bf16 v[52:55], v[166:169], v[198:201], v[52:55]
	v_mfma_f32_16x16x32_bf16 v[48:51], v[190:193], v[198:201], v[48:51]
	v_mfma_f32_16x16x32_bf16 v[36:39], v[166:169], v[206:209], v[36:39]
	v_mfma_f32_16x16x32_bf16 v[32:35], v[190:193], v[206:209], v[32:35]
	v_mfma_f32_16x16x32_bf16 v[20:23], v[166:169], v[214:217], v[20:23]
	v_mfma_f32_16x16x32_bf16 v[16:19], v[190:193], v[214:217], v[16:19]
	v_mfma_f32_16x16x32_bf16 v[4:7], v[166:169], v[222:225], v[4:7]
	v_mfma_f32_16x16x32_bf16 v[0:3], v[190:193], v[222:225], v[0:3]
	v_mfma_f32_16x16x32_bf16 v[52:55], v[170:173], v[202:205], v[52:55]
	v_mfma_f32_16x16x32_bf16 v[48:51], v[194:197], v[202:205], v[48:51]
	v_mfma_f32_16x16x32_bf16 v[36:39], v[170:173], v[210:213], v[36:39]
	v_mfma_f32_16x16x32_bf16 v[32:35], v[194:197], v[210:213], v[32:35]
	v_mfma_f32_16x16x32_bf16 v[20:23], v[170:173], v[218:221], v[20:23]
	v_mfma_f32_16x16x32_bf16 v[16:19], v[194:197], v[218:221], v[16:19]
	v_mfma_f32_16x16x32_bf16 v[4:7], v[170:173], v[226:229], v[4:7]
	v_mfma_f32_16x16x32_bf16 v[0:3], v[194:197], v[226:229], v[0:3]
	s_barrier
	s_add_i32 s35, s35, 2
	s_add_u32 s80, s80, 0x100
	s_addc_u32 s81, s81, 0
	s_add_u32 vcc_hi, vcc_hi, 0x100
	s_addc_u32 s34, s34, 0
	s_cmp_gt_u32 s35, 13
	s_cbranch_scc0 .LBB0_96
	s_and_b64 vcc, exec, s[28:29]
	s_cbranch_vccz .LBB0_99
	s_barrier

; #define PG8_STAGE(bufoff, gbase, voff) do { _Pragma("unroll") for (int _i = 0; _i < 2; ++_i) \
;         __builtin_amdgcn_global_load_lds((const unsigned*)((const char*)(gbase) + (voff)[_i]), (PG8_LAS unsigned*)(lds + (bufoff) + ldsw + _i * 8192), 16, 0, 0); } while (0)
; #define PG8_LDA(dst, b, h) do { _Pragma("unroll") for (int m = 0; m < 4; ++m) _Pragma("unroll") for (int k = 0; k < 2; ++k) dst[m][k] = *(const PG8_LAS bf16x8*)(lds + PG8_SA(b, h) + aoff + m * 2048 + k * 1024); } while (0)
; #define PG8_LDB(dst, b, h) do { _Pragma("unroll") for (int n = 0; n < 2; ++n) _Pragma("unroll") for (int k = 0; k < 2; ++k) dst[n][k] = *(const PG8_LAS bf16x8*)(lds + PG8_SB(b, h) + boff + n * 2048 + k * 1024); } while (0)
; #define PG8_MMA(ai, bj, At, Bt) do { __builtin_amdgcn_s_setprio(1); _Pragma("unroll") for (int m = 0; m < 4; ++m) _Pragma("unroll") for (int n = 0; n < 2; ++n) _Pragma("unroll") for (int k = 0; k < 2; ++k) \
;         acc[ai][bj][m][n] = __builtin_amdgcn_mfma_f32_16x16x32_bf16(Bt[n][k], At[m][k], acc[ai][bj][m][n], 0, 0, 0); __builtin_amdgcn_s_setprio(0); } while (0)
; #define PG8_WAIT_V(n) asm volatile("s_waitcnt vmcnt(" #n ")" ::: "memory")
; #define PG8_WAIT_L(n) asm volatile("s_waitcnt lgkmcnt(" #n ")" ::: "memory")
; #define PG8_BAR __builtin_amdgcn_s_barrier()
; #define PG8_SCHED __builtin_amdgcn_sched_barrier(0)
; template <class Epi, class Sched, bool ALIGN_EPI = false, bool SP2 = false>
; __device__ __forceinline__ void gemm_phase(PG8_LAS unsigned char* lds, const Gemm g, const Sched& S, const Epi& E) {
;     ...
;             PG8_LDB(B0, 0, 0); PG8_LDB(B1, 0, 1); PG8_SCHED; PG8_LDA(At, 0, 0); PG8_STAGE(PG8_SA(1, 1), a1 + hstep, voffA);
;             PG8_WAIT_V(8); PG8_WAIT_L(0); PG8_BAR; PG8_MMA(0, 0, At, B0); PG8_MMA(0, 1, At, B1); PG8_BAR; PG8_SCHED;
;             PG8_LDA(At, 0, 1); PG8_STAGE(PG8_SB(0, 0), b2, voffB); PG8_STAGE(PG8_SB(0, 1), b2 + hstep, voffB); PG8_STAGE(PG8_SA(0, 0), a2, voffA);
;             PG8_WAIT_V(8); PG8_WAIT_L(0); PG8_BAR; PG8_MMA(1, 0, At, B0); PG8_MMA(1, 1, At, B1); PG8_BAR; PG8_SCHED;
.LBB0_150:
	s_add_u32 s24, s22, 0xfffc0080
	s_addc_u32 s25, s23, -1
	s_waitcnt lgkmcnt(0)
	s_add_i32 s54, 0, 0x10000
	v_add_u32_e32 v147, s54, v152
	ds_read_b128 v[156:159], v147
	ds_read_b128 v[160:163], v147 offset:1024
	ds_read_b128 v[164:167], v147 offset:2048
	ds_read_b128 v[168:171], v147 offset:3072
	ds_read_b128 v[172:175], v154
	ds_read_b128 v[176:179], v154 offset:1024
	ds_read_b128 v[182:185], v154 offset:2048
	ds_read_b128 v[190:193], v154 offset:3072
	s_cmp_eq_u32 s49, 12
	s_cselect_b32 s27, s17, s25
	s_cselect_b32 s26, s45, s24
	s_cselect_b32 s25, s15, s48
	s_cselect_b32 s24, s46, s47
	s_add_i32 m0, s13, 0xc000
	ds_read_b128 v[194:197], v155
	ds_read_b128 v[198:201], v155 offset:1024
	ds_read_b128 v[202:205], v155 offset:2048
	ds_read_b128 v[206:209], v155 offset:3072
	ds_read_b128 v[210:213], v155 offset:4096
	ds_read_b128 v[214:217], v155 offset:5120
	ds_read_b128 v[218:221], v155 offset:6144
	ds_read_b128 v[222:225], v155 offset:7168
	global_load_lds_dwordx4 v138, s[22:23]
	s_add_i32 m0, s13, 0xe000
	s_nop 0
	global_load_lds_dwordx4 v140, s[22:23]
	s_waitcnt vmcnt(8)
	s_waitcnt lgkmcnt(0)
	s_barrier
	v_mfma_f32_16x16x32_bf16 v[124:127], v[156:159], v[194:197], v[124:127]
	v_mfma_f32_16x16x32_bf16 v[120:123], v[164:167], v[194:197], v[120:123]
	v_mfma_f32_16x16x32_bf16 v[116:119], v[156:159], v[202:205], v[116:119]
	v_mfma_f32_16x16x32_bf16 v[112:115], v[164:167], v[202:205], v[112:115]
	v_mfma_f32_16x16x32_bf16 v[100:103], v[156:159], v[210:213], v[100:103]
	v_mfma_f32_16x16x32_bf16 v[96:99], v[164:167], v[210:213], v[96:99]
	v_mfma_f32_16x16x32_bf16 v[84:87], v[156:159], v[218:221], v[84:87]
	v_mfma_f32_16x16x32_bf16 v[80:83], v[164:167], v[218:221], v[80:83]
	v_mfma_f32_16x16x32_bf16 v[124:127], v[160:163], v[198:201], v[124:127]
	v_mfma_f32_16x16x32_bf16 v[120:123], v[168:171], v[198:201], v[120:123]
	v_mfma_f32_16x16x32_bf16 v[116:119], v[160:163], v[206:209], v[116:119]
	v_mfma_f32_16x16x32_bf16 v[112:115], v[168:171], v[206:209], v[112:115]
	v_mfma_f32_16x16x32_bf16 v[100:103], v[160:163], v[214:217], v[100:103]
	v_mfma_f32_16x16x32_bf16 v[96:99], v[168:171], v[214:217], v[96:99]
	v_mfma_f32_16x16x32_bf16 v[84:87], v[160:163], v[222:225], v[84:87]
	v_mfma_f32_16x16x32_bf16 v[80:83], v[168:171], v[222:225], v[80:83]
	v_mfma_f32_16x16x32_bf16 v[108:111], v[172:175], v[194:197], v[108:111]
	v_mfma_f32_16x16x32_bf16 v[104:107], v[182:185], v[194:197], v[104:107]
	v_mfma_f32_16x16x32_bf16 v[92:95], v[172:175], v[202:205], v[92:95]
	v_mfma_f32_16x16x32_bf16 v[88:91], v[182:185], v[202:205], v[88:91]
	v_mfma_f32_16x16x32_bf16 v[76:79], v[172:175], v[210:213], v[76:79]
	v_mfma_f32_16x16x32_bf16 v[72:75], v[182:185], v[210:213], v[72:75]
	v_mfma_f32_16x16x32_bf16 v[68:71], v[172:175], v[218:221], v[68:71]
	v_mfma_f32_16x16x32_bf16 v[64:67], v[182:185], v[218:221], v[64:67]
	v_mfma_f32_16x16x32_bf16 v[108:111], v[176:179], v[198:201], v[108:111]
	v_mfma_f32_16x16x32_bf16 v[104:107], v[190:193], v[198:201], v[104:107]
	v_mfma_f32_16x16x32_bf16 v[92:95], v[176:179], v[206:209], v[92:95]
	v_mfma_f32_16x16x32_bf16 v[88:91], v[190:193], v[206:209], v[88:91]
	v_mfma_f32_16x16x32_bf16 v[76:79], v[176:179], v[214:217], v[76:79]
	v_mfma_f32_16x16x32_bf16 v[72:75], v[190:193], v[214:217], v[72:75]
	v_mfma_f32_16x16x32_bf16 v[68:71], v[176:179], v[222:225], v[68:71]
	v_mfma_f32_16x16x32_bf16 v[64:67], v[190:193], v[222:225], v[64:67]
	s_barrier
	s_add_i32 s54, s54, s31
	v_lshl_add_u64 v[186:187], s[24:25], 0, v[130:131]
	s_mov_b32 m0, s54
	ds_read_b128 v[194:197], v155 offset:16384
	ds_read_b128 v[198:201], v155 offset:17408
	ds_read_b128 v[202:205], v155 offset:18432
	ds_read_b128 v[206:209], v155 offset:19456
	ds_read_b128 v[210:213], v155 offset:20480
	ds_read_b128 v[214:217], v155 offset:21504
	ds_read_b128 v[218:221], v155 offset:22528
	ds_read_b128 v[222:225], v155 offset:23552
	global_load_lds_dwordx4 v[186:187], off
	s_add_i32 m0, s54, 0x2000
	s_add_u32 s54, s24, 0x40000
	v_lshl_add_u64 v[226:227], s[24:25], 0, v[134:135]
	s_addc_u32 s55, s25, 0
	s_add_i32 s76, s43, s31
	global_load_lds_dwordx4 v[226:227], off
	s_mov_b32 m0, s76
	v_lshl_add_u64 v[230:231], s[26:27], 0, v[132:133]
	global_load_lds_dwordx4 v130, s[54:55]
	s_add_i32 m0, s76, 0x2000
	s_nop 0
	global_load_lds_dwordx4 v134, s[54:55]
	v_lshl_add_u64 v[228:229], s[26:27], 0, v[128:129]
	s_mov_b32 m0, s13
	s_nop 0
	global_load_lds_dwordx4 v[228:229], off
	s_mov_b32 m0, s34
	s_nop 0
	global_load_lds_dwordx4 v[230:231], off
	s_waitcnt vmcnt(8)
	s_waitcnt lgkmcnt(0)
	s_barrier
	v_mfma_f32_16x16x32_bf16 v[60:63], v[156:159], v[194:197], v[60:63]
	v_mfma_f32_16x16x32_bf16 v[56:59], v[164:167], v[194:197], v[56:59]
	v_mfma_f32_16x16x32_bf16 v[52:55], v[156:159], v[202:205], v[52:55]
	v_mfma_f32_16x16x32_bf16 v[48:51], v[164:167], v[202:205], v[48:51]
	v_mfma_f32_16x16x32_bf16 v[36:39], v[156:159], v[210:213], v[36:39]
	v_mfma_f32_16x16x32_bf16 v[32:35], v[164:167], v[210:213], v[32:35]
	v_mfma_f32_16x16x32_bf16 v[20:23], v[156:159], v[218:221], v[20:23]
	v_mfma_f32_16x16x32_bf16 v[16:19], v[164:167], v[218:221], v[16:19]
	v_mfma_f32_16x16x32_bf16 v[60:63], v[160:163], v[198:201], v[60:63]
	v_mfma_f32_16x16x32_bf16 v[56:59], v[168:171], v[198:201], v[56:59]
	v_mfma_f32_16x16x32_bf16 v[52:55], v[160:163], v[206:209], v[52:55]
	v_mfma_f32_16x16x32_bf16 v[48:51], v[168:171], v[206:209], v[48:51]
	v_mfma_f32_16x16x32_bf16 v[36:39], v[160:163], v[214:217], v[36:39]
	v_mfma_f32_16x16x32_bf16 v[32:35], v[168:171], v[214:217], v[32:35]
	v_mfma_f32_16x16x32_bf16 v[20:23], v[160:163], v[222:225], v[20:23]
	v_mfma_f32_16x16x32_bf16 v[16:19], v[168:171], v[222:225], v[16:19]
	v_mfma_f32_16x16x32_bf16 v[44:47], v[172:175], v[194:197], v[44:47]
	v_mfma_f32_16x16x32_bf16 v[40:43], v[182:185], v[194:197], v[40:43]
	v_mfma_f32_16x16x32_bf16 v[28:31], v[172:175], v[202:205], v[28:31]
	v_mfma_f32_16x16x32_bf16 v[24:27], v[182:185], v[202:205], v[24:27]
	v_mfma_f32_16x16x32_bf16 v[12:15], v[172:175], v[210:213], v[12:15]
	v_mfma_f32_16x16x32_bf16 v[8:11], v[182:185], v[210:213], v[8:11]
	v_mfma_f32_16x16x32_bf16 v[4:7], v[172:175], v[218:221], v[4:7]
	v_mfma_f32_16x16x32_bf16 v[0:3], v[182:185], v[218:221], v[0:3]
	v_mfma_f32_16x16x32_bf16 v[44:47], v[176:179], v[198:201], v[44:47]
	v_mfma_f32_16x16x32_bf16 v[40:43], v[190:193], v[198:201], v[40:43]
	v_mfma_f32_16x16x32_bf16 v[28:31], v[176:179], v[206:209], v[28:31]
	v_mfma_f32_16x16x32_bf16 v[24:27], v[190:193], v[206:209], v[24:27]
	v_mfma_f32_16x16x32_bf16 v[12:15], v[176:179], v[214:217], v[12:15]
	v_mfma_f32_16x16x32_bf16 v[8:11], v[190:193], v[214:217], v[8:11]
	v_mfma_f32_16x16x32_bf16 v[4:7], v[176:179], v[222:225], v[4:7]
	v_mfma_f32_16x16x32_bf16 v[0:3], v[190:193], v[222:225], v[0:3]
	s_barrier
; #define PG8_STAGE(bufoff, gbase, voff) do { _Pragma("unroll") for (int _i = 0; _i < 2; ++_i) \
;         __builtin_amdgcn_global_load_lds((const unsigned*)((const char*)(gbase) + (voff)[_i]), (PG8_LAS unsigned*)(lds + (bufoff) + ldsw + _i * 8192), 16, 0, 0); } while (0)
; #define PG8_LDA(dst, b, h) do { _Pragma("unroll") for (int m = 0; m < 4; ++m) _Pragma("unroll") for (int k = 0; k < 2; ++k) dst[m][k] = *(const PG8_LAS bf16x8*)(lds + PG8_SA(b, h) + aoff + m * 2048 + k * 1024); } while (0)
; #define PG8_LDB(dst, b, h) do { _Pragma("unroll") for (int n = 0; n < 2; ++n) _Pragma("unroll") for (int k = 0; k < 2; ++k) dst[n][k] = *(const PG8_LAS bf16x8*)(lds + PG8_SB(b, h) + boff + n * 2048 + k * 1024); } while (0)
; #define PG8_MMA(ai, bj, At, Bt) do { __builtin_amdgcn_s_setprio(1); _Pragma("unroll") for (int m = 0; m < 4; ++m) _Pragma("unroll") for (int n = 0; n < 2; ++n) _Pragma("unroll") for (int k = 0; k < 2; ++k) \
;         acc[ai][bj][m][n] = __builtin_amdgcn_mfma_f32_16x16x32_bf16(Bt[n][k], At[m][k], acc[ai][bj][m][n], 0, 0, 0); __builtin_amdgcn_s_setprio(0); } while (0)
; #define PG8_WAIT_V(n) asm volatile("s_waitcnt vmcnt(" #n ")" ::: "memory")
; #define PG8_WAIT_L(n) asm volatile("s_waitcnt lgkmcnt(" #n ")" ::: "memory")
; #define PG8_BAR __builtin_amdgcn_s_barrier()
; #define PG8_SCHED __builtin_amdgcn_sched_barrier(0)
; template <class Epi, class Sched, bool ALIGN_EPI = false, bool SP2 = false>
; __device__ __forceinline__ void gemm_phase(PG8_LAS unsigned char* lds, const Gemm g, const Sched& S, const Epi& E) {
;     ...
;             PG8_LDB(B0, 1, 0); PG8_LDB(B1, 1, 1); PG8_SCHED; PG8_LDA(At, 1, 0); PG8_STAGE(PG8_SA(0, 1), a2 + hstep, voffA);
;             PG8_WAIT_V(8); PG8_WAIT_L(0); PG8_BAR; PG8_MMA(0, 0, At, B0); PG8_MMA(0, 1, At, B1); PG8_BAR; PG8_SCHED;
;             PG8_LDA(At, 1, 1); PG8_STAGE(PG8_SB(1, 0), b3, voffB); PG8_STAGE(PG8_SB(1, 1), b3 + hstep, voffB); PG8_STAGE(PG8_SA(1, 0), a3, voffA);
;             PG8_WAIT_V(8); PG8_WAIT_L(0); PG8_BAR; PG8_MMA(1, 0, At, B0); PG8_MMA(1, 1, At, B1); PG8_BAR; PG8_SCHED;
;     ...
;         if constexpr (ALIGN_EPI) { if (wr == 0) PG8_BAR; }
	s_add_i32 s54, 0, 0x18000
	v_add_u32_e32 v147, s54, v152
	s_add_i32 s55, 0, 0x1c000
	ds_read_b128 v[156:159], v147
	ds_read_b128 v[160:163], v147 offset:1024
	ds_read_b128 v[164:167], v147 offset:2048
	ds_read_b128 v[168:171], v147 offset:3072
	v_add_u32_e32 v147, s55, v152
	ds_read_b128 v[172:175], v147
	ds_read_b128 v[176:179], v147 offset:1024
	ds_read_b128 v[182:185], v147 offset:2048
	ds_read_b128 v[190:193], v147 offset:3072
	s_add_u32 s26, s26, 0x40000
	s_addc_u32 s27, s27, 0
	s_mov_b32 m0, s35
	ds_read_b128 v[194:197], v155 offset:32768
	ds_read_b128 v[198:201], v155 offset:33792
	ds_read_b128 v[202:205], v155 offset:34816
	ds_read_b128 v[206:209], v155 offset:35840
	ds_read_b128 v[210:213], v155 offset:36864
	ds_read_b128 v[214:217], v155 offset:37888
	ds_read_b128 v[218:221], v155 offset:38912
	ds_read_b128 v[222:225], v155 offset:39936
	global_load_lds_dwordx4 v128, s[26:27]
	s_mov_b32 m0, s36
	s_nop 0
	global_load_lds_dwordx4 v132, s[26:27]
	s_waitcnt vmcnt(8)
	s_waitcnt lgkmcnt(0)
	s_barrier
	v_mfma_f32_16x16x32_bf16 v[124:127], v[156:159], v[194:197], v[124:127]
	v_mfma_f32_16x16x32_bf16 v[120:123], v[164:167], v[194:197], v[120:123]
	v_mfma_f32_16x16x32_bf16 v[116:119], v[156:159], v[202:205], v[116:119]
	v_mfma_f32_16x16x32_bf16 v[112:115], v[164:167], v[202:205], v[112:115]
	v_mfma_f32_16x16x32_bf16 v[100:103], v[156:159], v[210:213], v[100:103]
	v_mfma_f32_16x16x32_bf16 v[96:99], v[164:167], v[210:213], v[96:99]
	v_mfma_f32_16x16x32_bf16 v[84:87], v[156:159], v[218:221], v[84:87]
	v_mfma_f32_16x16x32_bf16 v[80:83], v[164:167], v[218:221], v[80:83]
	v_mfma_f32_16x16x32_bf16 v[124:127], v[160:163], v[198:201], v[124:127]
	v_mfma_f32_16x16x32_bf16 v[120:123], v[168:171], v[198:201], v[120:123]
	v_mfma_f32_16x16x32_bf16 v[116:119], v[160:163], v[206:209], v[116:119]
	v_mfma_f32_16x16x32_bf16 v[112:115], v[168:171], v[206:209], v[112:115]
	v_mfma_f32_16x16x32_bf16 v[100:103], v[160:163], v[214:217], v[100:103]
	v_mfma_f32_16x16x32_bf16 v[96:99], v[168:171], v[214:217], v[96:99]
	v_mfma_f32_16x16x32_bf16 v[84:87], v[160:163], v[222:225], v[84:87]
	v_mfma_f32_16x16x32_bf16 v[80:83], v[168:171], v[222:225], v[80:83]
	v_mfma_f32_16x16x32_bf16 v[108:111], v[172:175], v[194:197], v[108:111]
	v_mfma_f32_16x16x32_bf16 v[104:107], v[182:185], v[194:197], v[104:107]
	v_mfma_f32_16x16x32_bf16 v[92:95], v[172:175], v[202:205], v[92:95]
	v_mfma_f32_16x16x32_bf16 v[88:91], v[182:185], v[202:205], v[88:91]
	v_mfma_f32_16x16x32_bf16 v[76:79], v[172:175], v[210:213], v[76:79]
	v_mfma_f32_16x16x32_bf16 v[72:75], v[182:185], v[210:213], v[72:75]
	v_mfma_f32_16x16x32_bf16 v[68:71], v[172:175], v[218:221], v[68:71]
	v_mfma_f32_16x16x32_bf16 v[64:67], v[182:185], v[218:221], v[64:67]
	v_mfma_f32_16x16x32_bf16 v[108:111], v[176:179], v[198:201], v[108:111]
	v_mfma_f32_16x16x32_bf16 v[104:107], v[190:193], v[198:201], v[104:107]
	v_mfma_f32_16x16x32_bf16 v[92:95], v[176:179], v[206:209], v[92:95]
	v_mfma_f32_16x16x32_bf16 v[88:91], v[190:193], v[206:209], v[88:91]
	v_mfma_f32_16x16x32_bf16 v[76:79], v[176:179], v[214:217], v[76:79]
	v_mfma_f32_16x16x32_bf16 v[72:75], v[190:193], v[214:217], v[72:75]
	v_mfma_f32_16x16x32_bf16 v[68:71], v[176:179], v[222:225], v[68:71]
	v_mfma_f32_16x16x32_bf16 v[64:67], v[190:193], v[222:225], v[64:67]
	s_barrier
	s_add_i32 s26, s54, s31
	v_lshl_add_u64 v[186:187], v[186:187], 0, s[8:9]
	s_mov_b32 m0, s26
	ds_read_b128 v[194:197], v155 offset:49152
	ds_read_b128 v[198:201], v155 offset:50176
	ds_read_b128 v[202:205], v155 offset:51200
	ds_read_b128 v[206:209], v155 offset:52224
	ds_read_b128 v[210:213], v155 offset:53248
	ds_read_b128 v[214:217], v155 offset:54272
	ds_read_b128 v[218:221], v155 offset:55296
	ds_read_b128 v[222:225], v155 offset:56320
	global_load_lds_dwordx4 v[186:187], off
	s_add_i32 m0, s26, 0x2000
	s_add_u32 s24, s24, 0x40080
	v_lshl_add_u64 v[186:187], v[226:227], 0, s[8:9]
	s_addc_u32 s25, s25, 0
	s_add_i32 s26, s55, s31
	global_load_lds_dwordx4 v[186:187], off
	s_mov_b32 m0, s26
	s_nop 0
	global_load_lds_dwordx4 v130, s[24:25]
	s_add_i32 m0, s26, 0x2000
	s_nop 0
	global_load_lds_dwordx4 v134, s[24:25]
	v_lshl_add_u64 v[186:187], v[228:229], 0, s[8:9]
	s_mov_b32 m0, s39
	s_nop 0
	global_load_lds_dwordx4 v[186:187], off
	v_lshl_add_u64 v[186:187], v[230:231], 0, s[8:9]
	s_mov_b32 m0, s40
	s_nop 0
	global_load_lds_dwordx4 v[186:187], off
	s_waitcnt vmcnt(8)
	s_waitcnt lgkmcnt(0)
	s_barrier
	v_mfma_f32_16x16x32_bf16 v[60:63], v[156:159], v[194:197], v[60:63]
	v_mfma_f32_16x16x32_bf16 v[56:59], v[164:167], v[194:197], v[56:59]
	v_mfma_f32_16x16x32_bf16 v[52:55], v[156:159], v[202:205], v[52:55]
	v_mfma_f32_16x16x32_bf16 v[48:51], v[164:167], v[202:205], v[48:51]
	v_mfma_f32_16x16x32_bf16 v[36:39], v[156:159], v[210:213], v[36:39]
	v_mfma_f32_16x16x32_bf16 v[32:35], v[164:167], v[210:213], v[32:35]
	v_mfma_f32_16x16x32_bf16 v[20:23], v[156:159], v[218:221], v[20:23]
	v_mfma_f32_16x16x32_bf16 v[16:19], v[164:167], v[218:221], v[16:19]
	v_mfma_f32_16x16x32_bf16 v[60:63], v[160:163], v[198:201], v[60:63]
	v_mfma_f32_16x16x32_bf16 v[56:59], v[168:171], v[198:201], v[56:59]
	v_mfma_f32_16x16x32_bf16 v[52:55], v[160:163], v[206:209], v[52:55]
	v_mfma_f32_16x16x32_bf16 v[48:51], v[168:171], v[206:209], v[48:51]
	v_mfma_f32_16x16x32_bf16 v[36:39], v[160:163], v[214:217], v[36:39]
	v_mfma_f32_16x16x32_bf16 v[32:35], v[168:171], v[214:217], v[32:35]
	v_mfma_f32_16x16x32_bf16 v[20:23], v[160:163], v[222:225], v[20:23]
	v_mfma_f32_16x16x32_bf16 v[16:19], v[168:171], v[222:225], v[16:19]
	v_mfma_f32_16x16x32_bf16 v[44:47], v[172:175], v[194:197], v[44:47]
	v_mfma_f32_16x16x32_bf16 v[40:43], v[182:185], v[194:197], v[40:43]
	v_mfma_f32_16x16x32_bf16 v[28:31], v[172:175], v[202:205], v[28:31]
	v_mfma_f32_16x16x32_bf16 v[24:27], v[182:185], v[202:205], v[24:27]
	v_mfma_f32_16x16x32_bf16 v[12:15], v[172:175], v[210:213], v[12:15]
	v_mfma_f32_16x16x32_bf16 v[8:11], v[182:185], v[210:213], v[8:11]
	v_mfma_f32_16x16x32_bf16 v[4:7], v[172:175], v[218:221], v[4:7]
	v_mfma_f32_16x16x32_bf16 v[0:3], v[182:185], v[218:221], v[0:3]
	v_mfma_f32_16x16x32_bf16 v[44:47], v[176:179], v[198:201], v[44:47]
	v_mfma_f32_16x16x32_bf16 v[40:43], v[190:193], v[198:201], v[40:43]
	v_mfma_f32_16x16x32_bf16 v[28:31], v[176:179], v[206:209], v[28:31]
	v_mfma_f32_16x16x32_bf16 v[24:27], v[190:193], v[206:209], v[24:27]
	v_mfma_f32_16x16x32_bf16 v[12:15], v[176:179], v[214:217], v[12:15]
	v_mfma_f32_16x16x32_bf16 v[8:11], v[190:193], v[214:217], v[8:11]
	v_mfma_f32_16x16x32_bf16 v[4:7], v[176:179], v[222:225], v[4:7]
	v_mfma_f32_16x16x32_bf16 v[0:3], v[190:193], v[222:225], v[0:3]
	s_barrier
	s_add_i32 s49, s49, 2
	s_add_u32 s22, s22, 0x100
	s_addc_u32 s23, s23, 0
	s_add_u32 s47, s47, 0x100
	s_addc_u32 s48, s48, 0
	s_cmp_gt_u32 s49, 13
	s_cbranch_scc0 .LBB0_150
	s_and_b64 vcc, exec, s[10:11]
	s_cbranch_vccz .LBB0_153
	s_barrier

; #define PG8_STAGE(bufoff, gbase, voff) do { _Pragma("unroll") for (int _i = 0; _i < 2; ++_i) \
;         __builtin_amdgcn_global_load_lds((const unsigned*)((const char*)(gbase) + (voff)[_i]), (PG8_LAS unsigned*)(lds + (bufoff) + ldsw + _i * 8192), 16, 0, 0); } while (0)
; #define PG8_LDA(dst, b, h) do { _Pragma("unroll") for (int m = 0; m < 4; ++m) _Pragma("unroll") for (int k = 0; k < 2; ++k) dst[m][k] = *(const PG8_LAS bf16x8*)(lds + PG8_SA(b, h) + aoff + m * 2048 + k * 1024); } while (0)
; #define PG8_LDB(dst, b, h) do { _Pragma("unroll") for (int n = 0; n < 2; ++n) _Pragma("unroll") for (int k = 0; k < 2; ++k) dst[n][k] = *(const PG8_LAS bf16x8*)(lds + PG8_SB(b, h) + boff + n * 2048 + k * 1024); } while (0)
; #define PG8_MMA(ai, bj, At, Bt) do { __builtin_amdgcn_s_setprio(1); _Pragma("unroll") for (int m = 0; m < 4; ++m) _Pragma("unroll") for (int n = 0; n < 2; ++n) _Pragma("unroll") for (int k = 0; k < 2; ++k) \
;         acc[ai][bj][m][n] = __builtin_amdgcn_mfma_f32_16x16x32_bf16(Bt[n][k], At[m][k], acc[ai][bj][m][n], 0, 0, 0); __builtin_amdgcn_s_setprio(0); } while (0)
; #define PG8_WAIT_V(n) asm volatile("s_waitcnt vmcnt(" #n ")" ::: "memory")
; #define PG8_WAIT_L(n) asm volatile("s_waitcnt lgkmcnt(" #n ")" ::: "memory")
; #define PG8_BAR __builtin_amdgcn_s_barrier()
; #define PG8_SCHED __builtin_amdgcn_sched_barrier(0)
; template <class Epi, class Sched, bool ALIGN_EPI = false, bool SP2 = false>
; __device__ __forceinline__ void gemm_phase(PG8_LAS unsigned char* lds, const Gemm g, const Sched& S, const Epi& E) {
;     ...
;             PG8_LDB(B0, 0, 0); PG8_LDB(B1, 0, 1); PG8_SCHED; PG8_LDA(At, 0, 0); PG8_STAGE(PG8_SA(1, 1), a1 + hstep, voffA);
;             PG8_WAIT_V(8); PG8_WAIT_L(0); PG8_BAR; PG8_MMA(0, 0, At, B0); PG8_MMA(0, 1, At, B1); PG8_BAR; PG8_SCHED;
;             PG8_LDA(At, 0, 1); PG8_STAGE(PG8_SB(0, 0), b2, voffB); PG8_STAGE(PG8_SB(0, 1), b2 + hstep, voffB); PG8_STAGE(PG8_SA(0, 0), a2, voffA);
;             PG8_WAIT_V(8); PG8_WAIT_L(0); PG8_BAR; PG8_MMA(1, 0, At, B0); PG8_MMA(1, 1, At, B1); PG8_BAR; PG8_SCHED;
.LBB0_358:
	ds_read_b128 v[128:131], v178
	ds_read_b128 v[132:135], v178 offset:1024
	ds_read_b128 v[136:139], v178 offset:2048
	ds_read_b128 v[140:143], v178 offset:3072
	ds_read_b128 v[166:169], v179
	ds_read_b128 v[170:173], v179 offset:1024
	ds_read_b128 v[190:193], v179 offset:2048
	ds_read_b128 v[194:197], v179 offset:3072
	s_add_u32 s42, s40, 0xfffc0080
	s_addc_u32 s43, s41, -1
	s_cmp_eq_u32 s25, 12
	s_cselect_b32 s45, s1, s43
	s_cselect_b32 s44, s35, s42
	s_cselect_b32 s43, s31, s24
	s_cselect_b32 s42, vcc_lo, vcc_hi
	v_lshl_add_u64 v[174:175], s[40:41], 0, v[158:159]
	s_add_i32 m0, s47, 0xc000
	ds_read_b128 v[198:201], v181
	ds_read_b128 v[202:205], v181 offset:1024
	ds_read_b128 v[206:209], v181 offset:2048
	ds_read_b128 v[210:213], v181 offset:3072
	ds_read_b128 v[214:217], v181 offset:4096
	ds_read_b128 v[218:221], v181 offset:5120
	ds_read_b128 v[222:225], v181 offset:6144
	ds_read_b128 v[226:229], v181 offset:7168
	global_load_lds_dwordx4 v[174:175], off
	v_lshl_add_u64 v[174:175], s[40:41], 0, v[160:161]
	s_add_i32 m0, s47, 0xe000
	s_nop 0
	global_load_lds_dwordx4 v[174:175], off
	s_waitcnt vmcnt(8)
	s_waitcnt lgkmcnt(0)
	s_barrier
	v_mfma_f32_16x16x32_bf16 v[124:127], v[128:131], v[198:201], v[124:127]
	v_mfma_f32_16x16x32_bf16 v[120:123], v[136:139], v[198:201], v[120:123]
	v_mfma_f32_16x16x32_bf16 v[108:111], v[128:131], v[206:209], v[108:111]
	v_mfma_f32_16x16x32_bf16 v[104:107], v[136:139], v[206:209], v[104:107]
	v_mfma_f32_16x16x32_bf16 v[92:95], v[128:131], v[214:217], v[92:95]
	v_mfma_f32_16x16x32_bf16 v[88:91], v[136:139], v[214:217], v[88:91]
	v_mfma_f32_16x16x32_bf16 v[76:79], v[128:131], v[222:225], v[76:79]
	v_mfma_f32_16x16x32_bf16 v[72:75], v[136:139], v[222:225], v[72:75]
	v_mfma_f32_16x16x32_bf16 v[124:127], v[132:135], v[202:205], v[124:127]
	v_mfma_f32_16x16x32_bf16 v[120:123], v[140:143], v[202:205], v[120:123]
	v_mfma_f32_16x16x32_bf16 v[108:111], v[132:135], v[210:213], v[108:111]
	v_mfma_f32_16x16x32_bf16 v[104:107], v[140:143], v[210:213], v[104:107]
	v_mfma_f32_16x16x32_bf16 v[92:95], v[132:135], v[218:221], v[92:95]
	v_mfma_f32_16x16x32_bf16 v[88:91], v[140:143], v[218:221], v[88:91]
	v_mfma_f32_16x16x32_bf16 v[76:79], v[132:135], v[226:229], v[76:79]
	v_mfma_f32_16x16x32_bf16 v[72:75], v[140:143], v[226:229], v[72:75]
	v_mfma_f32_16x16x32_bf16 v[116:119], v[166:169], v[198:201], v[116:119]
	v_mfma_f32_16x16x32_bf16 v[112:115], v[190:193], v[198:201], v[112:115]
	v_mfma_f32_16x16x32_bf16 v[100:103], v[166:169], v[206:209], v[100:103]
	v_mfma_f32_16x16x32_bf16 v[96:99], v[190:193], v[206:209], v[96:99]
	v_mfma_f32_16x16x32_bf16 v[84:87], v[166:169], v[214:217], v[84:87]
	v_mfma_f32_16x16x32_bf16 v[80:83], v[190:193], v[214:217], v[80:83]
	v_mfma_f32_16x16x32_bf16 v[68:71], v[166:169], v[222:225], v[68:71]
	v_mfma_f32_16x16x32_bf16 v[64:67], v[190:193], v[222:225], v[64:67]
	v_mfma_f32_16x16x32_bf16 v[116:119], v[170:173], v[202:205], v[116:119]
	v_mfma_f32_16x16x32_bf16 v[112:115], v[194:197], v[202:205], v[112:115]
	v_mfma_f32_16x16x32_bf16 v[100:103], v[170:173], v[210:213], v[100:103]
	v_mfma_f32_16x16x32_bf16 v[96:99], v[194:197], v[210:213], v[96:99]
	v_mfma_f32_16x16x32_bf16 v[84:87], v[170:173], v[218:221], v[84:87]
	v_mfma_f32_16x16x32_bf16 v[80:83], v[194:197], v[218:221], v[80:83]
	v_mfma_f32_16x16x32_bf16 v[68:71], v[170:173], v[226:229], v[68:71]
	v_mfma_f32_16x16x32_bf16 v[64:67], v[194:197], v[226:229], v[64:67]
	s_barrier
	s_add_i32 s54, s93, s46
	v_lshl_add_u64 v[174:175], s[42:43], 0, v[146:147]
	s_mov_b32 m0, s54
	ds_read_b128 v[198:201], v181 offset:16384
	ds_read_b128 v[202:205], v181 offset:17408
	ds_read_b128 v[206:209], v181 offset:18432
	ds_read_b128 v[210:213], v181 offset:19456
	ds_read_b128 v[214:217], v181 offset:20480
	ds_read_b128 v[218:221], v181 offset:21504
	ds_read_b128 v[222:225], v181 offset:22528
	ds_read_b128 v[226:229], v181 offset:23552
	global_load_lds_dwordx4 v[174:175], off
	s_add_i32 m0, s54, 0x2000
	s_add_u32 s54, s42, 0x40000
	v_lshl_add_u64 v[186:187], s[42:43], 0, v[150:151]
	s_addc_u32 s55, s43, 0
	s_add_i32 s23, s94, s46
	global_load_lds_dwordx4 v[186:187], off
	v_lshl_add_u64 v[230:231], s[54:55], 0, v[146:147]
	s_mov_b32 m0, s23
	v_lshl_add_u64 v[232:233], s[44:45], 0, v[148:149]
	global_load_lds_dwordx4 v[230:231], off
	v_lshl_add_u64 v[230:231], s[54:55], 0, v[150:151]
	s_add_i32 m0, s23, 0x2000
	s_nop 0
	global_load_lds_dwordx4 v[230:231], off
	v_lshl_add_u64 v[230:231], s[44:45], 0, v[144:145]
	s_mov_b32 m0, s47
	s_nop 0
	global_load_lds_dwordx4 v[230:231], off
	s_mov_b32 m0, s48
	s_nop 0
	global_load_lds_dwordx4 v[232:233], off
	s_waitcnt vmcnt(8)
	s_waitcnt lgkmcnt(0)
	s_barrier
; #define PG8_STAGE(bufoff, gbase, voff) do { _Pragma("unroll") for (int _i = 0; _i < 2; ++_i) \
;         __builtin_amdgcn_global_load_lds((const unsigned*)((const char*)(gbase) + (voff)[_i]), (PG8_LAS unsigned*)(lds + (bufoff) + ldsw + _i * 8192), 16, 0, 0); } while (0)
; #define PG8_LDA(dst, b, h) do { _Pragma("unroll") for (int m = 0; m < 4; ++m) _Pragma("unroll") for (int k = 0; k < 2; ++k) dst[m][k] = *(const PG8_LAS bf16x8*)(lds + PG8_SA(b, h) + aoff + m * 2048 + k * 1024); } while (0)
; #define PG8_LDB(dst, b, h) do { _Pragma("unroll") for (int n = 0; n < 2; ++n) _Pragma("unroll") for (int k = 0; k < 2; ++k) dst[n][k] = *(const PG8_LAS bf16x8*)(lds + PG8_SB(b, h) + boff + n * 2048 + k * 1024); } while (0)
; #define PG8_MMA(ai, bj, At, Bt) do { __builtin_amdgcn_s_setprio(1); _Pragma("unroll") for (int m = 0; m < 4; ++m) _Pragma("unroll") for (int n = 0; n < 2; ++n) _Pragma("unroll") for (int k = 0; k < 2; ++k) \
;         acc[ai][bj][m][n] = __builtin_amdgcn_mfma_f32_16x16x32_bf16(Bt[n][k], At[m][k], acc[ai][bj][m][n], 0, 0, 0); __builtin_amdgcn_s_setprio(0); } while (0)
; #define PG8_WAIT_V(n) asm volatile("s_waitcnt vmcnt(" #n ")" ::: "memory")
; #define PG8_WAIT_L(n) asm volatile("s_waitcnt lgkmcnt(" #n ")" ::: "memory")
; #define PG8_BAR __builtin_amdgcn_s_barrier()
; #define PG8_SCHED __builtin_amdgcn_sched_barrier(0)
; template <class Epi, class Sched, bool ALIGN_EPI = false, bool SP2 = false>
; __device__ __forceinline__ void gemm_phase(PG8_LAS unsigned char* lds, const Gemm g, const Sched& S, const Epi& E) {
;     ...
;             PG8_WAIT_V(8); PG8_WAIT_L(0); PG8_BAR; PG8_MMA(1, 0, At, B0); PG8_MMA(1, 1, At, B1); PG8_BAR; PG8_SCHED;
;             PG8_LDB(B0, 1, 0); PG8_LDB(B1, 1, 1); PG8_SCHED; PG8_LDA(At, 1, 0); PG8_STAGE(PG8_SA(0, 1), a2 + hstep, voffA);
;             PG8_WAIT_V(8); PG8_WAIT_L(0); PG8_BAR; PG8_MMA(0, 0, At, B0); PG8_MMA(0, 1, At, B1); PG8_BAR; PG8_SCHED;
	v_mfma_f32_16x16x32_bf16 v[60:63], v[128:131], v[198:201], v[60:63]
	v_mfma_f32_16x16x32_bf16 v[56:59], v[136:139], v[198:201], v[56:59]
	v_mfma_f32_16x16x32_bf16 v[44:47], v[128:131], v[206:209], v[44:47]
	v_mfma_f32_16x16x32_bf16 v[40:43], v[136:139], v[206:209], v[40:43]
	v_mfma_f32_16x16x32_bf16 v[28:31], v[128:131], v[214:217], v[28:31]
	v_mfma_f32_16x16x32_bf16 v[24:27], v[136:139], v[214:217], v[24:27]
	v_mfma_f32_16x16x32_bf16 v[12:15], v[128:131], v[222:225], v[12:15]
	v_mfma_f32_16x16x32_bf16 v[8:11], v[136:139], v[222:225], v[8:11]
	v_mfma_f32_16x16x32_bf16 v[60:63], v[132:135], v[202:205], v[60:63]
	v_mfma_f32_16x16x32_bf16 v[56:59], v[140:143], v[202:205], v[56:59]
	v_mfma_f32_16x16x32_bf16 v[44:47], v[132:135], v[210:213], v[44:47]
	v_mfma_f32_16x16x32_bf16 v[40:43], v[140:143], v[210:213], v[40:43]
	v_mfma_f32_16x16x32_bf16 v[28:31], v[132:135], v[218:221], v[28:31]
	v_mfma_f32_16x16x32_bf16 v[24:27], v[140:143], v[218:221], v[24:27]
	v_mfma_f32_16x16x32_bf16 v[12:15], v[132:135], v[226:229], v[12:15]
	v_mfma_f32_16x16x32_bf16 v[8:11], v[140:143], v[226:229], v[8:11]
	v_mfma_f32_16x16x32_bf16 v[52:55], v[166:169], v[198:201], v[52:55]
	v_mfma_f32_16x16x32_bf16 v[48:51], v[190:193], v[198:201], v[48:51]
	v_mfma_f32_16x16x32_bf16 v[36:39], v[166:169], v[206:209], v[36:39]
	v_mfma_f32_16x16x32_bf16 v[32:35], v[190:193], v[206:209], v[32:35]
	v_mfma_f32_16x16x32_bf16 v[20:23], v[166:169], v[214:217], v[20:23]
	v_mfma_f32_16x16x32_bf16 v[16:19], v[190:193], v[214:217], v[16:19]
	v_mfma_f32_16x16x32_bf16 v[4:7], v[166:169], v[222:225], v[4:7]
	v_mfma_f32_16x16x32_bf16 v[0:3], v[190:193], v[222:225], v[0:3]
	v_mfma_f32_16x16x32_bf16 v[52:55], v[170:173], v[202:205], v[52:55]
	v_mfma_f32_16x16x32_bf16 v[48:51], v[194:197], v[202:205], v[48:51]
	v_mfma_f32_16x16x32_bf16 v[36:39], v[170:173], v[210:213], v[36:39]
	v_mfma_f32_16x16x32_bf16 v[32:35], v[194:197], v[210:213], v[32:35]
	v_mfma_f32_16x16x32_bf16 v[20:23], v[170:173], v[218:221], v[20:23]
	v_mfma_f32_16x16x32_bf16 v[16:19], v[194:197], v[218:221], v[16:19]
	v_mfma_f32_16x16x32_bf16 v[4:7], v[170:173], v[226:229], v[4:7]
	v_mfma_f32_16x16x32_bf16 v[0:3], v[194:197], v[226:229], v[0:3]
	s_barrier
	s_add_i32 s23, 0, 0x18000
	s_add_i32 s54, 0, 0x1c000
	v_add_u32_e32 v140, s23, v176
	v_add_u32_e32 v152, s54, v176
	ds_read_b128 v[128:131], v140
	ds_read_b128 v[132:135], v140 offset:1024
	ds_read_b128 v[136:139], v140 offset:2048
	ds_read_b128 v[140:143], v140 offset:3072
	ds_read_b128 v[166:169], v152
	ds_read_b128 v[170:173], v152 offset:1024
	ds_read_b128 v[190:193], v152 offset:2048
	ds_read_b128 v[194:197], v152 offset:3072
	s_add_u32 s44, s44, 0x40000
	s_addc_u32 s45, s45, 0
	s_mov_b32 m0, s49
	v_lshl_add_u64 v[234:235], s[44:45], 0, v[144:145]
	ds_read_b128 v[198:201], v181 offset:32768
	ds_read_b128 v[202:205], v181 offset:33792
	ds_read_b128 v[206:209], v181 offset:34816
	ds_read_b128 v[210:213], v181 offset:35840
	ds_read_b128 v[214:217], v181 offset:36864
	ds_read_b128 v[218:221], v181 offset:37888
	ds_read_b128 v[222:225], v181 offset:38912
	ds_read_b128 v[226:229], v181 offset:39936
	global_load_lds_dwordx4 v[234:235], off
	v_lshl_add_u64 v[234:235], s[44:45], 0, v[148:149]
	s_mov_b32 m0, s51
	s_nop 0
	global_load_lds_dwordx4 v[234:235], off
	s_waitcnt vmcnt(8)
	s_waitcnt lgkmcnt(0)
	s_barrier
	v_mfma_f32_16x16x32_bf16 v[124:127], v[128:131], v[198:201], v[124:127]
	v_mfma_f32_16x16x32_bf16 v[120:123], v[136:139], v[198:201], v[120:123]
	v_mfma_f32_16x16x32_bf16 v[108:111], v[128:131], v[206:209], v[108:111]
	v_mfma_f32_16x16x32_bf16 v[104:107], v[136:139], v[206:209], v[104:107]
	v_mfma_f32_16x16x32_bf16 v[92:95], v[128:131], v[214:217], v[92:95]
	v_mfma_f32_16x16x32_bf16 v[88:91], v[136:139], v[214:217], v[88:91]
	v_mfma_f32_16x16x32_bf16 v[76:79], v[128:131], v[222:225], v[76:79]
	v_mfma_f32_16x16x32_bf16 v[72:75], v[136:139], v[222:225], v[72:75]
	v_mfma_f32_16x16x32_bf16 v[124:127], v[132:135], v[202:205], v[124:127]
	v_mfma_f32_16x16x32_bf16 v[120:123], v[140:143], v[202:205], v[120:123]
	v_mfma_f32_16x16x32_bf16 v[108:111], v[132:135], v[210:213], v[108:111]
	v_mfma_f32_16x16x32_bf16 v[104:107], v[140:143], v[210:213], v[104:107]
	v_mfma_f32_16x16x32_bf16 v[92:95], v[132:135], v[218:221], v[92:95]
	v_mfma_f32_16x16x32_bf16 v[88:91], v[140:143], v[218:221], v[88:91]
	v_mfma_f32_16x16x32_bf16 v[76:79], v[132:135], v[226:229], v[76:79]
	v_mfma_f32_16x16x32_bf16 v[72:75], v[140:143], v[226:229], v[72:75]
	v_mfma_f32_16x16x32_bf16 v[116:119], v[166:169], v[198:201], v[116:119]
	v_mfma_f32_16x16x32_bf16 v[112:115], v[190:193], v[198:201], v[112:115]
	v_mfma_f32_16x16x32_bf16 v[100:103], v[166:169], v[206:209], v[100:103]
	v_mfma_f32_16x16x32_bf16 v[96:99], v[190:193], v[206:209], v[96:99]
	v_mfma_f32_16x16x32_bf16 v[84:87], v[166:169], v[214:217], v[84:87]
	v_mfma_f32_16x16x32_bf16 v[80:83], v[190:193], v[214:217], v[80:83]
	v_mfma_f32_16x16x32_bf16 v[68:71], v[166:169], v[222:225], v[68:71]
	v_mfma_f32_16x16x32_bf16 v[64:67], v[190:193], v[222:225], v[64:67]
	v_mfma_f32_16x16x32_bf16 v[116:119], v[170:173], v[202:205], v[116:119]
	v_mfma_f32_16x16x32_bf16 v[112:115], v[194:197], v[202:205], v[112:115]
	v_mfma_f32_16x16x32_bf16 v[100:103], v[170:173], v[210:213], v[100:103]
	v_mfma_f32_16x16x32_bf16 v[96:99], v[194:197], v[210:213], v[96:99]
	v_mfma_f32_16x16x32_bf16 v[84:87], v[170:173], v[218:221], v[84:87]
	v_mfma_f32_16x16x32_bf16 v[80:83], v[194:197], v[218:221], v[80:83]
	v_mfma_f32_16x16x32_bf16 v[68:71], v[170:173], v[226:229], v[68:71]
	v_mfma_f32_16x16x32_bf16 v[64:67], v[194:197], v[226:229], v[64:67]
	s_barrier
; #define PG8_STAGE(bufoff, gbase, voff) do { _Pragma("unroll") for (int _i = 0; _i < 2; ++_i) \
;         __builtin_amdgcn_global_load_lds((const unsigned*)((const char*)(gbase) + (voff)[_i]), (PG8_LAS unsigned*)(lds + (bufoff) + ldsw + _i * 8192), 16, 0, 0); } while (0)
; #define PG8_LDA(dst, b, h) do { _Pragma("unroll") for (int m = 0; m < 4; ++m) _Pragma("unroll") for (int k = 0; k < 2; ++k) dst[m][k] = *(const PG8_LAS bf16x8*)(lds + PG8_SA(b, h) + aoff + m * 2048 + k * 1024); } while (0)
; #define PG8_MMA(ai, bj, At, Bt) do { __builtin_amdgcn_s_setprio(1); _Pragma("unroll") for (int m = 0; m < 4; ++m) _Pragma("unroll") for (int n = 0; n < 2; ++n) _Pragma("unroll") for (int k = 0; k < 2; ++k) \
;         acc[ai][bj][m][n] = __builtin_amdgcn_mfma_f32_16x16x32_bf16(Bt[n][k], At[m][k], acc[ai][bj][m][n], 0, 0, 0); __builtin_amdgcn_s_setprio(0); } while (0)
; #define PG8_WAIT_V(n) asm volatile("s_waitcnt vmcnt(" #n ")" ::: "memory")
; #define PG8_WAIT_L(n) asm volatile("s_waitcnt lgkmcnt(" #n ")" ::: "memory")
; #define PG8_BAR __builtin_amdgcn_s_barrier()
; #define PG8_SCHED __builtin_amdgcn_sched_barrier(0)
; template <class Epi, class Sched, bool ALIGN_EPI = false, bool SP2 = false>
; __device__ __forceinline__ void gemm_phase(PG8_LAS unsigned char* lds, const Gemm g, const Sched& S, const Epi& E) {
;     ...
;             PG8_LDA(At, 1, 1); PG8_STAGE(PG8_SB(1, 0), b3, voffB); PG8_STAGE(PG8_SB(1, 1), b3 + hstep, voffB); PG8_STAGE(PG8_SA(1, 0), a3, voffA);
;             PG8_WAIT_V(8); PG8_WAIT_L(0); PG8_BAR; PG8_MMA(1, 0, At, B0); PG8_MMA(1, 1, At, B1); PG8_BAR; PG8_SCHED;
;     ...
;         if constexpr (ALIGN_EPI) { if (wr == 0) PG8_BAR; }
	s_add_i32 s23, s23, s46
	v_lshl_add_u64 v[174:175], v[174:175], 0, s[10:11]
	s_mov_b32 m0, s23
	ds_read_b128 v[198:201], v181 offset:49152
	ds_read_b128 v[202:205], v181 offset:50176
	ds_read_b128 v[206:209], v181 offset:51200
	ds_read_b128 v[210:213], v181 offset:52224
	ds_read_b128 v[214:217], v181 offset:53248
	ds_read_b128 v[218:221], v181 offset:54272
	ds_read_b128 v[222:225], v181 offset:55296
	ds_read_b128 v[226:229], v181 offset:56320
	global_load_lds_dwordx4 v[174:175], off
	s_add_i32 m0, s23, 0x2000
	s_add_u32 s42, s42, 0x40080
	v_lshl_add_u64 v[174:175], v[186:187], 0, s[10:11]
	s_addc_u32 s43, s43, 0
	s_add_i32 s23, s54, s46
	global_load_lds_dwordx4 v[174:175], off
	v_lshl_add_u64 v[174:175], s[42:43], 0, v[146:147]
	s_mov_b32 m0, s23
	s_nop 0
	global_load_lds_dwordx4 v[174:175], off
	v_lshl_add_u64 v[174:175], s[42:43], 0, v[150:151]
	s_add_i32 m0, s23, 0x2000
	s_nop 0
	global_load_lds_dwordx4 v[174:175], off
	v_lshl_add_u64 v[174:175], v[230:231], 0, s[10:11]
	s_mov_b32 m0, s80
	s_nop 0
	global_load_lds_dwordx4 v[174:175], off
	v_lshl_add_u64 v[174:175], v[232:233], 0, s[10:11]
	s_mov_b32 m0, s81
	s_nop 0
	global_load_lds_dwordx4 v[174:175], off
	s_waitcnt vmcnt(8)
	s_waitcnt lgkmcnt(0)
	s_barrier
	v_mfma_f32_16x16x32_bf16 v[60:63], v[128:131], v[198:201], v[60:63]
	v_mfma_f32_16x16x32_bf16 v[56:59], v[136:139], v[198:201], v[56:59]
	v_mfma_f32_16x16x32_bf16 v[44:47], v[128:131], v[206:209], v[44:47]
	v_mfma_f32_16x16x32_bf16 v[40:43], v[136:139], v[206:209], v[40:43]
	v_mfma_f32_16x16x32_bf16 v[28:31], v[128:131], v[214:217], v[28:31]
	v_mfma_f32_16x16x32_bf16 v[24:27], v[136:139], v[214:217], v[24:27]
	v_mfma_f32_16x16x32_bf16 v[12:15], v[128:131], v[222:225], v[12:15]
	v_mfma_f32_16x16x32_bf16 v[8:11], v[136:139], v[222:225], v[8:11]
	v_mfma_f32_16x16x32_bf16 v[60:63], v[132:135], v[202:205], v[60:63]
	v_mfma_f32_16x16x32_bf16 v[56:59], v[140:143], v[202:205], v[56:59]
	v_mfma_f32_16x16x32_bf16 v[44:47], v[132:135], v[210:213], v[44:47]
	v_mfma_f32_16x16x32_bf16 v[40:43], v[140:143], v[210:213], v[40:43]
	v_mfma_f32_16x16x32_bf16 v[28:31], v[132:135], v[218:221], v[28:31]
	v_mfma_f32_16x16x32_bf16 v[24:27], v[140:143], v[218:221], v[24:27]
	v_mfma_f32_16x16x32_bf16 v[12:15], v[132:135], v[226:229], v[12:15]
	v_mfma_f32_16x16x32_bf16 v[8:11], v[140:143], v[226:229], v[8:11]
	v_mfma_f32_16x16x32_bf16 v[52:55], v[166:169], v[198:201], v[52:55]
	v_mfma_f32_16x16x32_bf16 v[48:51], v[190:193], v[198:201], v[48:51]
	v_mfma_f32_16x16x32_bf16 v[36:39], v[166:169], v[206:209], v[36:39]
	v_mfma_f32_16x16x32_bf16 v[32:35], v[190:193], v[206:209], v[32:35]
	v_mfma_f32_16x16x32_bf16 v[20:23], v[166:169], v[214:217], v[20:23]
	v_mfma_f32_16x16x32_bf16 v[16:19], v[190:193], v[214:217], v[16:19]
	v_mfma_f32_16x16x32_bf16 v[4:7], v[166:169], v[222:225], v[4:7]
	v_mfma_f32_16x16x32_bf16 v[0:3], v[190:193], v[222:225], v[0:3]
	v_mfma_f32_16x16x32_bf16 v[52:55], v[170:173], v[202:205], v[52:55]
	v_mfma_f32_16x16x32_bf16 v[48:51], v[194:197], v[202:205], v[48:51]
	v_mfma_f32_16x16x32_bf16 v[36:39], v[170:173], v[210:213], v[36:39]
	v_mfma_f32_16x16x32_bf16 v[32:35], v[194:197], v[210:213], v[32:35]
	v_mfma_f32_16x16x32_bf16 v[20:23], v[170:173], v[218:221], v[20:23]
	v_mfma_f32_16x16x32_bf16 v[16:19], v[194:197], v[218:221], v[16:19]
	v_mfma_f32_16x16x32_bf16 v[4:7], v[170:173], v[226:229], v[4:7]
	v_mfma_f32_16x16x32_bf16 v[0:3], v[194:197], v[226:229], v[0:3]
	s_barrier
	s_add_i32 s25, s25, 2
	s_add_u32 s40, s40, 0x100
	s_addc_u32 s41, s41, 0
	s_add_u32 vcc_hi, vcc_hi, 0x100
	s_addc_u32 s24, s24, 0
	s_cmp_gt_u32 s25, 13
	s_cbranch_scc0 .LBB0_358
	s_and_b64 vcc, exec, s[12:13]
	s_cbranch_vccz .LBB0_361
	s_barrier

; #define PG8_STAGE(bufoff, gbase, voff) do { _Pragma("unroll") for (int _i = 0; _i < 2; ++_i) \
;         __builtin_amdgcn_global_load_lds((const unsigned*)((const char*)(gbase) + (voff)[_i]), (PG8_LAS unsigned*)(lds + (bufoff) + ldsw + _i * 8192), 16, 0, 0); } while (0)
; #define PG8_LDA(dst, b, h) do { _Pragma("unroll") for (int m = 0; m < 4; ++m) _Pragma("unroll") for (int k = 0; k < 2; ++k) dst[m][k] = *(const PG8_LAS bf16x8*)(lds + PG8_SA(b, h) + aoff + m * 2048 + k * 1024); } while (0)
; #define PG8_LDB(dst, b, h) do { _Pragma("unroll") for (int n = 0; n < 2; ++n) _Pragma("unroll") for (int k = 0; k < 2; ++k) dst[n][k] = *(const PG8_LAS bf16x8*)(lds + PG8_SB(b, h) + boff + n * 2048 + k * 1024); } while (0)
; #define PG8_MMA(ai, bj, At, Bt) do { __builtin_amdgcn_s_setprio(1); _Pragma("unroll") for (int m = 0; m < 4; ++m) _Pragma("unroll") for (int n = 0; n < 2; ++n) _Pragma("unroll") for (int k = 0; k < 2; ++k) \
;         acc[ai][bj][m][n] = __builtin_amdgcn_mfma_f32_16x16x32_bf16(Bt[n][k], At[m][k], acc[ai][bj][m][n], 0, 0, 0); __builtin_amdgcn_s_setprio(0); } while (0)
; #define PG8_WAIT_V(n) asm volatile("s_waitcnt vmcnt(" #n ")" ::: "memory")
; #define PG8_WAIT_L(n) asm volatile("s_waitcnt lgkmcnt(" #n ")" ::: "memory")
; #define PG8_BAR __builtin_amdgcn_s_barrier()
; #define PG8_SCHED __builtin_amdgcn_sched_barrier(0)
; template <class Epi, class Sched, bool ALIGN_EPI = false, bool SP2 = false>
; __device__ __forceinline__ void gemm_phase(PG8_LAS unsigned char* lds, const Gemm g, const Sched& S, const Epi& E) {
;     ...
;             PG8_LDB(B0, 0, 0); PG8_LDB(B1, 0, 1); PG8_SCHED; PG8_LDA(At, 0, 0); PG8_STAGE(PG8_SA(1, 1), a1 + hstep, voffA);
;             PG8_WAIT_V(8); PG8_WAIT_L(0); PG8_BAR; PG8_MMA(0, 0, At, B0); PG8_MMA(0, 1, At, B1); PG8_BAR; PG8_SCHED;
;             PG8_LDA(At, 0, 1); PG8_STAGE(PG8_SB(0, 0), b2, voffB); PG8_STAGE(PG8_SB(0, 1), b2 + hstep, voffB); PG8_STAGE(PG8_SA(0, 0), a2, voffA);
;             PG8_WAIT_V(8); PG8_WAIT_L(0); PG8_BAR; PG8_MMA(1, 0, At, B0); PG8_MMA(1, 1, At, B1); PG8_BAR; PG8_SCHED;
.LBB0_684:
	ds_read_b128 v[128:131], v174
	ds_read_b128 v[132:135], v174 offset:1024
	ds_read_b128 v[136:139], v174 offset:2048
	ds_read_b128 v[140:143], v174 offset:3072
	ds_read_b128 v[162:165], v175
	ds_read_b128 v[166:169], v175 offset:1024
	ds_read_b128 v[180:183], v175 offset:2048
	ds_read_b128 v[184:187], v175 offset:3072
	s_add_u32 s8, s0, 0xfffc0080
	s_addc_u32 s9, s1, -1
	s_cmp_eq_u32 vcc_lo, 12
	s_cselect_b32 s43, s3, s9
	s_cselect_b32 s42, s94, s8
	s_cselect_b32 s41, s5, s97
	s_cselect_b32 s40, s95, s96
	s_add_i32 m0, s47, 0xc000
	ds_read_b128 v[190:193], v176
	ds_read_b128 v[194:197], v176 offset:1024
	ds_read_b128 v[198:201], v176 offset:2048
	ds_read_b128 v[202:205], v176 offset:3072
	ds_read_b128 v[206:209], v176 offset:4096
	ds_read_b128 v[210:213], v176 offset:5120
	ds_read_b128 v[214:217], v176 offset:6144
	ds_read_b128 v[218:221], v176 offset:7168
	global_load_lds_dwordx4 v158, s[0:1]
	s_add_i32 m0, s47, 0xe000
	s_nop 0
	global_load_lds_dwordx4 v160, s[0:1]
	s_waitcnt vmcnt(8)
	s_waitcnt lgkmcnt(0)
	s_barrier
	v_mfma_f32_16x16x32_bf16 v[124:127], v[128:131], v[190:193], v[124:127]
	v_mfma_f32_16x16x32_bf16 v[120:123], v[136:139], v[190:193], v[120:123]
	v_mfma_f32_16x16x32_bf16 v[108:111], v[128:131], v[198:201], v[108:111]
	v_mfma_f32_16x16x32_bf16 v[104:107], v[136:139], v[198:201], v[104:107]
	v_mfma_f32_16x16x32_bf16 v[92:95], v[128:131], v[206:209], v[92:95]
	v_mfma_f32_16x16x32_bf16 v[88:91], v[136:139], v[206:209], v[88:91]
	v_mfma_f32_16x16x32_bf16 v[76:79], v[128:131], v[214:217], v[76:79]
	v_mfma_f32_16x16x32_bf16 v[72:75], v[136:139], v[214:217], v[72:75]
	v_mfma_f32_16x16x32_bf16 v[124:127], v[132:135], v[194:197], v[124:127]
	v_mfma_f32_16x16x32_bf16 v[120:123], v[140:143], v[194:197], v[120:123]
	v_mfma_f32_16x16x32_bf16 v[108:111], v[132:135], v[202:205], v[108:111]
	v_mfma_f32_16x16x32_bf16 v[104:107], v[140:143], v[202:205], v[104:107]
	v_mfma_f32_16x16x32_bf16 v[92:95], v[132:135], v[210:213], v[92:95]
	v_mfma_f32_16x16x32_bf16 v[88:91], v[140:143], v[210:213], v[88:91]
	v_mfma_f32_16x16x32_bf16 v[76:79], v[132:135], v[218:221], v[76:79]
	v_mfma_f32_16x16x32_bf16 v[72:75], v[140:143], v[218:221], v[72:75]
	v_mfma_f32_16x16x32_bf16 v[116:119], v[162:165], v[190:193], v[116:119]
	v_mfma_f32_16x16x32_bf16 v[112:115], v[180:183], v[190:193], v[112:115]
	v_mfma_f32_16x16x32_bf16 v[100:103], v[162:165], v[198:201], v[100:103]
	v_mfma_f32_16x16x32_bf16 v[96:99], v[180:183], v[198:201], v[96:99]
	v_mfma_f32_16x16x32_bf16 v[84:87], v[162:165], v[206:209], v[84:87]
	v_mfma_f32_16x16x32_bf16 v[80:83], v[180:183], v[206:209], v[80:83]
	v_mfma_f32_16x16x32_bf16 v[68:71], v[162:165], v[214:217], v[68:71]
	v_mfma_f32_16x16x32_bf16 v[64:67], v[180:183], v[214:217], v[64:67]
	v_mfma_f32_16x16x32_bf16 v[116:119], v[166:169], v[194:197], v[116:119]
	v_mfma_f32_16x16x32_bf16 v[112:115], v[184:187], v[194:197], v[112:115]
	v_mfma_f32_16x16x32_bf16 v[100:103], v[166:169], v[202:205], v[100:103]
	v_mfma_f32_16x16x32_bf16 v[96:99], v[184:187], v[202:205], v[96:99]
	v_mfma_f32_16x16x32_bf16 v[84:87], v[166:169], v[210:213], v[84:87]
	v_mfma_f32_16x16x32_bf16 v[80:83], v[184:187], v[210:213], v[80:83]
	v_mfma_f32_16x16x32_bf16 v[68:71], v[166:169], v[218:221], v[68:71]
	v_mfma_f32_16x16x32_bf16 v[64:67], v[184:187], v[218:221], v[64:67]
	s_barrier
	s_add_i32 s8, s76, s46
	v_lshl_add_u64 v[170:171], s[40:41], 0, v[146:147]
	s_mov_b32 m0, s8
	ds_read_b128 v[190:193], v176 offset:16384
	ds_read_b128 v[194:197], v176 offset:17408
	ds_read_b128 v[198:201], v176 offset:18432
	ds_read_b128 v[202:205], v176 offset:19456
	ds_read_b128 v[206:209], v176 offset:20480
	ds_read_b128 v[210:213], v176 offset:21504
	ds_read_b128 v[214:217], v176 offset:22528
	ds_read_b128 v[218:221], v176 offset:23552
	global_load_lds_dwordx4 v[170:171], off
	s_add_i32 m0, s8, 0x2000
	s_add_u32 s8, s40, 0x40000
	v_lshl_add_u64 v[222:223], s[40:41], 0, v[150:151]
	s_addc_u32 s9, s41, 0
	s_add_i32 s54, s77, s46
	global_load_lds_dwordx4 v[222:223], off
	s_mov_b32 m0, s54
	v_lshl_add_u64 v[226:227], s[42:43], 0, v[148:149]
	global_load_lds_dwordx4 v146, s[8:9]
	s_add_i32 m0, s54, 0x2000
	s_nop 0
	global_load_lds_dwordx4 v150, s[8:9]
	v_lshl_add_u64 v[224:225], s[42:43], 0, v[144:145]
	s_mov_b32 m0, s47
	s_nop 0
	global_load_lds_dwordx4 v[224:225], off
	s_mov_b32 m0, s48
	s_nop 0
	global_load_lds_dwordx4 v[226:227], off
	s_waitcnt vmcnt(8)
	s_waitcnt lgkmcnt(0)
	s_barrier
	v_mfma_f32_16x16x32_bf16 v[60:63], v[128:131], v[190:193], v[60:63]
	v_mfma_f32_16x16x32_bf16 v[56:59], v[136:139], v[190:193], v[56:59]
	v_mfma_f32_16x16x32_bf16 v[44:47], v[128:131], v[198:201], v[44:47]
	v_mfma_f32_16x16x32_bf16 v[40:43], v[136:139], v[198:201], v[40:43]
	v_mfma_f32_16x16x32_bf16 v[28:31], v[128:131], v[206:209], v[28:31]
	v_mfma_f32_16x16x32_bf16 v[24:27], v[136:139], v[206:209], v[24:27]
	v_mfma_f32_16x16x32_bf16 v[12:15], v[128:131], v[214:217], v[12:15]
	v_mfma_f32_16x16x32_bf16 v[8:11], v[136:139], v[214:217], v[8:11]
	v_mfma_f32_16x16x32_bf16 v[60:63], v[132:135], v[194:197], v[60:63]
	v_mfma_f32_16x16x32_bf16 v[56:59], v[140:143], v[194:197], v[56:59]
	v_mfma_f32_16x16x32_bf16 v[44:47], v[132:135], v[202:205], v[44:47]
	v_mfma_f32_16x16x32_bf16 v[40:43], v[140:143], v[202:205], v[40:43]
	v_mfma_f32_16x16x32_bf16 v[28:31], v[132:135], v[210:213], v[28:31]
	v_mfma_f32_16x16x32_bf16 v[24:27], v[140:143], v[210:213], v[24:27]
	v_mfma_f32_16x16x32_bf16 v[12:15], v[132:135], v[218:221], v[12:15]
	v_mfma_f32_16x16x32_bf16 v[8:11], v[140:143], v[218:221], v[8:11]
	v_mfma_f32_16x16x32_bf16 v[52:55], v[162:165], v[190:193], v[52:55]
	v_mfma_f32_16x16x32_bf16 v[48:51], v[180:183], v[190:193], v[48:51]
	v_mfma_f32_16x16x32_bf16 v[36:39], v[162:165], v[198:201], v[36:39]
	v_mfma_f32_16x16x32_bf16 v[32:35], v[180:183], v[198:201], v[32:35]
	v_mfma_f32_16x16x32_bf16 v[20:23], v[162:165], v[206:209], v[20:23]
	v_mfma_f32_16x16x32_bf16 v[16:19], v[180:183], v[206:209], v[16:19]
	v_mfma_f32_16x16x32_bf16 v[4:7], v[162:165], v[214:217], v[4:7]
	v_mfma_f32_16x16x32_bf16 v[0:3], v[180:183], v[214:217], v[0:3]
	v_mfma_f32_16x16x32_bf16 v[52:55], v[166:169], v[194:197], v[52:55]
	v_mfma_f32_16x16x32_bf16 v[48:51], v[184:187], v[194:197], v[48:51]
	v_mfma_f32_16x16x32_bf16 v[36:39], v[166:169], v[202:205], v[36:39]
	v_mfma_f32_16x16x32_bf16 v[32:35], v[184:187], v[202:205], v[32:35]
	v_mfma_f32_16x16x32_bf16 v[20:23], v[166:169], v[210:213], v[20:23]
	v_mfma_f32_16x16x32_bf16 v[16:19], v[184:187], v[210:213], v[16:19]
	v_mfma_f32_16x16x32_bf16 v[4:7], v[166:169], v[218:221], v[4:7]
	v_mfma_f32_16x16x32_bf16 v[0:3], v[184:187], v[218:221], v[0:3]
	s_barrier
; #define PG8_STAGE(bufoff, gbase, voff) do { _Pragma("unroll") for (int _i = 0; _i < 2; ++_i) \
;         __builtin_amdgcn_global_load_lds((const unsigned*)((const char*)(gbase) + (voff)[_i]), (PG8_LAS unsigned*)(lds + (bufoff) + ldsw + _i * 8192), 16, 0, 0); } while (0)
; #define PG8_LDA(dst, b, h) do { _Pragma("unroll") for (int m = 0; m < 4; ++m) _Pragma("unroll") for (int k = 0; k < 2; ++k) dst[m][k] = *(const PG8_LAS bf16x8*)(lds + PG8_SA(b, h) + aoff + m * 2048 + k * 1024); } while (0)
; #define PG8_LDB(dst, b, h) do { _Pragma("unroll") for (int n = 0; n < 2; ++n) _Pragma("unroll") for (int k = 0; k < 2; ++k) dst[n][k] = *(const PG8_LAS bf16x8*)(lds + PG8_SB(b, h) + boff + n * 2048 + k * 1024); } while (0)
; #define PG8_MMA(ai, bj, At, Bt) do { __builtin_amdgcn_s_setprio(1); _Pragma("unroll") for (int m = 0; m < 4; ++m) _Pragma("unroll") for (int n = 0; n < 2; ++n) _Pragma("unroll") for (int k = 0; k < 2; ++k) \
;         acc[ai][bj][m][n] = __builtin_amdgcn_mfma_f32_16x16x32_bf16(Bt[n][k], At[m][k], acc[ai][bj][m][n], 0, 0, 0); __builtin_amdgcn_s_setprio(0); } while (0)
; #define PG8_WAIT_V(n) asm volatile("s_waitcnt vmcnt(" #n ")" ::: "memory")
; #define PG8_WAIT_L(n) asm volatile("s_waitcnt lgkmcnt(" #n ")" ::: "memory")
; #define PG8_BAR __builtin_amdgcn_s_barrier()
; #define PG8_SCHED __builtin_amdgcn_sched_barrier(0)
; template <class Epi, class Sched, bool ALIGN_EPI = false, bool SP2 = false>
; __device__ __forceinline__ void gemm_phase(PG8_LAS unsigned char* lds, const Gemm g, const Sched& S, const Epi& E) {
;     ...
;             PG8_LDB(B0, 1, 0); PG8_LDB(B1, 1, 1); PG8_SCHED; PG8_LDA(At, 1, 0); PG8_STAGE(PG8_SA(0, 1), a2 + hstep, voffA);
;             PG8_WAIT_V(8); PG8_WAIT_L(0); PG8_BAR; PG8_MMA(0, 0, At, B0); PG8_MMA(0, 1, At, B1); PG8_BAR; PG8_SCHED;
;             PG8_LDA(At, 1, 1); PG8_STAGE(PG8_SB(1, 0), b3, voffB); PG8_STAGE(PG8_SB(1, 1), b3 + hstep, voffB); PG8_STAGE(PG8_SA(1, 0), a3, voffA);
;             PG8_WAIT_V(8); PG8_WAIT_L(0); PG8_BAR; PG8_MMA(1, 0, At, B0); PG8_MMA(1, 1, At, B1); PG8_BAR; PG8_SCHED;
;     ...
;         if constexpr (ALIGN_EPI) { if (wr == 0) PG8_BAR; }
	s_add_i32 s54, 0, 0x18000
	s_add_i32 s55, 0, 0x1c000
	v_add_u32_e32 v140, s54, v172
	v_add_u32_e32 v152, s55, v172
	ds_read_b128 v[128:131], v140
	ds_read_b128 v[132:135], v140 offset:1024
	ds_read_b128 v[136:139], v140 offset:2048
	ds_read_b128 v[140:143], v140 offset:3072
	ds_read_b128 v[162:165], v152
	ds_read_b128 v[166:169], v152 offset:1024
	ds_read_b128 v[180:183], v152 offset:2048
	ds_read_b128 v[184:187], v152 offset:3072
	s_add_u32 s8, s42, 0x40000
	s_addc_u32 s9, s43, 0
	s_mov_b32 m0, s49
	ds_read_b128 v[190:193], v176 offset:32768
	ds_read_b128 v[194:197], v176 offset:33792
	ds_read_b128 v[198:201], v176 offset:34816
	ds_read_b128 v[202:205], v176 offset:35840
	ds_read_b128 v[206:209], v176 offset:36864
	ds_read_b128 v[210:213], v176 offset:37888
	ds_read_b128 v[214:217], v176 offset:38912
	ds_read_b128 v[218:221], v176 offset:39936
	global_load_lds_dwordx4 v144, s[8:9]
	s_mov_b32 m0, s51
	s_nop 0
	global_load_lds_dwordx4 v148, s[8:9]
	s_waitcnt vmcnt(8)
	s_waitcnt lgkmcnt(0)
	s_barrier
	v_mfma_f32_16x16x32_bf16 v[124:127], v[128:131], v[190:193], v[124:127]
	v_mfma_f32_16x16x32_bf16 v[120:123], v[136:139], v[190:193], v[120:123]
	v_mfma_f32_16x16x32_bf16 v[108:111], v[128:131], v[198:201], v[108:111]
	v_mfma_f32_16x16x32_bf16 v[104:107], v[136:139], v[198:201], v[104:107]
	v_mfma_f32_16x16x32_bf16 v[92:95], v[128:131], v[206:209], v[92:95]
	v_mfma_f32_16x16x32_bf16 v[88:91], v[136:139], v[206:209], v[88:91]
	v_mfma_f32_16x16x32_bf16 v[76:79], v[128:131], v[214:217], v[76:79]
	v_mfma_f32_16x16x32_bf16 v[72:75], v[136:139], v[214:217], v[72:75]
	v_mfma_f32_16x16x32_bf16 v[124:127], v[132:135], v[194:197], v[124:127]
	v_mfma_f32_16x16x32_bf16 v[120:123], v[140:143], v[194:197], v[120:123]
	v_mfma_f32_16x16x32_bf16 v[108:111], v[132:135], v[202:205], v[108:111]
	v_mfma_f32_16x16x32_bf16 v[104:107], v[140:143], v[202:205], v[104:107]
	v_mfma_f32_16x16x32_bf16 v[92:95], v[132:135], v[210:213], v[92:95]
	v_mfma_f32_16x16x32_bf16 v[88:91], v[140:143], v[210:213], v[88:91]
	v_mfma_f32_16x16x32_bf16 v[76:79], v[132:135], v[218:221], v[76:79]
	v_mfma_f32_16x16x32_bf16 v[72:75], v[140:143], v[218:221], v[72:75]
	v_mfma_f32_16x16x32_bf16 v[116:119], v[162:165], v[190:193], v[116:119]
	v_mfma_f32_16x16x32_bf16 v[112:115], v[180:183], v[190:193], v[112:115]
	v_mfma_f32_16x16x32_bf16 v[100:103], v[162:165], v[198:201], v[100:103]
	v_mfma_f32_16x16x32_bf16 v[96:99], v[180:183], v[198:201], v[96:99]
	v_mfma_f32_16x16x32_bf16 v[84:87], v[162:165], v[206:209], v[84:87]
	v_mfma_f32_16x16x32_bf16 v[80:83], v[180:183], v[206:209], v[80:83]
	v_mfma_f32_16x16x32_bf16 v[68:71], v[162:165], v[214:217], v[68:71]
	v_mfma_f32_16x16x32_bf16 v[64:67], v[180:183], v[214:217], v[64:67]
	v_mfma_f32_16x16x32_bf16 v[116:119], v[166:169], v[194:197], v[116:119]
	v_mfma_f32_16x16x32_bf16 v[112:115], v[184:187], v[194:197], v[112:115]
	v_mfma_f32_16x16x32_bf16 v[100:103], v[166:169], v[202:205], v[100:103]
	v_mfma_f32_16x16x32_bf16 v[96:99], v[184:187], v[202:205], v[96:99]
	v_mfma_f32_16x16x32_bf16 v[84:87], v[166:169], v[210:213], v[84:87]
	v_mfma_f32_16x16x32_bf16 v[80:83], v[184:187], v[210:213], v[80:83]
	v_mfma_f32_16x16x32_bf16 v[68:71], v[166:169], v[218:221], v[68:71]
	v_mfma_f32_16x16x32_bf16 v[64:67], v[184:187], v[218:221], v[64:67]
	s_barrier
	s_add_i32 s8, s54, s46
	v_lshl_add_u64 v[170:171], v[170:171], 0, s[14:15]
	s_mov_b32 m0, s8
	ds_read_b128 v[190:193], v176 offset:49152
	ds_read_b128 v[194:197], v176 offset:50176
	ds_read_b128 v[198:201], v176 offset:51200
	ds_read_b128 v[202:205], v176 offset:52224
	ds_read_b128 v[206:209], v176 offset:53248
	ds_read_b128 v[210:213], v176 offset:54272
	ds_read_b128 v[214:217], v176 offset:55296
	ds_read_b128 v[218:221], v176 offset:56320
	global_load_lds_dwordx4 v[170:171], off
	s_add_i32 m0, s8, 0x2000
	s_add_u32 s8, s40, 0x40080
	v_lshl_add_u64 v[170:171], v[222:223], 0, s[14:15]
	s_addc_u32 s9, s41, 0
	s_add_i32 s40, s55, s46
	global_load_lds_dwordx4 v[170:171], off
	s_mov_b32 m0, s40
	s_nop 0
	global_load_lds_dwordx4 v146, s[8:9]
	s_add_i32 m0, s40, 0x2000
	s_nop 0
	global_load_lds_dwordx4 v150, s[8:9]
	v_lshl_add_u64 v[170:171], v[224:225], 0, s[14:15]
	s_mov_b32 m0, s66
	s_nop 0
	global_load_lds_dwordx4 v[170:171], off
	v_lshl_add_u64 v[170:171], v[226:227], 0, s[14:15]
	s_mov_b32 m0, s67
	s_nop 0
	global_load_lds_dwordx4 v[170:171], off
	s_waitcnt vmcnt(8)
	s_waitcnt lgkmcnt(0)
	s_barrier
	v_mfma_f32_16x16x32_bf16 v[60:63], v[128:131], v[190:193], v[60:63]
	v_mfma_f32_16x16x32_bf16 v[56:59], v[136:139], v[190:193], v[56:59]
	v_mfma_f32_16x16x32_bf16 v[44:47], v[128:131], v[198:201], v[44:47]
	v_mfma_f32_16x16x32_bf16 v[40:43], v[136:139], v[198:201], v[40:43]
	v_mfma_f32_16x16x32_bf16 v[28:31], v[128:131], v[206:209], v[28:31]
	v_mfma_f32_16x16x32_bf16 v[24:27], v[136:139], v[206:209], v[24:27]
	v_mfma_f32_16x16x32_bf16 v[12:15], v[128:131], v[214:217], v[12:15]
	v_mfma_f32_16x16x32_bf16 v[8:11], v[136:139], v[214:217], v[8:11]
	v_mfma_f32_16x16x32_bf16 v[60:63], v[132:135], v[194:197], v[60:63]
	v_mfma_f32_16x16x32_bf16 v[56:59], v[140:143], v[194:197], v[56:59]
	v_mfma_f32_16x16x32_bf16 v[44:47], v[132:135], v[202:205], v[44:47]
	v_mfma_f32_16x16x32_bf16 v[40:43], v[140:143], v[202:205], v[40:43]
	v_mfma_f32_16x16x32_bf16 v[28:31], v[132:135], v[210:213], v[28:31]
	v_mfma_f32_16x16x32_bf16 v[24:27], v[140:143], v[210:213], v[24:27]
	v_mfma_f32_16x16x32_bf16 v[12:15], v[132:135], v[218:221], v[12:15]
	v_mfma_f32_16x16x32_bf16 v[8:11], v[140:143], v[218:221], v[8:11]
	v_mfma_f32_16x16x32_bf16 v[52:55], v[162:165], v[190:193], v[52:55]
	v_mfma_f32_16x16x32_bf16 v[48:51], v[180:183], v[190:193], v[48:51]
	v_mfma_f32_16x16x32_bf16 v[36:39], v[162:165], v[198:201], v[36:39]
	v_mfma_f32_16x16x32_bf16 v[32:35], v[180:183], v[198:201], v[32:35]
	v_mfma_f32_16x16x32_bf16 v[20:23], v[162:165], v[206:209], v[20:23]
	v_mfma_f32_16x16x32_bf16 v[16:19], v[180:183], v[206:209], v[16:19]
	v_mfma_f32_16x16x32_bf16 v[4:7], v[162:165], v[214:217], v[4:7]
	v_mfma_f32_16x16x32_bf16 v[0:3], v[180:183], v[214:217], v[0:3]
	v_mfma_f32_16x16x32_bf16 v[52:55], v[166:169], v[194:197], v[52:55]
	v_mfma_f32_16x16x32_bf16 v[48:51], v[184:187], v[194:197], v[48:51]
	v_mfma_f32_16x16x32_bf16 v[36:39], v[166:169], v[202:205], v[36:39]
	v_mfma_f32_16x16x32_bf16 v[32:35], v[184:187], v[202:205], v[32:35]
	v_mfma_f32_16x16x32_bf16 v[20:23], v[166:169], v[210:213], v[20:23]
	v_mfma_f32_16x16x32_bf16 v[16:19], v[184:187], v[210:213], v[16:19]
	v_mfma_f32_16x16x32_bf16 v[4:7], v[166:169], v[218:221], v[4:7]
	v_mfma_f32_16x16x32_bf16 v[0:3], v[184:187], v[218:221], v[0:3]
	s_barrier
	s_add_i32 vcc_lo, vcc_lo, 2
	s_add_u32 s0, s0, 0x100
	s_addc_u32 s1, s1, 0
	s_add_u32 s96, s96, 0x100
	s_addc_u32 s97, s97, 0
	s_cmp_gt_u32 vcc_lo, 13
	s_cbranch_scc0 .LBB0_684
	s_and_b64 vcc, exec, s[18:19]
	s_cbranch_vccz .LBB0_687
	s_barrier

; #define PG8_STAGE(bufoff, gbase, voff) do { _Pragma("unroll") for (int _i = 0; _i < 2; ++_i) \
;         __builtin_amdgcn_global_load_lds((const unsigned*)((const char*)(gbase) + (voff)[_i]), (PG8_LAS unsigned*)(lds + (bufoff) + ldsw + _i * 8192), 16, 0, 0); } while (0)
; #define PG8_LDA(dst, b, h) do { _Pragma("unroll") for (int m = 0; m < 4; ++m) _Pragma("unroll") for (int k = 0; k < 2; ++k) dst[m][k] = *(const PG8_LAS bf16x8*)(lds + PG8_SA(b, h) + aoff + m * 2048 + k * 1024); } while (0)
; #define PG8_LDB(dst, b, h) do { _Pragma("unroll") for (int n = 0; n < 2; ++n) _Pragma("unroll") for (int k = 0; k < 2; ++k) dst[n][k] = *(const PG8_LAS bf16x8*)(lds + PG8_SB(b, h) + boff + n * 2048 + k * 1024); } while (0)
; #define PG8_MMA(ai, bj, At, Bt) do { __builtin_amdgcn_s_setprio(1); _Pragma("unroll") for (int m = 0; m < 4; ++m) _Pragma("unroll") for (int n = 0; n < 2; ++n) _Pragma("unroll") for (int k = 0; k < 2; ++k) \
;         acc[ai][bj][m][n] = __builtin_amdgcn_mfma_f32_16x16x32_bf16(Bt[n][k], At[m][k], acc[ai][bj][m][n], 0, 0, 0); __builtin_amdgcn_s_setprio(0); } while (0)
; #define PG8_WAIT_V(n) asm volatile("s_waitcnt vmcnt(" #n ")" ::: "memory")
; #define PG8_WAIT_L(n) asm volatile("s_waitcnt lgkmcnt(" #n ")" ::: "memory")
; #define PG8_BAR __builtin_amdgcn_s_barrier()
; #define PG8_SCHED __builtin_amdgcn_sched_barrier(0)
; template <class Epi, class Sched, bool ALIGN_EPI = false, bool SP2 = false>
; __device__ __forceinline__ void gemm_phase(PG8_LAS unsigned char* lds, const Gemm g, const Sched& S, const Epi& E) {
;     ...
;             PG8_LDB(B0, 0, 0); PG8_LDB(B1, 0, 1); PG8_SCHED; PG8_LDA(At, 0, 0); PG8_STAGE(PG8_SA(1, 1), a1 + hstep, voffA);
;             PG8_WAIT_V(8); PG8_WAIT_L(0); PG8_BAR; PG8_MMA(0, 0, At, B0); PG8_MMA(0, 1, At, B1); PG8_BAR; PG8_SCHED;
;             PG8_LDA(At, 0, 1); PG8_STAGE(PG8_SB(0, 0), b2, voffB); PG8_STAGE(PG8_SB(0, 1), b2 + hstep, voffB); PG8_STAGE(PG8_SA(0, 0), a2, voffA);
;             PG8_WAIT_V(8); PG8_WAIT_L(0); PG8_BAR; PG8_MMA(1, 0, At, B0); PG8_MMA(1, 1, At, B1); PG8_BAR; PG8_SCHED;
.LBB0_795:
	v_add_u32_e32 v162, s67, v186
	v_add_u32_e32 v178, s68, v186
	ds_read_b128 v[150:153], v162
	ds_read_b128 v[154:157], v162 offset:1024
	ds_read_b128 v[158:161], v162 offset:2048
	ds_read_b128 v[162:165], v162 offset:3072
	ds_read_b128 v[166:169], v178
	ds_read_b128 v[170:173], v178 offset:1024
	ds_read_b128 v[174:177], v178 offset:2048
	ds_read_b128 v[178:181], v178 offset:3072
	s_add_u32 s54, s46, 0xfff80080
	s_addc_u32 s55, s47, -1
	s_cmp_eq_u32 s82, 12
	s_cselect_b32 s57, s41, s55
	s_cselect_b32 s56, s78, s54
	s_cselect_b32 s55, s39, s81
	s_cselect_b32 s54, s79, s80
	s_add_i32 m0, s61, 0xc000
	ds_read_b128 v[182:185], v187
	ds_read_b128 v[190:193], v187 offset:1024
	ds_read_b128 v[194:197], v187 offset:2048
	ds_read_b128 v[198:201], v187 offset:3072
	ds_read_b128 v[202:205], v187 offset:4096
	ds_read_b128 v[206:209], v187 offset:5120
	ds_read_b128 v[210:213], v187 offset:6144
	ds_read_b128 v[214:217], v187 offset:7168
	global_load_lds_dwordx4 v142, s[46:47]
	s_add_i32 m0, s61, 0xe000
	s_nop 0
	global_load_lds_dwordx4 v144, s[46:47]
	s_waitcnt vmcnt(8)
	s_waitcnt lgkmcnt(0)
	s_barrier
	v_mfma_f32_16x16x32_bf16 v[124:127], v[150:153], v[182:185], v[124:127]
	v_mfma_f32_16x16x32_bf16 v[120:123], v[158:161], v[182:185], v[120:123]
	v_mfma_f32_16x16x32_bf16 v[116:119], v[150:153], v[194:197], v[116:119]
	v_mfma_f32_16x16x32_bf16 v[112:115], v[158:161], v[194:197], v[112:115]
	v_mfma_f32_16x16x32_bf16 v[108:111], v[150:153], v[202:205], v[108:111]
	v_mfma_f32_16x16x32_bf16 v[104:107], v[158:161], v[202:205], v[104:107]
	v_mfma_f32_16x16x32_bf16 v[100:103], v[150:153], v[210:213], v[100:103]
	v_mfma_f32_16x16x32_bf16 v[96:99], v[158:161], v[210:213], v[96:99]
	v_mfma_f32_16x16x32_bf16 v[124:127], v[154:157], v[190:193], v[124:127]
	v_mfma_f32_16x16x32_bf16 v[120:123], v[162:165], v[190:193], v[120:123]
	v_mfma_f32_16x16x32_bf16 v[116:119], v[154:157], v[198:201], v[116:119]
	v_mfma_f32_16x16x32_bf16 v[112:115], v[162:165], v[198:201], v[112:115]
	v_mfma_f32_16x16x32_bf16 v[108:111], v[154:157], v[206:209], v[108:111]
	v_mfma_f32_16x16x32_bf16 v[104:107], v[162:165], v[206:209], v[104:107]
	v_mfma_f32_16x16x32_bf16 v[100:103], v[154:157], v[214:217], v[100:103]
	v_mfma_f32_16x16x32_bf16 v[96:99], v[162:165], v[214:217], v[96:99]
	v_mfma_f32_16x16x32_bf16 v[92:95], v[166:169], v[182:185], v[92:95]
	v_mfma_f32_16x16x32_bf16 v[88:91], v[174:177], v[182:185], v[88:91]
	v_mfma_f32_16x16x32_bf16 v[84:87], v[166:169], v[194:197], v[84:87]
	v_mfma_f32_16x16x32_bf16 v[80:83], v[174:177], v[194:197], v[80:83]
	v_mfma_f32_16x16x32_bf16 v[76:79], v[166:169], v[202:205], v[76:79]
	v_mfma_f32_16x16x32_bf16 v[72:75], v[174:177], v[202:205], v[72:75]
	v_mfma_f32_16x16x32_bf16 v[68:71], v[166:169], v[210:213], v[68:71]
	v_mfma_f32_16x16x32_bf16 v[64:67], v[174:177], v[210:213], v[64:67]
	v_mfma_f32_16x16x32_bf16 v[92:95], v[170:173], v[190:193], v[92:95]
	v_mfma_f32_16x16x32_bf16 v[88:91], v[178:181], v[190:193], v[88:91]
	v_mfma_f32_16x16x32_bf16 v[84:87], v[170:173], v[198:201], v[84:87]
	v_mfma_f32_16x16x32_bf16 v[80:83], v[178:181], v[198:201], v[80:83]
	v_mfma_f32_16x16x32_bf16 v[76:79], v[170:173], v[206:209], v[76:79]
	v_mfma_f32_16x16x32_bf16 v[72:75], v[178:181], v[206:209], v[72:75]
	v_mfma_f32_16x16x32_bf16 v[68:71], v[170:173], v[214:217], v[68:71]
	v_mfma_f32_16x16x32_bf16 v[64:67], v[178:181], v[214:217], v[64:67]
	s_barrier
	s_add_i32 s83, s67, s60
	v_lshl_add_u64 v[218:219], s[54:55], 0, v[130:131]
	s_mov_b32 m0, s83
	ds_read_b128 v[182:185], v187 offset:16384
	ds_read_b128 v[190:193], v187 offset:17408
	ds_read_b128 v[194:197], v187 offset:18432
	ds_read_b128 v[198:201], v187 offset:19456
	ds_read_b128 v[202:205], v187 offset:20480
	ds_read_b128 v[206:209], v187 offset:21504
	ds_read_b128 v[210:213], v187 offset:22528
	ds_read_b128 v[214:217], v187 offset:23552
	global_load_lds_dwordx4 v[218:219], off
	s_add_i32 m0, s83, 0x2000
	s_add_u32 s86, s54, 0x80000
	v_lshl_add_u64 v[220:221], s[54:55], 0, v[134:135]
	s_addc_u32 s87, s55, 0
	s_add_i32 s83, s68, s60
	global_load_lds_dwordx4 v[220:221], off
	s_mov_b32 m0, s83
	v_lshl_add_u64 v[224:225], s[56:57], 0, v[132:133]
	global_load_lds_dwordx4 v130, s[86:87]
	s_add_i32 m0, s83, 0x2000
	s_nop 0
	global_load_lds_dwordx4 v134, s[86:87]
	v_lshl_add_u64 v[222:223], s[56:57], 0, v[128:129]
	s_mov_b32 m0, s61
	s_nop 0
	global_load_lds_dwordx4 v[222:223], off
	s_mov_b32 m0, s62
	s_nop 0
	global_load_lds_dwordx4 v[224:225], off
	s_waitcnt vmcnt(8)
	s_waitcnt lgkmcnt(0)
	s_barrier
	v_mfma_f32_16x16x32_bf16 v[60:63], v[150:153], v[182:185], v[60:63]
	v_mfma_f32_16x16x32_bf16 v[56:59], v[158:161], v[182:185], v[56:59]
	v_mfma_f32_16x16x32_bf16 v[52:55], v[150:153], v[194:197], v[52:55]
	v_mfma_f32_16x16x32_bf16 v[48:51], v[158:161], v[194:197], v[48:51]
	v_mfma_f32_16x16x32_bf16 v[44:47], v[150:153], v[202:205], v[44:47]
	v_mfma_f32_16x16x32_bf16 v[40:43], v[158:161], v[202:205], v[40:43]
	v_mfma_f32_16x16x32_bf16 v[36:39], v[150:153], v[210:213], v[36:39]
	v_mfma_f32_16x16x32_bf16 v[32:35], v[158:161], v[210:213], v[32:35]
	v_mfma_f32_16x16x32_bf16 v[60:63], v[154:157], v[190:193], v[60:63]
	v_mfma_f32_16x16x32_bf16 v[56:59], v[162:165], v[190:193], v[56:59]
	v_mfma_f32_16x16x32_bf16 v[52:55], v[154:157], v[198:201], v[52:55]
	v_mfma_f32_16x16x32_bf16 v[48:51], v[162:165], v[198:201], v[48:51]
	v_mfma_f32_16x16x32_bf16 v[44:47], v[154:157], v[206:209], v[44:47]
	v_mfma_f32_16x16x32_bf16 v[40:43], v[162:165], v[206:209], v[40:43]
	v_mfma_f32_16x16x32_bf16 v[36:39], v[154:157], v[214:217], v[36:39]
	v_mfma_f32_16x16x32_bf16 v[32:35], v[162:165], v[214:217], v[32:35]
	v_mfma_f32_16x16x32_bf16 v[28:31], v[166:169], v[182:185], v[28:31]
	v_mfma_f32_16x16x32_bf16 v[24:27], v[174:177], v[182:185], v[24:27]
	v_mfma_f32_16x16x32_bf16 v[20:23], v[166:169], v[194:197], v[20:23]
	v_mfma_f32_16x16x32_bf16 v[16:19], v[174:177], v[194:197], v[16:19]
	v_mfma_f32_16x16x32_bf16 v[12:15], v[166:169], v[202:205], v[12:15]
	v_mfma_f32_16x16x32_bf16 v[8:11], v[174:177], v[202:205], v[8:11]
	v_mfma_f32_16x16x32_bf16 v[4:7], v[166:169], v[210:213], v[4:7]
	v_mfma_f32_16x16x32_bf16 v[0:3], v[174:177], v[210:213], v[0:3]
	v_mfma_f32_16x16x32_bf16 v[28:31], v[170:173], v[190:193], v[28:31]
	v_mfma_f32_16x16x32_bf16 v[24:27], v[178:181], v[190:193], v[24:27]
	v_mfma_f32_16x16x32_bf16 v[20:23], v[170:173], v[198:201], v[20:23]
	v_mfma_f32_16x16x32_bf16 v[16:19], v[178:181], v[198:201], v[16:19]
	v_mfma_f32_16x16x32_bf16 v[12:15], v[170:173], v[206:209], v[12:15]
	v_mfma_f32_16x16x32_bf16 v[8:11], v[178:181], v[206:209], v[8:11]
	v_mfma_f32_16x16x32_bf16 v[4:7], v[170:173], v[214:217], v[4:7]
	v_mfma_f32_16x16x32_bf16 v[0:3], v[178:181], v[214:217], v[0:3]
	s_barrier
; #define PG8_STAGE(bufoff, gbase, voff) do { _Pragma("unroll") for (int _i = 0; _i < 2; ++_i) \
;         __builtin_amdgcn_global_load_lds((const unsigned*)((const char*)(gbase) + (voff)[_i]), (PG8_LAS unsigned*)(lds + (bufoff) + ldsw + _i * 8192), 16, 0, 0); } while (0)
; #define PG8_LDA(dst, b, h) do { _Pragma("unroll") for (int m = 0; m < 4; ++m) _Pragma("unroll") for (int k = 0; k < 2; ++k) dst[m][k] = *(const PG8_LAS bf16x8*)(lds + PG8_SA(b, h) + aoff + m * 2048 + k * 1024); } while (0)
; #define PG8_LDB(dst, b, h) do { _Pragma("unroll") for (int n = 0; n < 2; ++n) _Pragma("unroll") for (int k = 0; k < 2; ++k) dst[n][k] = *(const PG8_LAS bf16x8*)(lds + PG8_SB(b, h) + boff + n * 2048 + k * 1024); } while (0)
; #define PG8_MMA(ai, bj, At, Bt) do { __builtin_amdgcn_s_setprio(1); _Pragma("unroll") for (int m = 0; m < 4; ++m) _Pragma("unroll") for (int n = 0; n < 2; ++n) _Pragma("unroll") for (int k = 0; k < 2; ++k) \
;         acc[ai][bj][m][n] = __builtin_amdgcn_mfma_f32_16x16x32_bf16(Bt[n][k], At[m][k], acc[ai][bj][m][n], 0, 0, 0); __builtin_amdgcn_s_setprio(0); } while (0)
; #define PG8_WAIT_V(n) asm volatile("s_waitcnt vmcnt(" #n ")" ::: "memory")
; #define PG8_WAIT_L(n) asm volatile("s_waitcnt lgkmcnt(" #n ")" ::: "memory")
; #define PG8_BAR __builtin_amdgcn_s_barrier()
; #define PG8_SCHED __builtin_amdgcn_sched_barrier(0)
; template <class Epi, class Sched, bool ALIGN_EPI = false, bool SP2 = false>
; __device__ __forceinline__ void gemm_phase(PG8_LAS unsigned char* lds, const Gemm g, const Sched& S, const Epi& E) {
;     ...
;             PG8_LDB(B0, 1, 0); PG8_LDB(B1, 1, 1); PG8_SCHED; PG8_LDA(At, 1, 0); PG8_STAGE(PG8_SA(0, 1), a2 + hstep, voffA);
;             PG8_WAIT_V(8); PG8_WAIT_L(0); PG8_BAR; PG8_MMA(0, 0, At, B0); PG8_MMA(0, 1, At, B1); PG8_BAR; PG8_SCHED;
;             PG8_LDA(At, 1, 1); PG8_STAGE(PG8_SB(1, 0), b3, voffB); PG8_STAGE(PG8_SB(1, 1), b3 + hstep, voffB); PG8_STAGE(PG8_SA(1, 0), a3, voffA);
;             PG8_WAIT_V(8); PG8_WAIT_L(0); PG8_BAR; PG8_MMA(1, 0, At, B0); PG8_MMA(1, 1, At, B1); PG8_BAR; PG8_SCHED;
;     ...
;         if constexpr (ALIGN_EPI) { if (wr == 0) PG8_BAR; }
	s_add_i32 s83, 0, 0x18000
	s_add_i32 s86, 0, 0x1c000
	v_add_u32_e32 v162, s83, v186
	v_add_u32_e32 v178, s86, v186
	ds_read_b128 v[150:153], v162
	ds_read_b128 v[154:157], v162 offset:1024
	ds_read_b128 v[158:161], v162 offset:2048
	ds_read_b128 v[162:165], v162 offset:3072
	ds_read_b128 v[166:169], v178
	ds_read_b128 v[170:173], v178 offset:1024
	ds_read_b128 v[174:177], v178 offset:2048
	ds_read_b128 v[178:181], v178 offset:3072
	s_add_u32 s56, s56, 0x80000
	s_addc_u32 s57, s57, 0
	s_mov_b32 m0, s63
	ds_read_b128 v[182:185], v187 offset:32768
	ds_read_b128 v[190:193], v187 offset:33792
	ds_read_b128 v[194:197], v187 offset:34816
	ds_read_b128 v[198:201], v187 offset:35840
	ds_read_b128 v[202:205], v187 offset:36864
	ds_read_b128 v[206:209], v187 offset:37888
	ds_read_b128 v[210:213], v187 offset:38912
	ds_read_b128 v[214:217], v187 offset:39936
	global_load_lds_dwordx4 v128, s[56:57]
	s_mov_b32 m0, s64
	s_nop 0
	global_load_lds_dwordx4 v132, s[56:57]
	s_waitcnt vmcnt(8)
	s_waitcnt lgkmcnt(0)
	s_barrier
	v_mfma_f32_16x16x32_bf16 v[124:127], v[150:153], v[182:185], v[124:127]
	v_mfma_f32_16x16x32_bf16 v[120:123], v[158:161], v[182:185], v[120:123]
	v_mfma_f32_16x16x32_bf16 v[116:119], v[150:153], v[194:197], v[116:119]
	v_mfma_f32_16x16x32_bf16 v[112:115], v[158:161], v[194:197], v[112:115]
	v_mfma_f32_16x16x32_bf16 v[108:111], v[150:153], v[202:205], v[108:111]
	v_mfma_f32_16x16x32_bf16 v[104:107], v[158:161], v[202:205], v[104:107]
	v_mfma_f32_16x16x32_bf16 v[100:103], v[150:153], v[210:213], v[100:103]
	v_mfma_f32_16x16x32_bf16 v[96:99], v[158:161], v[210:213], v[96:99]
	v_mfma_f32_16x16x32_bf16 v[124:127], v[154:157], v[190:193], v[124:127]
	v_mfma_f32_16x16x32_bf16 v[120:123], v[162:165], v[190:193], v[120:123]
	v_mfma_f32_16x16x32_bf16 v[116:119], v[154:157], v[198:201], v[116:119]
	v_mfma_f32_16x16x32_bf16 v[112:115], v[162:165], v[198:201], v[112:115]
	v_mfma_f32_16x16x32_bf16 v[108:111], v[154:157], v[206:209], v[108:111]
	v_mfma_f32_16x16x32_bf16 v[104:107], v[162:165], v[206:209], v[104:107]
	v_mfma_f32_16x16x32_bf16 v[100:103], v[154:157], v[214:217], v[100:103]
	v_mfma_f32_16x16x32_bf16 v[96:99], v[162:165], v[214:217], v[96:99]
	v_mfma_f32_16x16x32_bf16 v[92:95], v[166:169], v[182:185], v[92:95]
	v_mfma_f32_16x16x32_bf16 v[88:91], v[174:177], v[182:185], v[88:91]
	v_mfma_f32_16x16x32_bf16 v[84:87], v[166:169], v[194:197], v[84:87]
	v_mfma_f32_16x16x32_bf16 v[80:83], v[174:177], v[194:197], v[80:83]
	v_mfma_f32_16x16x32_bf16 v[76:79], v[166:169], v[202:205], v[76:79]
	v_mfma_f32_16x16x32_bf16 v[72:75], v[174:177], v[202:205], v[72:75]
	v_mfma_f32_16x16x32_bf16 v[68:71], v[166:169], v[210:213], v[68:71]
	v_mfma_f32_16x16x32_bf16 v[64:67], v[174:177], v[210:213], v[64:67]
	v_mfma_f32_16x16x32_bf16 v[92:95], v[170:173], v[190:193], v[92:95]
	v_mfma_f32_16x16x32_bf16 v[88:91], v[178:181], v[190:193], v[88:91]
	v_mfma_f32_16x16x32_bf16 v[84:87], v[170:173], v[198:201], v[84:87]
	v_mfma_f32_16x16x32_bf16 v[80:83], v[178:181], v[198:201], v[80:83]
	v_mfma_f32_16x16x32_bf16 v[76:79], v[170:173], v[206:209], v[76:79]
	v_mfma_f32_16x16x32_bf16 v[72:75], v[178:181], v[206:209], v[72:75]
	v_mfma_f32_16x16x32_bf16 v[68:71], v[170:173], v[214:217], v[68:71]
	v_mfma_f32_16x16x32_bf16 v[64:67], v[178:181], v[214:217], v[64:67]
	s_barrier
	s_add_i32 s56, s83, s60
	v_lshl_add_u64 v[218:219], v[218:219], 0, s[14:15]
	s_mov_b32 m0, s56
	ds_read_b128 v[182:185], v187 offset:49152
	ds_read_b128 v[190:193], v187 offset:50176
	ds_read_b128 v[194:197], v187 offset:51200
	ds_read_b128 v[198:201], v187 offset:52224
	ds_read_b128 v[202:205], v187 offset:53248
	ds_read_b128 v[206:209], v187 offset:54272
	ds_read_b128 v[210:213], v187 offset:55296
	ds_read_b128 v[214:217], v187 offset:56320
	global_load_lds_dwordx4 v[218:219], off
	s_add_i32 m0, s56, 0x2000
	s_add_u32 s54, s54, 0x80080
	v_lshl_add_u64 v[218:219], v[220:221], 0, s[14:15]
	s_addc_u32 s55, s55, 0
	s_add_i32 s56, s86, s60
	global_load_lds_dwordx4 v[218:219], off
	s_mov_b32 m0, s56
	s_nop 0
	global_load_lds_dwordx4 v130, s[54:55]
	s_add_i32 m0, s56, 0x2000
	s_nop 0
	global_load_lds_dwordx4 v134, s[54:55]
	v_lshl_add_u64 v[218:219], v[222:223], 0, s[14:15]
	s_mov_b32 m0, s65
	s_nop 0
	global_load_lds_dwordx4 v[218:219], off
	v_lshl_add_u64 v[218:219], v[224:225], 0, s[14:15]
	s_mov_b32 m0, s66
	s_nop 0
	global_load_lds_dwordx4 v[218:219], off
	s_waitcnt vmcnt(8)
	s_waitcnt lgkmcnt(0)
	s_barrier
	v_mfma_f32_16x16x32_bf16 v[60:63], v[150:153], v[182:185], v[60:63]
	v_mfma_f32_16x16x32_bf16 v[56:59], v[158:161], v[182:185], v[56:59]
	v_mfma_f32_16x16x32_bf16 v[52:55], v[150:153], v[194:197], v[52:55]
	v_mfma_f32_16x16x32_bf16 v[48:51], v[158:161], v[194:197], v[48:51]
	v_mfma_f32_16x16x32_bf16 v[44:47], v[150:153], v[202:205], v[44:47]
	v_mfma_f32_16x16x32_bf16 v[40:43], v[158:161], v[202:205], v[40:43]
	v_mfma_f32_16x16x32_bf16 v[36:39], v[150:153], v[210:213], v[36:39]
	v_mfma_f32_16x16x32_bf16 v[32:35], v[158:161], v[210:213], v[32:35]
	v_mfma_f32_16x16x32_bf16 v[60:63], v[154:157], v[190:193], v[60:63]
	v_mfma_f32_16x16x32_bf16 v[56:59], v[162:165], v[190:193], v[56:59]
	v_mfma_f32_16x16x32_bf16 v[52:55], v[154:157], v[198:201], v[52:55]
	v_mfma_f32_16x16x32_bf16 v[48:51], v[162:165], v[198:201], v[48:51]
	v_mfma_f32_16x16x32_bf16 v[44:47], v[154:157], v[206:209], v[44:47]
	v_mfma_f32_16x16x32_bf16 v[40:43], v[162:165], v[206:209], v[40:43]
	v_mfma_f32_16x16x32_bf16 v[36:39], v[154:157], v[214:217], v[36:39]
	v_mfma_f32_16x16x32_bf16 v[32:35], v[162:165], v[214:217], v[32:35]
	v_mfma_f32_16x16x32_bf16 v[28:31], v[166:169], v[182:185], v[28:31]
	v_mfma_f32_16x16x32_bf16 v[24:27], v[174:177], v[182:185], v[24:27]
	v_mfma_f32_16x16x32_bf16 v[20:23], v[166:169], v[194:197], v[20:23]
	v_mfma_f32_16x16x32_bf16 v[16:19], v[174:177], v[194:197], v[16:19]
	v_mfma_f32_16x16x32_bf16 v[12:15], v[166:169], v[202:205], v[12:15]
	v_mfma_f32_16x16x32_bf16 v[8:11], v[174:177], v[202:205], v[8:11]
	v_mfma_f32_16x16x32_bf16 v[4:7], v[166:169], v[210:213], v[4:7]
	v_mfma_f32_16x16x32_bf16 v[0:3], v[174:177], v[210:213], v[0:3]
	v_mfma_f32_16x16x32_bf16 v[28:31], v[170:173], v[190:193], v[28:31]
	v_mfma_f32_16x16x32_bf16 v[24:27], v[178:181], v[190:193], v[24:27]
	v_mfma_f32_16x16x32_bf16 v[20:23], v[170:173], v[198:201], v[20:23]
	v_mfma_f32_16x16x32_bf16 v[16:19], v[178:181], v[198:201], v[16:19]
	v_mfma_f32_16x16x32_bf16 v[12:15], v[170:173], v[206:209], v[12:15]
	v_mfma_f32_16x16x32_bf16 v[8:11], v[178:181], v[206:209], v[8:11]
	v_mfma_f32_16x16x32_bf16 v[4:7], v[170:173], v[214:217], v[4:7]
	v_mfma_f32_16x16x32_bf16 v[0:3], v[178:181], v[214:217], v[0:3]
	s_barrier
	s_add_i32 s82, s82, 2
	s_add_u32 s46, s46, 0x100
	s_addc_u32 s47, s47, 0
	s_add_u32 s80, s80, 0x100
	s_addc_u32 s81, s81, 0
	s_cmp_gt_u32 s82, 13
	s_cbranch_scc0 .LBB0_795
	s_and_b64 vcc, exec, s[16:17]
	s_cbranch_vccz .LBB0_798
	s_barrier

; #define PG8_STAGE(bufoff, gbase, voff) do { _Pragma("unroll") for (int _i = 0; _i < 2; ++_i) \
;         __builtin_amdgcn_global_load_lds((const unsigned*)((const char*)(gbase) + (voff)[_i]), (PG8_LAS unsigned*)(lds + (bufoff) + ldsw + _i * 8192), 16, 0, 0); } while (0)
; #define PG8_LDA(dst, b, h) do { _Pragma("unroll") for (int m = 0; m < 4; ++m) _Pragma("unroll") for (int k = 0; k < 2; ++k) dst[m][k] = *(const PG8_LAS bf16x8*)(lds + PG8_SA(b, h) + aoff + m * 2048 + k * 1024); } while (0)
; #define PG8_LDB(dst, b, h) do { _Pragma("unroll") for (int n = 0; n < 2; ++n) _Pragma("unroll") for (int k = 0; k < 2; ++k) dst[n][k] = *(const PG8_LAS bf16x8*)(lds + PG8_SB(b, h) + boff + n * 2048 + k * 1024); } while (0)
; #define PG8_MMA(ai, bj, At, Bt) do { __builtin_amdgcn_s_setprio(1); _Pragma("unroll") for (int m = 0; m < 4; ++m) _Pragma("unroll") for (int n = 0; n < 2; ++n) _Pragma("unroll") for (int k = 0; k < 2; ++k) \
;         acc[ai][bj][m][n] = __builtin_amdgcn_mfma_f32_16x16x32_bf16(Bt[n][k], At[m][k], acc[ai][bj][m][n], 0, 0, 0); __builtin_amdgcn_s_setprio(0); } while (0)
; #define PG8_WAIT_V(n) asm volatile("s_waitcnt vmcnt(" #n ")" ::: "memory")
; #define PG8_BAR __builtin_amdgcn_s_barrier()
; template <class Epi, class Sched, bool ALIGN_EPI = false, bool SP2 = false>
; __device__ __forceinline__ void gemm_phase(PG8_LAS unsigned char* lds, const Gemm g, const Sched& S, const Epi& E) {
;     ...
;         for (int t = 0; t < nt; t += 2) {
;             const bool last = (t == nt - 2);
;             const char* a1 = cA + (size_t)(t + 1) * kstep;
;             const char* a2 = last ? nA : cA + (size_t)(t + 2) * kstep; const char* b2 = last ? nB : cB + (size_t)(t + 2) * kstep;
;             const char* a3 = a2 + kstep; const char* b3 = b2 + kstep;
;             if (last && has_next) S.a_ready(nxt);
;             if constexpr (SP2) {
;             PG8_LDB(B0, 0, 0); PG8_LDB(B1, 0, 1); PG8_SCHED; PG8_LDA(At, 0, 0); PG8_STAGE(PG8_SA(1, 1), a1 + hstep, voffA);
;             PG8_WAIT_V(8); PG8_WAIT_L(0); PG8_BAR; PG8_MMA(0, 0, At, B0); PG8_MMA(0, 1, At, B1); PG8_BAR; PG8_SCHED;
;             PG8_LDA(At, 0, 1); PG8_STAGE(PG8_SB(0, 0), b2, voffB); PG8_STAGE(PG8_SB(0, 1), b2 + hstep, voffB); PG8_STAGE(PG8_SA(0, 0), a2, voffA);
;             PG8_WAIT_V(8); PG8_WAIT_L(0); PG8_BAR; PG8_MMA(1, 0, At, B0); PG8_MMA(1, 1, At, B1); PG8_BAR; PG8_SCHED;
.LBB0_882:
	ds_read_b128 v[128:131], v173
	ds_read_b128 v[132:135], v173 offset:1024
	ds_read_b128 v[136:139], v173 offset:2048
	ds_read_b128 v[140:143], v173 offset:3072
	ds_read_b128 v[164:167], v174
	ds_read_b128 v[168:171], v174 offset:1024
	ds_read_b128 v[178:181], v174 offset:2048
	ds_read_b128 v[182:185], v174 offset:3072
	s_add_u32 s34, s30, 0xfffc0080
	s_addc_u32 s35, s31, -1
	s_cmp_eq_u32 s61, 12
	s_cselect_b32 s37, s23, s35
	s_cselect_b32 s36, s29, s34
	s_cselect_b32 s35, s21, s60
	s_cselect_b32 s34, s58, s59
	s_add_i32 m0, s43, 0xc000
	ds_read_b128 v[190:193], v175
	ds_read_b128 v[194:197], v175 offset:1024
	ds_read_b128 v[198:201], v175 offset:2048
	ds_read_b128 v[202:205], v175 offset:3072
	ds_read_b128 v[206:209], v175 offset:4096
	ds_read_b128 v[210:213], v175 offset:5120
	ds_read_b128 v[214:217], v175 offset:6144
	ds_read_b128 v[218:221], v175 offset:7168
	global_load_lds_dwordx4 v156, s[30:31]
	s_add_i32 m0, s43, 0xe000
	s_nop 0
	global_load_lds_dwordx4 v158, s[30:31]
	s_waitcnt vmcnt(8)
	s_waitcnt lgkmcnt(0)
	s_barrier
	v_mfma_f32_16x16x32_bf16 v[124:127], v[128:131], v[190:193], v[124:127]
	v_mfma_f32_16x16x32_bf16 v[120:123], v[136:139], v[190:193], v[120:123]
	v_mfma_f32_16x16x32_bf16 v[108:111], v[128:131], v[198:201], v[108:111]
	v_mfma_f32_16x16x32_bf16 v[104:107], v[136:139], v[198:201], v[104:107]
	v_mfma_f32_16x16x32_bf16 v[92:95], v[128:131], v[206:209], v[92:95]
	v_mfma_f32_16x16x32_bf16 v[88:91], v[136:139], v[206:209], v[88:91]
	v_mfma_f32_16x16x32_bf16 v[76:79], v[128:131], v[214:217], v[76:79]
	v_mfma_f32_16x16x32_bf16 v[72:75], v[136:139], v[214:217], v[72:75]
	v_mfma_f32_16x16x32_bf16 v[124:127], v[132:135], v[194:197], v[124:127]
	v_mfma_f32_16x16x32_bf16 v[120:123], v[140:143], v[194:197], v[120:123]
	v_mfma_f32_16x16x32_bf16 v[108:111], v[132:135], v[202:205], v[108:111]
	v_mfma_f32_16x16x32_bf16 v[104:107], v[140:143], v[202:205], v[104:107]
	v_mfma_f32_16x16x32_bf16 v[92:95], v[132:135], v[210:213], v[92:95]
	v_mfma_f32_16x16x32_bf16 v[88:91], v[140:143], v[210:213], v[88:91]
	v_mfma_f32_16x16x32_bf16 v[76:79], v[132:135], v[218:221], v[76:79]
	v_mfma_f32_16x16x32_bf16 v[72:75], v[140:143], v[218:221], v[72:75]
	v_mfma_f32_16x16x32_bf16 v[116:119], v[164:167], v[190:193], v[116:119]
	v_mfma_f32_16x16x32_bf16 v[112:115], v[178:181], v[190:193], v[112:115]
	v_mfma_f32_16x16x32_bf16 v[100:103], v[164:167], v[198:201], v[100:103]
	v_mfma_f32_16x16x32_bf16 v[96:99], v[178:181], v[198:201], v[96:99]
	v_mfma_f32_16x16x32_bf16 v[84:87], v[164:167], v[206:209], v[84:87]
	v_mfma_f32_16x16x32_bf16 v[80:83], v[178:181], v[206:209], v[80:83]
	v_mfma_f32_16x16x32_bf16 v[68:71], v[164:167], v[214:217], v[68:71]
	v_mfma_f32_16x16x32_bf16 v[64:67], v[178:181], v[214:217], v[64:67]
	v_mfma_f32_16x16x32_bf16 v[116:119], v[168:171], v[194:197], v[116:119]
	v_mfma_f32_16x16x32_bf16 v[112:115], v[182:185], v[194:197], v[112:115]
	v_mfma_f32_16x16x32_bf16 v[100:103], v[168:171], v[202:205], v[100:103]
	v_mfma_f32_16x16x32_bf16 v[96:99], v[182:185], v[202:205], v[96:99]
	v_mfma_f32_16x16x32_bf16 v[84:87], v[168:171], v[210:213], v[84:87]
	v_mfma_f32_16x16x32_bf16 v[80:83], v[182:185], v[210:213], v[80:83]
	v_mfma_f32_16x16x32_bf16 v[68:71], v[168:171], v[218:221], v[68:71]
	v_mfma_f32_16x16x32_bf16 v[64:67], v[182:185], v[218:221], v[64:67]
	s_barrier
	s_add_i32 s62, s55, s42
	v_lshl_add_u64 v[186:187], s[34:35], 0, v[146:147]
	s_mov_b32 m0, s62
	ds_read_b128 v[190:193], v175 offset:16384
	ds_read_b128 v[194:197], v175 offset:17408
	ds_read_b128 v[198:201], v175 offset:18432
	ds_read_b128 v[202:205], v175 offset:19456
	ds_read_b128 v[206:209], v175 offset:20480
	ds_read_b128 v[210:213], v175 offset:21504
	ds_read_b128 v[214:217], v175 offset:22528
	ds_read_b128 v[218:221], v175 offset:23552
	global_load_lds_dwordx4 v[186:187], off
	s_add_i32 m0, s62, 0x2000
	s_add_u32 s62, s34, 0x40000
	v_lshl_add_u64 v[222:223], s[34:35], 0, v[150:151]
	s_addc_u32 s63, s35, 0
	s_add_i32 s64, s56, s42
	global_load_lds_dwordx4 v[222:223], off
	s_mov_b32 m0, s64
	v_lshl_add_u64 v[226:227], s[36:37], 0, v[148:149]
	global_load_lds_dwordx4 v146, s[62:63]
	s_add_i32 m0, s64, 0x2000
	s_nop 0
	global_load_lds_dwordx4 v150, s[62:63]
	v_lshl_add_u64 v[224:225], s[36:37], 0, v[144:145]
	s_mov_b32 m0, s43
	s_nop 0
	global_load_lds_dwordx4 v[224:225], off
	s_mov_b32 m0, s44
	s_nop 0
	global_load_lds_dwordx4 v[226:227], off
	s_waitcnt vmcnt(8)
	s_waitcnt lgkmcnt(0)
	s_barrier
	v_mfma_f32_16x16x32_bf16 v[60:63], v[128:131], v[190:193], v[60:63]
	v_mfma_f32_16x16x32_bf16 v[56:59], v[136:139], v[190:193], v[56:59]
	v_mfma_f32_16x16x32_bf16 v[44:47], v[128:131], v[198:201], v[44:47]
	v_mfma_f32_16x16x32_bf16 v[40:43], v[136:139], v[198:201], v[40:43]
	v_mfma_f32_16x16x32_bf16 v[28:31], v[128:131], v[206:209], v[28:31]
	v_mfma_f32_16x16x32_bf16 v[24:27], v[136:139], v[206:209], v[24:27]
	v_mfma_f32_16x16x32_bf16 v[12:15], v[128:131], v[214:217], v[12:15]
	v_mfma_f32_16x16x32_bf16 v[8:11], v[136:139], v[214:217], v[8:11]
	v_mfma_f32_16x16x32_bf16 v[60:63], v[132:135], v[194:197], v[60:63]
	v_mfma_f32_16x16x32_bf16 v[56:59], v[140:143], v[194:197], v[56:59]
	v_mfma_f32_16x16x32_bf16 v[44:47], v[132:135], v[202:205], v[44:47]
	v_mfma_f32_16x16x32_bf16 v[40:43], v[140:143], v[202:205], v[40:43]
	v_mfma_f32_16x16x32_bf16 v[28:31], v[132:135], v[210:213], v[28:31]
	v_mfma_f32_16x16x32_bf16 v[24:27], v[140:143], v[210:213], v[24:27]
	v_mfma_f32_16x16x32_bf16 v[12:15], v[132:135], v[218:221], v[12:15]
	v_mfma_f32_16x16x32_bf16 v[8:11], v[140:143], v[218:221], v[8:11]
	v_mfma_f32_16x16x32_bf16 v[52:55], v[164:167], v[190:193], v[52:55]
	v_mfma_f32_16x16x32_bf16 v[48:51], v[178:181], v[190:193], v[48:51]
	v_mfma_f32_16x16x32_bf16 v[36:39], v[164:167], v[198:201], v[36:39]
	v_mfma_f32_16x16x32_bf16 v[32:35], v[178:181], v[198:201], v[32:35]
	v_mfma_f32_16x16x32_bf16 v[20:23], v[164:167], v[206:209], v[20:23]
	v_mfma_f32_16x16x32_bf16 v[16:19], v[178:181], v[206:209], v[16:19]
	v_mfma_f32_16x16x32_bf16 v[4:7], v[164:167], v[214:217], v[4:7]
	v_mfma_f32_16x16x32_bf16 v[0:3], v[178:181], v[214:217], v[0:3]
	v_mfma_f32_16x16x32_bf16 v[52:55], v[168:171], v[194:197], v[52:55]
	v_mfma_f32_16x16x32_bf16 v[48:51], v[182:185], v[194:197], v[48:51]
	v_mfma_f32_16x16x32_bf16 v[36:39], v[168:171], v[202:205], v[36:39]
	v_mfma_f32_16x16x32_bf16 v[32:35], v[182:185], v[202:205], v[32:35]
	v_mfma_f32_16x16x32_bf16 v[20:23], v[168:171], v[210:213], v[20:23]
	v_mfma_f32_16x16x32_bf16 v[16:19], v[182:185], v[210:213], v[16:19]
	v_mfma_f32_16x16x32_bf16 v[4:7], v[168:171], v[218:221], v[4:7]
	v_mfma_f32_16x16x32_bf16 v[0:3], v[182:185], v[218:221], v[0:3]
	s_barrier
; #define PG8_STAGE(bufoff, gbase, voff) do { _Pragma("unroll") for (int _i = 0; _i < 2; ++_i) \
;         __builtin_amdgcn_global_load_lds((const unsigned*)((const char*)(gbase) + (voff)[_i]), (PG8_LAS unsigned*)(lds + (bufoff) + ldsw + _i * 8192), 16, 0, 0); } while (0)
; #define PG8_LDA(dst, b, h) do { _Pragma("unroll") for (int m = 0; m < 4; ++m) _Pragma("unroll") for (int k = 0; k < 2; ++k) dst[m][k] = *(const PG8_LAS bf16x8*)(lds + PG8_SA(b, h) + aoff + m * 2048 + k * 1024); } while (0)
; #define PG8_LDB(dst, b, h) do { _Pragma("unroll") for (int n = 0; n < 2; ++n) _Pragma("unroll") for (int k = 0; k < 2; ++k) dst[n][k] = *(const PG8_LAS bf16x8*)(lds + PG8_SB(b, h) + boff + n * 2048 + k * 1024); } while (0)
; #define PG8_MMA(ai, bj, At, Bt) do { __builtin_amdgcn_s_setprio(1); _Pragma("unroll") for (int m = 0; m < 4; ++m) _Pragma("unroll") for (int n = 0; n < 2; ++n) _Pragma("unroll") for (int k = 0; k < 2; ++k) \
;         acc[ai][bj][m][n] = __builtin_amdgcn_mfma_f32_16x16x32_bf16(Bt[n][k], At[m][k], acc[ai][bj][m][n], 0, 0, 0); __builtin_amdgcn_s_setprio(0); } while (0)
; #define PG8_WAIT_V(n) asm volatile("s_waitcnt vmcnt(" #n ")" ::: "memory")
; #define PG8_WAIT_L(n) asm volatile("s_waitcnt lgkmcnt(" #n ")" ::: "memory")
; #define PG8_BAR __builtin_amdgcn_s_barrier()
; #define PG8_SCHED __builtin_amdgcn_sched_barrier(0)
; template <class Epi, class Sched, bool ALIGN_EPI = false, bool SP2 = false>
; __device__ __forceinline__ void gemm_phase(PG8_LAS unsigned char* lds, const Gemm g, const Sched& S, const Epi& E) {
;     ...
;             PG8_LDB(B0, 1, 0); PG8_LDB(B1, 1, 1); PG8_SCHED; PG8_LDA(At, 1, 0); PG8_STAGE(PG8_SA(0, 1), a2 + hstep, voffA);
;             PG8_WAIT_V(8); PG8_WAIT_L(0); PG8_BAR; PG8_MMA(0, 0, At, B0); PG8_MMA(0, 1, At, B1); PG8_BAR; PG8_SCHED;
;             PG8_LDA(At, 1, 1); PG8_STAGE(PG8_SB(1, 0), b3, voffB); PG8_STAGE(PG8_SB(1, 1), b3 + hstep, voffB); PG8_STAGE(PG8_SA(1, 0), a3, voffA);
;             PG8_WAIT_V(8); PG8_WAIT_L(0); PG8_BAR; PG8_MMA(1, 0, At, B0); PG8_MMA(1, 1, At, B1); PG8_BAR; PG8_SCHED;
;     ...
;         if constexpr (ALIGN_EPI) { if (wr == 0) PG8_BAR; }
	s_add_i32 s62, 0, 0x18000
	s_add_i32 s63, 0, 0x1c000
	v_add_u32_e32 v140, s62, v172
	v_add_u32_e32 v177, s63, v172
	ds_read_b128 v[128:131], v140
	ds_read_b128 v[132:135], v140 offset:1024
	ds_read_b128 v[136:139], v140 offset:2048
	ds_read_b128 v[140:143], v140 offset:3072
	ds_read_b128 v[164:167], v177
	ds_read_b128 v[168:171], v177 offset:1024
	ds_read_b128 v[178:181], v177 offset:2048
	ds_read_b128 v[182:185], v177 offset:3072
	s_add_u32 s36, s36, 0x40000
	s_addc_u32 s37, s37, 0
	s_mov_b32 m0, s45
	ds_read_b128 v[190:193], v175 offset:32768
	ds_read_b128 v[194:197], v175 offset:33792
	ds_read_b128 v[198:201], v175 offset:34816
	ds_read_b128 v[202:205], v175 offset:35840
	ds_read_b128 v[206:209], v175 offset:36864
	ds_read_b128 v[210:213], v175 offset:37888
	ds_read_b128 v[214:217], v175 offset:38912
	ds_read_b128 v[218:221], v175 offset:39936
	global_load_lds_dwordx4 v144, s[36:37]
	s_mov_b32 m0, s46
	s_nop 0
	global_load_lds_dwordx4 v148, s[36:37]
	s_waitcnt vmcnt(8)
	s_waitcnt lgkmcnt(0)
	s_barrier
	v_mfma_f32_16x16x32_bf16 v[124:127], v[128:131], v[190:193], v[124:127]
	v_mfma_f32_16x16x32_bf16 v[120:123], v[136:139], v[190:193], v[120:123]
	v_mfma_f32_16x16x32_bf16 v[108:111], v[128:131], v[198:201], v[108:111]
	v_mfma_f32_16x16x32_bf16 v[104:107], v[136:139], v[198:201], v[104:107]
	v_mfma_f32_16x16x32_bf16 v[92:95], v[128:131], v[206:209], v[92:95]
	v_mfma_f32_16x16x32_bf16 v[88:91], v[136:139], v[206:209], v[88:91]
	v_mfma_f32_16x16x32_bf16 v[76:79], v[128:131], v[214:217], v[76:79]
	v_mfma_f32_16x16x32_bf16 v[72:75], v[136:139], v[214:217], v[72:75]
	v_mfma_f32_16x16x32_bf16 v[124:127], v[132:135], v[194:197], v[124:127]
	v_mfma_f32_16x16x32_bf16 v[120:123], v[140:143], v[194:197], v[120:123]
	v_mfma_f32_16x16x32_bf16 v[108:111], v[132:135], v[202:205], v[108:111]
	v_mfma_f32_16x16x32_bf16 v[104:107], v[140:143], v[202:205], v[104:107]
	v_mfma_f32_16x16x32_bf16 v[92:95], v[132:135], v[210:213], v[92:95]
	v_mfma_f32_16x16x32_bf16 v[88:91], v[140:143], v[210:213], v[88:91]
	v_mfma_f32_16x16x32_bf16 v[76:79], v[132:135], v[218:221], v[76:79]
	v_mfma_f32_16x16x32_bf16 v[72:75], v[140:143], v[218:221], v[72:75]
	v_mfma_f32_16x16x32_bf16 v[116:119], v[164:167], v[190:193], v[116:119]
	v_mfma_f32_16x16x32_bf16 v[112:115], v[178:181], v[190:193], v[112:115]
	v_mfma_f32_16x16x32_bf16 v[100:103], v[164:167], v[198:201], v[100:103]
	v_mfma_f32_16x16x32_bf16 v[96:99], v[178:181], v[198:201], v[96:99]
	v_mfma_f32_16x16x32_bf16 v[84:87], v[164:167], v[206:209], v[84:87]
	v_mfma_f32_16x16x32_bf16 v[80:83], v[178:181], v[206:209], v[80:83]
	v_mfma_f32_16x16x32_bf16 v[68:71], v[164:167], v[214:217], v[68:71]
	v_mfma_f32_16x16x32_bf16 v[64:67], v[178:181], v[214:217], v[64:67]
	v_mfma_f32_16x16x32_bf16 v[116:119], v[168:171], v[194:197], v[116:119]
	v_mfma_f32_16x16x32_bf16 v[112:115], v[182:185], v[194:197], v[112:115]
	v_mfma_f32_16x16x32_bf16 v[100:103], v[168:171], v[202:205], v[100:103]
	v_mfma_f32_16x16x32_bf16 v[96:99], v[182:185], v[202:205], v[96:99]
	v_mfma_f32_16x16x32_bf16 v[84:87], v[168:171], v[210:213], v[84:87]
	v_mfma_f32_16x16x32_bf16 v[80:83], v[182:185], v[210:213], v[80:83]
	v_mfma_f32_16x16x32_bf16 v[68:71], v[168:171], v[218:221], v[68:71]
	v_mfma_f32_16x16x32_bf16 v[64:67], v[182:185], v[218:221], v[64:67]
	s_barrier
	s_add_i32 s36, s62, s42
	v_lshl_add_u64 v[186:187], v[186:187], 0, s[16:17]
	s_mov_b32 m0, s36
	ds_read_b128 v[190:193], v175 offset:49152
	ds_read_b128 v[194:197], v175 offset:50176
	ds_read_b128 v[198:201], v175 offset:51200
	ds_read_b128 v[202:205], v175 offset:52224
	ds_read_b128 v[206:209], v175 offset:53248
	ds_read_b128 v[210:213], v175 offset:54272
	ds_read_b128 v[214:217], v175 offset:55296
	ds_read_b128 v[218:221], v175 offset:56320
	global_load_lds_dwordx4 v[186:187], off
	s_add_i32 m0, s36, 0x2000
	s_add_u32 s34, s34, 0x40080
	v_lshl_add_u64 v[186:187], v[222:223], 0, s[16:17]
	s_addc_u32 s35, s35, 0
	s_add_i32 s36, s63, s42
	global_load_lds_dwordx4 v[186:187], off
	s_mov_b32 m0, s36
	s_nop 0
	global_load_lds_dwordx4 v146, s[34:35]
	s_add_i32 m0, s36, 0x2000
	s_nop 0
	global_load_lds_dwordx4 v150, s[34:35]
	v_lshl_add_u64 v[186:187], v[224:225], 0, s[16:17]
	s_mov_b32 m0, s48
	s_nop 0
	global_load_lds_dwordx4 v[186:187], off
	v_lshl_add_u64 v[186:187], v[226:227], 0, s[16:17]
	s_mov_b32 m0, s49
	s_nop 0
	global_load_lds_dwordx4 v[186:187], off
	s_waitcnt vmcnt(8)
	s_waitcnt lgkmcnt(0)
	s_barrier
	v_mfma_f32_16x16x32_bf16 v[60:63], v[128:131], v[190:193], v[60:63]
	v_mfma_f32_16x16x32_bf16 v[56:59], v[136:139], v[190:193], v[56:59]
	v_mfma_f32_16x16x32_bf16 v[44:47], v[128:131], v[198:201], v[44:47]
	v_mfma_f32_16x16x32_bf16 v[40:43], v[136:139], v[198:201], v[40:43]
	v_mfma_f32_16x16x32_bf16 v[28:31], v[128:131], v[206:209], v[28:31]
	v_mfma_f32_16x16x32_bf16 v[24:27], v[136:139], v[206:209], v[24:27]
	v_mfma_f32_16x16x32_bf16 v[12:15], v[128:131], v[214:217], v[12:15]
	v_mfma_f32_16x16x32_bf16 v[8:11], v[136:139], v[214:217], v[8:11]
	v_mfma_f32_16x16x32_bf16 v[60:63], v[132:135], v[194:197], v[60:63]
	v_mfma_f32_16x16x32_bf16 v[56:59], v[140:143], v[194:197], v[56:59]
	v_mfma_f32_16x16x32_bf16 v[44:47], v[132:135], v[202:205], v[44:47]
	v_mfma_f32_16x16x32_bf16 v[40:43], v[140:143], v[202:205], v[40:43]
	v_mfma_f32_16x16x32_bf16 v[28:31], v[132:135], v[210:213], v[28:31]
	v_mfma_f32_16x16x32_bf16 v[24:27], v[140:143], v[210:213], v[24:27]
	v_mfma_f32_16x16x32_bf16 v[12:15], v[132:135], v[218:221], v[12:15]
	v_mfma_f32_16x16x32_bf16 v[8:11], v[140:143], v[218:221], v[8:11]
	v_mfma_f32_16x16x32_bf16 v[52:55], v[164:167], v[190:193], v[52:55]
	v_mfma_f32_16x16x32_bf16 v[48:51], v[178:181], v[190:193], v[48:51]
	v_mfma_f32_16x16x32_bf16 v[36:39], v[164:167], v[198:201], v[36:39]
	v_mfma_f32_16x16x32_bf16 v[32:35], v[178:181], v[198:201], v[32:35]
	v_mfma_f32_16x16x32_bf16 v[20:23], v[164:167], v[206:209], v[20:23]
	v_mfma_f32_16x16x32_bf16 v[16:19], v[178:181], v[206:209], v[16:19]
	v_mfma_f32_16x16x32_bf16 v[4:7], v[164:167], v[214:217], v[4:7]
	v_mfma_f32_16x16x32_bf16 v[0:3], v[178:181], v[214:217], v[0:3]
	v_mfma_f32_16x16x32_bf16 v[52:55], v[168:171], v[194:197], v[52:55]
	v_mfma_f32_16x16x32_bf16 v[48:51], v[182:185], v[194:197], v[48:51]
	v_mfma_f32_16x16x32_bf16 v[36:39], v[168:171], v[202:205], v[36:39]
	v_mfma_f32_16x16x32_bf16 v[32:35], v[182:185], v[202:205], v[32:35]
	v_mfma_f32_16x16x32_bf16 v[20:23], v[168:171], v[210:213], v[20:23]
	v_mfma_f32_16x16x32_bf16 v[16:19], v[182:185], v[210:213], v[16:19]
	v_mfma_f32_16x16x32_bf16 v[4:7], v[168:171], v[218:221], v[4:7]
	v_mfma_f32_16x16x32_bf16 v[0:3], v[182:185], v[218:221], v[0:3]
	s_barrier
	s_add_i32 s61, s61, 2
	s_add_u32 s30, s30, 0x100
	s_addc_u32 s31, s31, 0
	s_add_u32 s59, s59, 0x100
	s_addc_u32 s60, s60, 0
	s_cmp_gt_u32 s61, 13
	s_cbranch_scc0 .LBB0_882
	s_and_b64 vcc, exec, s[18:19]
	s_cbranch_vccz .LBB0_885
	s_barrier

; #define PG8_STAGE(bufoff, gbase, voff) do { _Pragma("unroll") for (int _i = 0; _i < 2; ++_i) \
;         __builtin_amdgcn_global_load_lds((const unsigned*)((const char*)(gbase) + (voff)[_i]), (PG8_LAS unsigned*)(lds + (bufoff) + ldsw + _i * 8192), 16, 0, 0); } while (0)
; #define PG8_LDA(dst, b, h) do { _Pragma("unroll") for (int m = 0; m < 4; ++m) _Pragma("unroll") for (int k = 0; k < 2; ++k) dst[m][k] = *(const PG8_LAS bf16x8*)(lds + PG8_SA(b, h) + aoff + m * 2048 + k * 1024); } while (0)
; #define PG8_LDB(dst, b, h) do { _Pragma("unroll") for (int n = 0; n < 2; ++n) _Pragma("unroll") for (int k = 0; k < 2; ++k) dst[n][k] = *(const PG8_LAS bf16x8*)(lds + PG8_SB(b, h) + boff + n * 2048 + k * 1024); } while (0)
; #define PG8_MMA(ai, bj, At, Bt) do { __builtin_amdgcn_s_setprio(1); _Pragma("unroll") for (int m = 0; m < 4; ++m) _Pragma("unroll") for (int n = 0; n < 2; ++n) _Pragma("unroll") for (int k = 0; k < 2; ++k) \
;         acc[ai][bj][m][n] = __builtin_amdgcn_mfma_f32_16x16x32_bf16(Bt[n][k], At[m][k], acc[ai][bj][m][n], 0, 0, 0); __builtin_amdgcn_s_setprio(0); } while (0)
; #define PG8_WAIT_V(n) asm volatile("s_waitcnt vmcnt(" #n ")" ::: "memory")
; #define PG8_BAR __builtin_amdgcn_s_barrier()
; template <class Epi, class Sched, bool ALIGN_EPI = false, bool SP2 = false>
; __device__ __forceinline__ void gemm_phase(PG8_LAS unsigned char* lds, const Gemm g, const Sched& S, const Epi& E) {
;     ...
;         for (int t = 0; t < nt; t += 2) {
;             const bool last = (t == nt - 2);
;             const char* a1 = cA + (size_t)(t + 1) * kstep;
;             const char* a2 = last ? nA : cA + (size_t)(t + 2) * kstep; const char* b2 = last ? nB : cB + (size_t)(t + 2) * kstep;
;             const char* a3 = a2 + kstep; const char* b3 = b2 + kstep;
;             if (last && has_next) S.a_ready(nxt);
;             if constexpr (SP2) {
;             PG8_LDB(B0, 0, 0); PG8_LDB(B1, 0, 1); PG8_SCHED; PG8_LDA(At, 0, 0); PG8_STAGE(PG8_SA(1, 1), a1 + hstep, voffA);
;             PG8_WAIT_V(8); PG8_WAIT_L(0); PG8_BAR; PG8_MMA(0, 0, At, B0); PG8_MMA(0, 1, At, B1); PG8_BAR; PG8_SCHED;
;             PG8_LDA(At, 0, 1); PG8_STAGE(PG8_SB(0, 0), b2, voffB); PG8_STAGE(PG8_SB(0, 1), b2 + hstep, voffB); PG8_STAGE(PG8_SA(0, 0), a2, voffA);
;             PG8_WAIT_V(8); PG8_WAIT_L(0); PG8_BAR; PG8_MMA(1, 0, At, B0); PG8_MMA(1, 1, At, B1); PG8_BAR; PG8_SCHED;
.LBB0_969:
	ds_read_b128 v[128:131], v191
	ds_read_b128 v[132:135], v191 offset:1024
	ds_read_b128 v[136:139], v191 offset:2048
	ds_read_b128 v[140:143], v191 offset:3072
	ds_read_b128 v[144:147], v192
	ds_read_b128 v[148:151], v192 offset:1024
	ds_read_b128 v[172:175], v192 offset:2048
	ds_read_b128 v[176:179], v192 offset:3072
	s_add_u32 s26, s24, 0xfffc0080
	s_addc_u32 s27, s25, -1
	s_cmp_eq_u32 s57, 12
	s_cselect_b32 s29, s17, s27
	s_cselect_b32 s28, s51, s26
	s_cselect_b32 s27, s15, s56
	s_cselect_b32 s26, s54, s55
	s_add_i32 m0, s39, 0xc000
	ds_read_b128 v[180:183], v193
	ds_read_b128 v[184:187], v193 offset:1024
	ds_read_b128 v[196:199], v193 offset:2048
	ds_read_b128 v[200:203], v193 offset:3072
	ds_read_b128 v[204:207], v193 offset:4096
	ds_read_b128 v[208:211], v193 offset:5120
	ds_read_b128 v[212:215], v193 offset:6144
	ds_read_b128 v[216:219], v193 offset:7168
	global_load_lds_dwordx4 v164, s[24:25]
	s_add_i32 m0, s39, 0xe000
	s_nop 0
	global_load_lds_dwordx4 v166, s[24:25]
	s_waitcnt vmcnt(8)
	s_waitcnt lgkmcnt(0)
	s_barrier
	v_mfma_f32_16x16x32_bf16 v[124:127], v[128:131], v[180:183], v[124:127]
	v_mfma_f32_16x16x32_bf16 v[120:123], v[136:139], v[180:183], v[120:123]
	v_mfma_f32_16x16x32_bf16 v[108:111], v[128:131], v[196:199], v[108:111]
	v_mfma_f32_16x16x32_bf16 v[104:107], v[136:139], v[196:199], v[104:107]
	v_mfma_f32_16x16x32_bf16 v[92:95], v[128:131], v[204:207], v[92:95]
	v_mfma_f32_16x16x32_bf16 v[84:87], v[136:139], v[204:207], v[84:87]
	v_mfma_f32_16x16x32_bf16 v[76:79], v[128:131], v[212:215], v[76:79]
	v_mfma_f32_16x16x32_bf16 v[72:75], v[136:139], v[212:215], v[72:75]
	v_mfma_f32_16x16x32_bf16 v[124:127], v[132:135], v[184:187], v[124:127]
	v_mfma_f32_16x16x32_bf16 v[120:123], v[140:143], v[184:187], v[120:123]
	v_mfma_f32_16x16x32_bf16 v[108:111], v[132:135], v[200:203], v[108:111]
	v_mfma_f32_16x16x32_bf16 v[104:107], v[140:143], v[200:203], v[104:107]
	v_mfma_f32_16x16x32_bf16 v[92:95], v[132:135], v[208:211], v[92:95]
	v_mfma_f32_16x16x32_bf16 v[84:87], v[140:143], v[208:211], v[84:87]
	v_mfma_f32_16x16x32_bf16 v[76:79], v[132:135], v[216:219], v[76:79]
	v_mfma_f32_16x16x32_bf16 v[72:75], v[140:143], v[216:219], v[72:75]
	v_mfma_f32_16x16x32_bf16 v[116:119], v[144:147], v[180:183], v[116:119]
	v_mfma_f32_16x16x32_bf16 v[112:115], v[172:175], v[180:183], v[112:115]
	v_mfma_f32_16x16x32_bf16 v[100:103], v[144:147], v[196:199], v[100:103]
	v_mfma_f32_16x16x32_bf16 v[96:99], v[172:175], v[196:199], v[96:99]
	v_mfma_f32_16x16x32_bf16 v[88:91], v[144:147], v[204:207], v[88:91]
	v_mfma_f32_16x16x32_bf16 v[80:83], v[172:175], v[204:207], v[80:83]
	v_mfma_f32_16x16x32_bf16 v[68:71], v[144:147], v[212:215], v[68:71]
	v_mfma_f32_16x16x32_bf16 v[64:67], v[172:175], v[212:215], v[64:67]
	v_mfma_f32_16x16x32_bf16 v[116:119], v[148:151], v[184:187], v[116:119]
	v_mfma_f32_16x16x32_bf16 v[112:115], v[176:179], v[184:187], v[112:115]
	v_mfma_f32_16x16x32_bf16 v[100:103], v[148:151], v[200:203], v[100:103]
	v_mfma_f32_16x16x32_bf16 v[96:99], v[176:179], v[200:203], v[96:99]
	v_mfma_f32_16x16x32_bf16 v[88:91], v[148:151], v[208:211], v[88:91]
	v_mfma_f32_16x16x32_bf16 v[80:83], v[176:179], v[208:211], v[80:83]
	v_mfma_f32_16x16x32_bf16 v[68:71], v[148:151], v[216:219], v[68:71]
	v_mfma_f32_16x16x32_bf16 v[64:67], v[176:179], v[216:219], v[64:67]
	s_barrier
	s_add_i32 s58, s47, s36
	v_lshl_add_u64 v[220:221], s[26:27], 0, v[156:157]
	s_mov_b32 m0, s58
	ds_read_b128 v[180:183], v193 offset:16384
	ds_read_b128 v[184:187], v193 offset:17408
	ds_read_b128 v[196:199], v193 offset:18432
	ds_read_b128 v[200:203], v193 offset:19456
	ds_read_b128 v[204:207], v193 offset:20480
	ds_read_b128 v[208:211], v193 offset:21504
	ds_read_b128 v[212:215], v193 offset:22528
	ds_read_b128 v[216:219], v193 offset:23552
	global_load_lds_dwordx4 v[220:221], off
	s_add_i32 m0, s58, 0x2000
	s_add_u32 s58, s26, 0x40000
	v_lshl_add_u64 v[222:223], s[26:27], 0, v[152:153]
	s_addc_u32 s59, s27, 0
	s_add_i32 s60, s48, s36
	global_load_lds_dwordx4 v[222:223], off
	s_mov_b32 m0, s60
	v_lshl_add_u64 v[226:227], s[28:29], 0, v[154:155]
	global_load_lds_dwordx4 v156, s[58:59]
	s_add_i32 m0, s60, 0x2000
	s_nop 0
	global_load_lds_dwordx4 v152, s[58:59]
	v_lshl_add_u64 v[224:225], s[28:29], 0, v[158:159]
	s_mov_b32 m0, s39
	s_nop 0
	global_load_lds_dwordx4 v[224:225], off
	s_mov_b32 m0, s40
	s_nop 0
	global_load_lds_dwordx4 v[226:227], off
	s_waitcnt vmcnt(8)
	s_waitcnt lgkmcnt(0)
	s_barrier
	v_mfma_f32_16x16x32_bf16 v[60:63], v[128:131], v[180:183], v[60:63]
	v_mfma_f32_16x16x32_bf16 v[52:55], v[136:139], v[180:183], v[52:55]
	v_mfma_f32_16x16x32_bf16 v[44:47], v[128:131], v[196:199], v[44:47]
	v_mfma_f32_16x16x32_bf16 v[40:43], v[136:139], v[196:199], v[40:43]
	v_mfma_f32_16x16x32_bf16 v[28:31], v[128:131], v[204:207], v[28:31]
	v_mfma_f32_16x16x32_bf16 v[20:23], v[136:139], v[204:207], v[20:23]
	v_mfma_f32_16x16x32_bf16 v[12:15], v[128:131], v[212:215], v[12:15]
	v_mfma_f32_16x16x32_bf16 v[8:11], v[136:139], v[212:215], v[8:11]
	v_mfma_f32_16x16x32_bf16 v[60:63], v[132:135], v[184:187], v[60:63]
	v_mfma_f32_16x16x32_bf16 v[52:55], v[140:143], v[184:187], v[52:55]
	v_mfma_f32_16x16x32_bf16 v[44:47], v[132:135], v[200:203], v[44:47]
	v_mfma_f32_16x16x32_bf16 v[40:43], v[140:143], v[200:203], v[40:43]
	v_mfma_f32_16x16x32_bf16 v[28:31], v[132:135], v[208:211], v[28:31]
	v_mfma_f32_16x16x32_bf16 v[20:23], v[140:143], v[208:211], v[20:23]
	v_mfma_f32_16x16x32_bf16 v[12:15], v[132:135], v[216:219], v[12:15]
	v_mfma_f32_16x16x32_bf16 v[8:11], v[140:143], v[216:219], v[8:11]
	v_mfma_f32_16x16x32_bf16 v[56:59], v[144:147], v[180:183], v[56:59]
	v_mfma_f32_16x16x32_bf16 v[48:51], v[172:175], v[180:183], v[48:51]
	v_mfma_f32_16x16x32_bf16 v[36:39], v[144:147], v[196:199], v[36:39]
	v_mfma_f32_16x16x32_bf16 v[32:35], v[172:175], v[196:199], v[32:35]
	v_mfma_f32_16x16x32_bf16 v[24:27], v[144:147], v[204:207], v[24:27]
	v_mfma_f32_16x16x32_bf16 v[16:19], v[172:175], v[204:207], v[16:19]
	v_mfma_f32_16x16x32_bf16 v[4:7], v[144:147], v[212:215], v[4:7]
	v_mfma_f32_16x16x32_bf16 v[0:3], v[172:175], v[212:215], v[0:3]
	v_mfma_f32_16x16x32_bf16 v[56:59], v[148:151], v[184:187], v[56:59]
	v_mfma_f32_16x16x32_bf16 v[48:51], v[176:179], v[184:187], v[48:51]
	v_mfma_f32_16x16x32_bf16 v[36:39], v[148:151], v[200:203], v[36:39]
	v_mfma_f32_16x16x32_bf16 v[32:35], v[176:179], v[200:203], v[32:35]
	v_mfma_f32_16x16x32_bf16 v[24:27], v[148:151], v[208:211], v[24:27]
	v_mfma_f32_16x16x32_bf16 v[16:19], v[176:179], v[208:211], v[16:19]
	v_mfma_f32_16x16x32_bf16 v[4:7], v[148:151], v[216:219], v[4:7]
	v_mfma_f32_16x16x32_bf16 v[0:3], v[176:179], v[216:219], v[0:3]
	s_barrier
; #define PG8_STAGE(bufoff, gbase, voff) do { _Pragma("unroll") for (int _i = 0; _i < 2; ++_i) \
;         __builtin_amdgcn_global_load_lds((const unsigned*)((const char*)(gbase) + (voff)[_i]), (PG8_LAS unsigned*)(lds + (bufoff) + ldsw + _i * 8192), 16, 0, 0); } while (0)
; #define PG8_LDA(dst, b, h) do { _Pragma("unroll") for (int m = 0; m < 4; ++m) _Pragma("unroll") for (int k = 0; k < 2; ++k) dst[m][k] = *(const PG8_LAS bf16x8*)(lds + PG8_SA(b, h) + aoff + m * 2048 + k * 1024); } while (0)
; #define PG8_LDB(dst, b, h) do { _Pragma("unroll") for (int n = 0; n < 2; ++n) _Pragma("unroll") for (int k = 0; k < 2; ++k) dst[n][k] = *(const PG8_LAS bf16x8*)(lds + PG8_SB(b, h) + boff + n * 2048 + k * 1024); } while (0)
; #define PG8_MMA(ai, bj, At, Bt) do { __builtin_amdgcn_s_setprio(1); _Pragma("unroll") for (int m = 0; m < 4; ++m) _Pragma("unroll") for (int n = 0; n < 2; ++n) _Pragma("unroll") for (int k = 0; k < 2; ++k) \
;         acc[ai][bj][m][n] = __builtin_amdgcn_mfma_f32_16x16x32_bf16(Bt[n][k], At[m][k], acc[ai][bj][m][n], 0, 0, 0); __builtin_amdgcn_s_setprio(0); } while (0)
; #define PG8_WAIT_V(n) asm volatile("s_waitcnt vmcnt(" #n ")" ::: "memory")
; #define PG8_WAIT_L(n) asm volatile("s_waitcnt lgkmcnt(" #n ")" ::: "memory")
; #define PG8_BAR __builtin_amdgcn_s_barrier()
; #define PG8_SCHED __builtin_amdgcn_sched_barrier(0)
; template <class Epi, class Sched, bool ALIGN_EPI = false, bool SP2 = false>
; __device__ __forceinline__ void gemm_phase(PG8_LAS unsigned char* lds, const Gemm g, const Sched& S, const Epi& E) {
;     ...
;             PG8_LDB(B0, 1, 0); PG8_LDB(B1, 1, 1); PG8_SCHED; PG8_LDA(At, 1, 0); PG8_STAGE(PG8_SA(0, 1), a2 + hstep, voffA);
;             PG8_WAIT_V(8); PG8_WAIT_L(0); PG8_BAR; PG8_MMA(0, 0, At, B0); PG8_MMA(0, 1, At, B1); PG8_BAR; PG8_SCHED;
;             PG8_LDA(At, 1, 1); PG8_STAGE(PG8_SB(1, 0), b3, voffB); PG8_STAGE(PG8_SB(1, 1), b3 + hstep, voffB); PG8_STAGE(PG8_SA(1, 0), a3, voffA);
;             PG8_WAIT_V(8); PG8_WAIT_L(0); PG8_BAR; PG8_MMA(1, 0, At, B0); PG8_MMA(1, 1, At, B1); PG8_BAR; PG8_SCHED;
;     ...
;         if constexpr (ALIGN_EPI) { if (wr == 0) PG8_BAR; }
	s_add_i32 s58, 0, 0x18000
	s_add_i32 s59, 0, 0x1c000
	v_add_u32_e32 v140, s58, v190
	v_add_u32_e32 v176, s59, v190
	ds_read_b128 v[128:131], v140
	ds_read_b128 v[132:135], v140 offset:1024
	ds_read_b128 v[136:139], v140 offset:2048
	ds_read_b128 v[140:143], v140 offset:3072
	ds_read_b128 v[144:147], v176
	ds_read_b128 v[148:151], v176 offset:1024
	ds_read_b128 v[172:175], v176 offset:2048
	ds_read_b128 v[176:179], v176 offset:3072
	s_add_u32 s28, s28, 0x40000
	s_addc_u32 s29, s29, 0
	s_mov_b32 m0, s41
	ds_read_b128 v[180:183], v193 offset:32768
	ds_read_b128 v[184:187], v193 offset:33792
	ds_read_b128 v[196:199], v193 offset:34816
	ds_read_b128 v[200:203], v193 offset:35840
	ds_read_b128 v[204:207], v193 offset:36864
	ds_read_b128 v[208:211], v193 offset:37888
	ds_read_b128 v[212:215], v193 offset:38912
	ds_read_b128 v[216:219], v193 offset:39936
	global_load_lds_dwordx4 v158, s[28:29]
	s_mov_b32 m0, s42
	s_nop 0
	global_load_lds_dwordx4 v154, s[28:29]
	s_waitcnt vmcnt(8)
	s_waitcnt lgkmcnt(0)
	s_barrier
	v_mfma_f32_16x16x32_bf16 v[124:127], v[128:131], v[180:183], v[124:127]
	v_mfma_f32_16x16x32_bf16 v[120:123], v[136:139], v[180:183], v[120:123]
	v_mfma_f32_16x16x32_bf16 v[108:111], v[128:131], v[196:199], v[108:111]
	v_mfma_f32_16x16x32_bf16 v[104:107], v[136:139], v[196:199], v[104:107]
	v_mfma_f32_16x16x32_bf16 v[92:95], v[128:131], v[204:207], v[92:95]
	v_mfma_f32_16x16x32_bf16 v[84:87], v[136:139], v[204:207], v[84:87]
	v_mfma_f32_16x16x32_bf16 v[76:79], v[128:131], v[212:215], v[76:79]
	v_mfma_f32_16x16x32_bf16 v[72:75], v[136:139], v[212:215], v[72:75]
	v_mfma_f32_16x16x32_bf16 v[124:127], v[132:135], v[184:187], v[124:127]
	v_mfma_f32_16x16x32_bf16 v[120:123], v[140:143], v[184:187], v[120:123]
	v_mfma_f32_16x16x32_bf16 v[108:111], v[132:135], v[200:203], v[108:111]
	v_mfma_f32_16x16x32_bf16 v[104:107], v[140:143], v[200:203], v[104:107]
	v_mfma_f32_16x16x32_bf16 v[92:95], v[132:135], v[208:211], v[92:95]
	v_mfma_f32_16x16x32_bf16 v[84:87], v[140:143], v[208:211], v[84:87]
	v_mfma_f32_16x16x32_bf16 v[76:79], v[132:135], v[216:219], v[76:79]
	v_mfma_f32_16x16x32_bf16 v[72:75], v[140:143], v[216:219], v[72:75]
	v_mfma_f32_16x16x32_bf16 v[116:119], v[144:147], v[180:183], v[116:119]
	v_mfma_f32_16x16x32_bf16 v[112:115], v[172:175], v[180:183], v[112:115]
	v_mfma_f32_16x16x32_bf16 v[100:103], v[144:147], v[196:199], v[100:103]
	v_mfma_f32_16x16x32_bf16 v[96:99], v[172:175], v[196:199], v[96:99]
	v_mfma_f32_16x16x32_bf16 v[88:91], v[144:147], v[204:207], v[88:91]
	v_mfma_f32_16x16x32_bf16 v[80:83], v[172:175], v[204:207], v[80:83]
	v_mfma_f32_16x16x32_bf16 v[68:71], v[144:147], v[212:215], v[68:71]
	v_mfma_f32_16x16x32_bf16 v[64:67], v[172:175], v[212:215], v[64:67]
	v_mfma_f32_16x16x32_bf16 v[116:119], v[148:151], v[184:187], v[116:119]
	v_mfma_f32_16x16x32_bf16 v[112:115], v[176:179], v[184:187], v[112:115]
	v_mfma_f32_16x16x32_bf16 v[100:103], v[148:151], v[200:203], v[100:103]
	v_mfma_f32_16x16x32_bf16 v[96:99], v[176:179], v[200:203], v[96:99]
	v_mfma_f32_16x16x32_bf16 v[88:91], v[148:151], v[208:211], v[88:91]
	v_mfma_f32_16x16x32_bf16 v[80:83], v[176:179], v[208:211], v[80:83]
	v_mfma_f32_16x16x32_bf16 v[68:71], v[148:151], v[216:219], v[68:71]
	v_mfma_f32_16x16x32_bf16 v[64:67], v[176:179], v[216:219], v[64:67]
	s_barrier
	s_add_i32 s28, s58, s36
	v_lshl_add_u64 v[220:221], v[220:221], 0, s[10:11]
	s_mov_b32 m0, s28
	ds_read_b128 v[180:183], v193 offset:49152
	ds_read_b128 v[184:187], v193 offset:50176
	ds_read_b128 v[196:199], v193 offset:51200
	ds_read_b128 v[200:203], v193 offset:52224
	ds_read_b128 v[204:207], v193 offset:53248
	ds_read_b128 v[208:211], v193 offset:54272
	ds_read_b128 v[212:215], v193 offset:55296
	ds_read_b128 v[216:219], v193 offset:56320
	global_load_lds_dwordx4 v[220:221], off
	s_add_i32 m0, s28, 0x2000
	s_add_u32 s26, s26, 0x40080
	v_lshl_add_u64 v[220:221], v[222:223], 0, s[10:11]
	s_addc_u32 s27, s27, 0
	s_add_i32 s28, s59, s36
	global_load_lds_dwordx4 v[220:221], off
	s_mov_b32 m0, s28
	s_nop 0
	global_load_lds_dwordx4 v156, s[26:27]
	s_add_i32 m0, s28, 0x2000
	s_nop 0
	global_load_lds_dwordx4 v152, s[26:27]
	v_lshl_add_u64 v[220:221], v[224:225], 0, s[10:11]
	s_mov_b32 m0, s43
	s_nop 0
	global_load_lds_dwordx4 v[220:221], off
	v_lshl_add_u64 v[220:221], v[226:227], 0, s[10:11]
	s_mov_b32 m0, s44
	s_nop 0
	global_load_lds_dwordx4 v[220:221], off
	s_waitcnt vmcnt(8)
	s_waitcnt lgkmcnt(0)
	s_barrier
	v_mfma_f32_16x16x32_bf16 v[60:63], v[128:131], v[180:183], v[60:63]
	v_mfma_f32_16x16x32_bf16 v[52:55], v[136:139], v[180:183], v[52:55]
	v_mfma_f32_16x16x32_bf16 v[44:47], v[128:131], v[196:199], v[44:47]
	v_mfma_f32_16x16x32_bf16 v[40:43], v[136:139], v[196:199], v[40:43]
	v_mfma_f32_16x16x32_bf16 v[28:31], v[128:131], v[204:207], v[28:31]
	v_mfma_f32_16x16x32_bf16 v[20:23], v[136:139], v[204:207], v[20:23]
	v_mfma_f32_16x16x32_bf16 v[12:15], v[128:131], v[212:215], v[12:15]
	v_mfma_f32_16x16x32_bf16 v[8:11], v[136:139], v[212:215], v[8:11]
	v_mfma_f32_16x16x32_bf16 v[60:63], v[132:135], v[184:187], v[60:63]
	v_mfma_f32_16x16x32_bf16 v[52:55], v[140:143], v[184:187], v[52:55]
	v_mfma_f32_16x16x32_bf16 v[44:47], v[132:135], v[200:203], v[44:47]
	v_mfma_f32_16x16x32_bf16 v[40:43], v[140:143], v[200:203], v[40:43]
	v_mfma_f32_16x16x32_bf16 v[28:31], v[132:135], v[208:211], v[28:31]
	v_mfma_f32_16x16x32_bf16 v[20:23], v[140:143], v[208:211], v[20:23]
	v_mfma_f32_16x16x32_bf16 v[12:15], v[132:135], v[216:219], v[12:15]
	v_mfma_f32_16x16x32_bf16 v[8:11], v[140:143], v[216:219], v[8:11]
	v_mfma_f32_16x16x32_bf16 v[56:59], v[144:147], v[180:183], v[56:59]
	v_mfma_f32_16x16x32_bf16 v[48:51], v[172:175], v[180:183], v[48:51]
	v_mfma_f32_16x16x32_bf16 v[36:39], v[144:147], v[196:199], v[36:39]
	v_mfma_f32_16x16x32_bf16 v[32:35], v[172:175], v[196:199], v[32:35]
	v_mfma_f32_16x16x32_bf16 v[24:27], v[144:147], v[204:207], v[24:27]
	v_mfma_f32_16x16x32_bf16 v[16:19], v[172:175], v[204:207], v[16:19]
	v_mfma_f32_16x16x32_bf16 v[4:7], v[144:147], v[212:215], v[4:7]
	v_mfma_f32_16x16x32_bf16 v[0:3], v[172:175], v[212:215], v[0:3]
	v_mfma_f32_16x16x32_bf16 v[56:59], v[148:151], v[184:187], v[56:59]
	v_mfma_f32_16x16x32_bf16 v[48:51], v[176:179], v[184:187], v[48:51]
	v_mfma_f32_16x16x32_bf16 v[36:39], v[148:151], v[200:203], v[36:39]
	v_mfma_f32_16x16x32_bf16 v[32:35], v[176:179], v[200:203], v[32:35]
	v_mfma_f32_16x16x32_bf16 v[24:27], v[148:151], v[208:211], v[24:27]
	v_mfma_f32_16x16x32_bf16 v[16:19], v[176:179], v[208:211], v[16:19]
	v_mfma_f32_16x16x32_bf16 v[4:7], v[148:151], v[216:219], v[4:7]
	v_mfma_f32_16x16x32_bf16 v[0:3], v[176:179], v[216:219], v[0:3]
	s_barrier
	s_add_i32 s57, s57, 2
	s_add_u32 s24, s24, 0x100
	s_addc_u32 s25, s25, 0
	s_add_u32 s55, s55, 0x100
	s_addc_u32 s56, s56, 0
	s_cmp_gt_u32 s57, 13
	s_cbranch_scc0 .LBB0_969
	s_and_b64 vcc, exec, s[12:13]
	s_cbranch_vccz .LBB0_972
	s_barrier

; #define PG8_STAGE(bufoff, gbase, voff) do { _Pragma("unroll") for (int _i = 0; _i < 2; ++_i) \
;         __builtin_amdgcn_global_load_lds((const unsigned*)((const char*)(gbase) + (voff)[_i]), (PG8_LAS unsigned*)(lds + (bufoff) + ldsw + _i * 8192), 16, 0, 0); } while (0)
; #define PG8_LDA(dst, b, h) do { _Pragma("unroll") for (int m = 0; m < 4; ++m) _Pragma("unroll") for (int k = 0; k < 2; ++k) dst[m][k] = *(const PG8_LAS bf16x8*)(lds + PG8_SA(b, h) + aoff + m * 2048 + k * 1024); } while (0)
; #define PG8_LDB(dst, b, h) do { _Pragma("unroll") for (int n = 0; n < 2; ++n) _Pragma("unroll") for (int k = 0; k < 2; ++k) dst[n][k] = *(const PG8_LAS bf16x8*)(lds + PG8_SB(b, h) + boff + n * 2048 + k * 1024); } while (0)
; #define PG8_MMA(ai, bj, At, Bt) do { __builtin_amdgcn_s_setprio(1); _Pragma("unroll") for (int m = 0; m < 4; ++m) _Pragma("unroll") for (int n = 0; n < 2; ++n) _Pragma("unroll") for (int k = 0; k < 2; ++k) \
;         acc[ai][bj][m][n] = __builtin_amdgcn_mfma_f32_16x16x32_bf16(Bt[n][k], At[m][k], acc[ai][bj][m][n], 0, 0, 0); __builtin_amdgcn_s_setprio(0); } while (0)
; #define PG8_WAIT_V(n) asm volatile("s_waitcnt vmcnt(" #n ")" ::: "memory")
; #define PG8_BAR __builtin_amdgcn_s_barrier()
; template <class Epi, class Sched, bool ALIGN_EPI = false, bool SP2 = false>
; __device__ __forceinline__ void gemm_phase(PG8_LAS unsigned char* lds, const Gemm g, const Sched& S, const Epi& E) {
;     ...
;         for (int t = 0; t < nt; t += 2) {
;             const bool last = (t == nt - 2);
;             const char* a1 = cA + (size_t)(t + 1) * kstep;
;             const char* a2 = last ? nA : cA + (size_t)(t + 2) * kstep; const char* b2 = last ? nB : cB + (size_t)(t + 2) * kstep;
;             const char* a3 = a2 + kstep; const char* b3 = b2 + kstep;
;             if (last && has_next) S.a_ready(nxt);
;             if constexpr (SP2) {
;             PG8_LDB(B0, 0, 0); PG8_LDB(B1, 0, 1); PG8_SCHED; PG8_LDA(At, 0, 0); PG8_STAGE(PG8_SA(1, 1), a1 + hstep, voffA);
;             PG8_WAIT_V(8); PG8_WAIT_L(0); PG8_BAR; PG8_MMA(0, 0, At, B0); PG8_MMA(0, 1, At, B1); PG8_BAR; PG8_SCHED;
;             PG8_LDA(At, 0, 1); PG8_STAGE(PG8_SB(0, 0), b2, voffB); PG8_STAGE(PG8_SB(0, 1), b2 + hstep, voffB); PG8_STAGE(PG8_SA(0, 0), a2, voffA);
;             PG8_WAIT_V(8); PG8_WAIT_L(0); PG8_BAR; PG8_MMA(1, 0, At, B0); PG8_MMA(1, 1, At, B1); PG8_BAR; PG8_SCHED;
.LBB0_1052:
	ds_read_b128 v[146:149], v153
	ds_read_b128 v[156:159], v153 offset:1024
	ds_read_b128 v[160:163], v153 offset:2048
	ds_read_b128 v[164:167], v153 offset:3072
	ds_read_b128 v[168:171], v154
	ds_read_b128 v[172:175], v154 offset:1024
	ds_read_b128 v[176:179], v154 offset:2048
	ds_read_b128 v[180:183], v154 offset:3072
	s_add_u32 s24, s22, 0x100
	s_addc_u32 s25, s23, 0
	s_cmp_eq_u32 s56, 40
	s_cselect_b32 s29, s3, s25
	s_cselect_b32 s28, s2, s24
	s_cselect_b32 s27, s21, s55
	s_cselect_b32 s26, s20, s54
	s_add_i32 m0, s38, 0xc000
	ds_read_b128 v[184:187], v155
	ds_read_b128 v[188:191], v155 offset:1024
	ds_read_b128 v[192:195], v155 offset:2048
	ds_read_b128 v[196:199], v155 offset:3072
	ds_read_b128 v[200:203], v155 offset:4096
	ds_read_b128 v[204:207], v155 offset:5120
	ds_read_b128 v[208:211], v155 offset:6144
	ds_read_b128 v[212:215], v155 offset:7168
	global_load_lds_dwordx4 v138, s[22:23]
	s_add_i32 m0, s38, 0xe000
	s_nop 0
	global_load_lds_dwordx4 v140, s[22:23]
	s_waitcnt vmcnt(8)
	s_waitcnt lgkmcnt(0)
	s_barrier
	v_mfma_f32_16x16x32_bf16 v[124:127], v[146:149], v[184:187], v[124:127]
	v_mfma_f32_16x16x32_bf16 v[120:123], v[160:163], v[184:187], v[120:123]
	v_mfma_f32_16x16x32_bf16 v[116:119], v[146:149], v[192:195], v[116:119]
	v_mfma_f32_16x16x32_bf16 v[112:115], v[160:163], v[192:195], v[112:115]
	v_mfma_f32_16x16x32_bf16 v[92:95], v[146:149], v[200:203], v[92:95]
	v_mfma_f32_16x16x32_bf16 v[88:91], v[160:163], v[200:203], v[88:91]
	v_mfma_f32_16x16x32_bf16 v[76:79], v[146:149], v[208:211], v[76:79]
	v_mfma_f32_16x16x32_bf16 v[72:75], v[160:163], v[208:211], v[72:75]
	v_mfma_f32_16x16x32_bf16 v[124:127], v[156:159], v[188:191], v[124:127]
	v_mfma_f32_16x16x32_bf16 v[120:123], v[164:167], v[188:191], v[120:123]
	v_mfma_f32_16x16x32_bf16 v[116:119], v[156:159], v[196:199], v[116:119]
	v_mfma_f32_16x16x32_bf16 v[112:115], v[164:167], v[196:199], v[112:115]
	v_mfma_f32_16x16x32_bf16 v[92:95], v[156:159], v[204:207], v[92:95]
	v_mfma_f32_16x16x32_bf16 v[88:91], v[164:167], v[204:207], v[88:91]
	v_mfma_f32_16x16x32_bf16 v[76:79], v[156:159], v[212:215], v[76:79]
	v_mfma_f32_16x16x32_bf16 v[72:75], v[164:167], v[212:215], v[72:75]
	v_mfma_f32_16x16x32_bf16 v[108:111], v[168:171], v[184:187], v[108:111]
	v_mfma_f32_16x16x32_bf16 v[104:107], v[176:179], v[184:187], v[104:107]
	v_mfma_f32_16x16x32_bf16 v[100:103], v[168:171], v[192:195], v[100:103]
	v_mfma_f32_16x16x32_bf16 v[96:99], v[176:179], v[192:195], v[96:99]
	v_mfma_f32_16x16x32_bf16 v[84:87], v[168:171], v[200:203], v[84:87]
	v_mfma_f32_16x16x32_bf16 v[80:83], v[176:179], v[200:203], v[80:83]
	v_mfma_f32_16x16x32_bf16 v[68:71], v[168:171], v[208:211], v[68:71]
	v_mfma_f32_16x16x32_bf16 v[64:67], v[176:179], v[208:211], v[64:67]
	v_mfma_f32_16x16x32_bf16 v[108:111], v[172:175], v[188:191], v[108:111]
	v_mfma_f32_16x16x32_bf16 v[104:107], v[180:183], v[188:191], v[104:107]
	v_mfma_f32_16x16x32_bf16 v[100:103], v[172:175], v[196:199], v[100:103]
	v_mfma_f32_16x16x32_bf16 v[96:99], v[180:183], v[196:199], v[96:99]
	v_mfma_f32_16x16x32_bf16 v[84:87], v[172:175], v[204:207], v[84:87]
	v_mfma_f32_16x16x32_bf16 v[80:83], v[180:183], v[204:207], v[80:83]
	v_mfma_f32_16x16x32_bf16 v[68:71], v[172:175], v[212:215], v[68:71]
	v_mfma_f32_16x16x32_bf16 v[64:67], v[180:183], v[212:215], v[64:67]
	s_barrier
	s_add_i32 s22, s46, s37
	v_lshl_add_u64 v[150:151], s[26:27], 0, v[130:131]
	s_mov_b32 m0, s22
	ds_read_b128 v[184:187], v155 offset:16384
	ds_read_b128 v[188:191], v155 offset:17408
	ds_read_b128 v[192:195], v155 offset:18432
	ds_read_b128 v[196:199], v155 offset:19456
	ds_read_b128 v[200:203], v155 offset:20480
	ds_read_b128 v[204:207], v155 offset:21504
	ds_read_b128 v[208:211], v155 offset:22528
	ds_read_b128 v[212:215], v155 offset:23552
	global_load_lds_dwordx4 v[150:151], off
	s_add_i32 m0, s22, 0x2000
	s_add_u32 s22, s26, 0xb0000
	v_lshl_add_u64 v[216:217], s[26:27], 0, v[134:135]
	s_addc_u32 s23, s27, 0
	s_add_i32 s57, s47, s37
	global_load_lds_dwordx4 v[216:217], off
	s_mov_b32 m0, s57
	v_lshl_add_u64 v[220:221], s[28:29], 0, v[132:133]
	global_load_lds_dwordx4 v130, s[22:23]
	s_add_i32 m0, s57, 0x2000
	s_nop 0
	global_load_lds_dwordx4 v134, s[22:23]
	v_lshl_add_u64 v[218:219], s[28:29], 0, v[128:129]
	s_mov_b32 m0, s38
	s_nop 0
	global_load_lds_dwordx4 v[218:219], off
	s_mov_b32 m0, s39
	s_nop 0
	global_load_lds_dwordx4 v[220:221], off
	s_waitcnt vmcnt(8)
	s_waitcnt lgkmcnt(0)
	s_barrier
	v_mfma_f32_16x16x32_bf16 v[60:63], v[146:149], v[184:187], v[60:63]
	v_mfma_f32_16x16x32_bf16 v[56:59], v[160:163], v[184:187], v[56:59]
	v_mfma_f32_16x16x32_bf16 v[44:47], v[146:149], v[192:195], v[44:47]
	v_mfma_f32_16x16x32_bf16 v[40:43], v[160:163], v[192:195], v[40:43]
	v_mfma_f32_16x16x32_bf16 v[28:31], v[146:149], v[200:203], v[28:31]
	v_mfma_f32_16x16x32_bf16 v[24:27], v[160:163], v[200:203], v[24:27]
	v_mfma_f32_16x16x32_bf16 v[12:15], v[146:149], v[208:211], v[12:15]
	v_mfma_f32_16x16x32_bf16 v[8:11], v[160:163], v[208:211], v[8:11]
	v_mfma_f32_16x16x32_bf16 v[60:63], v[156:159], v[188:191], v[60:63]
	v_mfma_f32_16x16x32_bf16 v[56:59], v[164:167], v[188:191], v[56:59]
	v_mfma_f32_16x16x32_bf16 v[44:47], v[156:159], v[196:199], v[44:47]
	v_mfma_f32_16x16x32_bf16 v[40:43], v[164:167], v[196:199], v[40:43]
	v_mfma_f32_16x16x32_bf16 v[28:31], v[156:159], v[204:207], v[28:31]
	v_mfma_f32_16x16x32_bf16 v[24:27], v[164:167], v[204:207], v[24:27]
	v_mfma_f32_16x16x32_bf16 v[12:15], v[156:159], v[212:215], v[12:15]
	v_mfma_f32_16x16x32_bf16 v[8:11], v[164:167], v[212:215], v[8:11]
	v_mfma_f32_16x16x32_bf16 v[52:55], v[168:171], v[184:187], v[52:55]
	v_mfma_f32_16x16x32_bf16 v[48:51], v[176:179], v[184:187], v[48:51]
	v_mfma_f32_16x16x32_bf16 v[36:39], v[168:171], v[192:195], v[36:39]
	v_mfma_f32_16x16x32_bf16 v[32:35], v[176:179], v[192:195], v[32:35]
	v_mfma_f32_16x16x32_bf16 v[20:23], v[168:171], v[200:203], v[20:23]
	v_mfma_f32_16x16x32_bf16 v[16:19], v[176:179], v[200:203], v[16:19]
	v_mfma_f32_16x16x32_bf16 v[4:7], v[168:171], v[208:211], v[4:7]
	v_mfma_f32_16x16x32_bf16 v[0:3], v[176:179], v[208:211], v[0:3]
	v_mfma_f32_16x16x32_bf16 v[52:55], v[172:175], v[188:191], v[52:55]
	v_mfma_f32_16x16x32_bf16 v[48:51], v[180:183], v[188:191], v[48:51]
	v_mfma_f32_16x16x32_bf16 v[36:39], v[172:175], v[196:199], v[36:39]
	v_mfma_f32_16x16x32_bf16 v[32:35], v[180:183], v[196:199], v[32:35]
	v_mfma_f32_16x16x32_bf16 v[20:23], v[172:175], v[204:207], v[20:23]
	v_mfma_f32_16x16x32_bf16 v[16:19], v[180:183], v[204:207], v[16:19]
	v_mfma_f32_16x16x32_bf16 v[4:7], v[172:175], v[212:215], v[4:7]
	v_mfma_f32_16x16x32_bf16 v[0:3], v[180:183], v[212:215], v[0:3]
	s_barrier
; #define PG8_STAGE(bufoff, gbase, voff) do { _Pragma("unroll") for (int _i = 0; _i < 2; ++_i) \
;         __builtin_amdgcn_global_load_lds((const unsigned*)((const char*)(gbase) + (voff)[_i]), (PG8_LAS unsigned*)(lds + (bufoff) + ldsw + _i * 8192), 16, 0, 0); } while (0)
; #define PG8_LDA(dst, b, h) do { _Pragma("unroll") for (int m = 0; m < 4; ++m) _Pragma("unroll") for (int k = 0; k < 2; ++k) dst[m][k] = *(const PG8_LAS bf16x8*)(lds + PG8_SA(b, h) + aoff + m * 2048 + k * 1024); } while (0)
; #define PG8_LDB(dst, b, h) do { _Pragma("unroll") for (int n = 0; n < 2; ++n) _Pragma("unroll") for (int k = 0; k < 2; ++k) dst[n][k] = *(const PG8_LAS bf16x8*)(lds + PG8_SB(b, h) + boff + n * 2048 + k * 1024); } while (0)
; #define PG8_MMA(ai, bj, At, Bt) do { __builtin_amdgcn_s_setprio(1); _Pragma("unroll") for (int m = 0; m < 4; ++m) _Pragma("unroll") for (int n = 0; n < 2; ++n) _Pragma("unroll") for (int k = 0; k < 2; ++k) \
;         acc[ai][bj][m][n] = __builtin_amdgcn_mfma_f32_16x16x32_bf16(Bt[n][k], At[m][k], acc[ai][bj][m][n], 0, 0, 0); __builtin_amdgcn_s_setprio(0); } while (0)
; #define PG8_WAIT_V(n) asm volatile("s_waitcnt vmcnt(" #n ")" ::: "memory")
; #define PG8_WAIT_L(n) asm volatile("s_waitcnt lgkmcnt(" #n ")" ::: "memory")
; #define PG8_BAR __builtin_amdgcn_s_barrier()
; #define PG8_SCHED __builtin_amdgcn_sched_barrier(0)
; template <class Epi, class Sched, bool ALIGN_EPI = false, bool SP2 = false>
; __device__ __forceinline__ void gemm_phase(PG8_LAS unsigned char* lds, const Gemm g, const Sched& S, const Epi& E) {
;     ...
;             PG8_LDB(B0, 1, 0); PG8_LDB(B1, 1, 1); PG8_SCHED; PG8_LDA(At, 1, 0); PG8_STAGE(PG8_SA(0, 1), a2 + hstep, voffA);
;             PG8_WAIT_V(8); PG8_WAIT_L(0); PG8_BAR; PG8_MMA(0, 0, At, B0); PG8_MMA(0, 1, At, B1); PG8_BAR; PG8_SCHED;
;             PG8_LDA(At, 1, 1); PG8_STAGE(PG8_SB(1, 0), b3, voffB); PG8_STAGE(PG8_SB(1, 1), b3 + hstep, voffB); PG8_STAGE(PG8_SA(1, 0), a3, voffA);
;             PG8_WAIT_V(8); PG8_WAIT_L(0); PG8_BAR; PG8_MMA(1, 0, At, B0); PG8_MMA(1, 1, At, B1); PG8_BAR; PG8_SCHED;
;     ...
;         if constexpr (ALIGN_EPI) { if (wr == 0) PG8_BAR; }
	s_add_i32 s57, 0, 0x18000
	s_add_i32 s58, 0, 0x1c000
	v_add_u32_e32 v164, s57, v152
	v_add_u32_e32 v180, s58, v152
	ds_read_b128 v[146:149], v164
	ds_read_b128 v[156:159], v164 offset:1024
	ds_read_b128 v[160:163], v164 offset:2048
	ds_read_b128 v[164:167], v164 offset:3072
	ds_read_b128 v[168:171], v180
	ds_read_b128 v[172:175], v180 offset:1024
	ds_read_b128 v[176:179], v180 offset:2048
	ds_read_b128 v[180:183], v180 offset:3072
	s_add_u32 s22, s28, 0xb0000
	s_addc_u32 s23, s29, 0
	s_mov_b32 m0, s40
	ds_read_b128 v[184:187], v155 offset:32768
	ds_read_b128 v[188:191], v155 offset:33792
	ds_read_b128 v[192:195], v155 offset:34816
	ds_read_b128 v[196:199], v155 offset:35840
	ds_read_b128 v[200:203], v155 offset:36864
	ds_read_b128 v[204:207], v155 offset:37888
	ds_read_b128 v[208:211], v155 offset:38912
	ds_read_b128 v[212:215], v155 offset:39936
	global_load_lds_dwordx4 v128, s[22:23]
	s_mov_b32 m0, s41
	s_nop 0
	global_load_lds_dwordx4 v132, s[22:23]
	s_waitcnt vmcnt(8)
	s_waitcnt lgkmcnt(0)
	s_barrier
	v_mfma_f32_16x16x32_bf16 v[124:127], v[146:149], v[184:187], v[124:127]
	v_mfma_f32_16x16x32_bf16 v[120:123], v[160:163], v[184:187], v[120:123]
	v_mfma_f32_16x16x32_bf16 v[116:119], v[146:149], v[192:195], v[116:119]
	v_mfma_f32_16x16x32_bf16 v[112:115], v[160:163], v[192:195], v[112:115]
	v_mfma_f32_16x16x32_bf16 v[92:95], v[146:149], v[200:203], v[92:95]
	v_mfma_f32_16x16x32_bf16 v[88:91], v[160:163], v[200:203], v[88:91]
	v_mfma_f32_16x16x32_bf16 v[76:79], v[146:149], v[208:211], v[76:79]
	v_mfma_f32_16x16x32_bf16 v[72:75], v[160:163], v[208:211], v[72:75]
	v_mfma_f32_16x16x32_bf16 v[124:127], v[156:159], v[188:191], v[124:127]
	v_mfma_f32_16x16x32_bf16 v[120:123], v[164:167], v[188:191], v[120:123]
	v_mfma_f32_16x16x32_bf16 v[116:119], v[156:159], v[196:199], v[116:119]
	v_mfma_f32_16x16x32_bf16 v[112:115], v[164:167], v[196:199], v[112:115]
	v_mfma_f32_16x16x32_bf16 v[92:95], v[156:159], v[204:207], v[92:95]
	v_mfma_f32_16x16x32_bf16 v[88:91], v[164:167], v[204:207], v[88:91]
	v_mfma_f32_16x16x32_bf16 v[76:79], v[156:159], v[212:215], v[76:79]
	v_mfma_f32_16x16x32_bf16 v[72:75], v[164:167], v[212:215], v[72:75]
	v_mfma_f32_16x16x32_bf16 v[108:111], v[168:171], v[184:187], v[108:111]
	v_mfma_f32_16x16x32_bf16 v[104:107], v[176:179], v[184:187], v[104:107]
	v_mfma_f32_16x16x32_bf16 v[100:103], v[168:171], v[192:195], v[100:103]
	v_mfma_f32_16x16x32_bf16 v[96:99], v[176:179], v[192:195], v[96:99]
	v_mfma_f32_16x16x32_bf16 v[84:87], v[168:171], v[200:203], v[84:87]
	v_mfma_f32_16x16x32_bf16 v[80:83], v[176:179], v[200:203], v[80:83]
	v_mfma_f32_16x16x32_bf16 v[68:71], v[168:171], v[208:211], v[68:71]
	v_mfma_f32_16x16x32_bf16 v[64:67], v[176:179], v[208:211], v[64:67]
	v_mfma_f32_16x16x32_bf16 v[108:111], v[172:175], v[188:191], v[108:111]
	v_mfma_f32_16x16x32_bf16 v[104:107], v[180:183], v[188:191], v[104:107]
	v_mfma_f32_16x16x32_bf16 v[100:103], v[172:175], v[196:199], v[100:103]
	v_mfma_f32_16x16x32_bf16 v[96:99], v[180:183], v[196:199], v[96:99]
	v_mfma_f32_16x16x32_bf16 v[84:87], v[172:175], v[204:207], v[84:87]
	v_mfma_f32_16x16x32_bf16 v[80:83], v[180:183], v[204:207], v[80:83]
	v_mfma_f32_16x16x32_bf16 v[68:71], v[172:175], v[212:215], v[68:71]
	v_mfma_f32_16x16x32_bf16 v[64:67], v[180:183], v[212:215], v[64:67]
	s_barrier
	s_add_i32 s22, s57, s37
	v_lshl_add_u64 v[150:151], v[150:151], 0, s[8:9]
	s_mov_b32 m0, s22
	ds_read_b128 v[184:187], v155 offset:49152
	ds_read_b128 v[188:191], v155 offset:50176
	ds_read_b128 v[192:195], v155 offset:51200
	ds_read_b128 v[196:199], v155 offset:52224
	ds_read_b128 v[200:203], v155 offset:53248
	ds_read_b128 v[204:207], v155 offset:54272
	ds_read_b128 v[208:211], v155 offset:55296
	ds_read_b128 v[212:215], v155 offset:56320
	global_load_lds_dwordx4 v[150:151], off
	s_add_i32 m0, s22, 0x2000
	s_add_u32 s22, s26, 0xb0080
	v_lshl_add_u64 v[150:151], v[216:217], 0, s[8:9]
	s_addc_u32 s23, s27, 0
	s_add_i32 s26, s58, s37
	global_load_lds_dwordx4 v[150:151], off
	s_mov_b32 m0, s26
	s_nop 0
	global_load_lds_dwordx4 v130, s[22:23]
	s_add_i32 m0, s26, 0x2000
	s_nop 0
	global_load_lds_dwordx4 v134, s[22:23]
	v_lshl_add_u64 v[150:151], v[218:219], 0, s[8:9]
	s_mov_b32 m0, s43
	s_nop 0
	global_load_lds_dwordx4 v[150:151], off
	v_lshl_add_u64 v[150:151], v[220:221], 0, s[8:9]
	s_mov_b32 m0, s44
	s_nop 0
	global_load_lds_dwordx4 v[150:151], off
	s_waitcnt vmcnt(8)
	s_waitcnt lgkmcnt(0)
	s_barrier
	v_mfma_f32_16x16x32_bf16 v[60:63], v[146:149], v[184:187], v[60:63]
	v_mfma_f32_16x16x32_bf16 v[56:59], v[160:163], v[184:187], v[56:59]
	v_mfma_f32_16x16x32_bf16 v[44:47], v[146:149], v[192:195], v[44:47]
	v_mfma_f32_16x16x32_bf16 v[40:43], v[160:163], v[192:195], v[40:43]
	v_mfma_f32_16x16x32_bf16 v[28:31], v[146:149], v[200:203], v[28:31]
	v_mfma_f32_16x16x32_bf16 v[24:27], v[160:163], v[200:203], v[24:27]
	v_mfma_f32_16x16x32_bf16 v[12:15], v[146:149], v[208:211], v[12:15]
	v_mfma_f32_16x16x32_bf16 v[8:11], v[160:163], v[208:211], v[8:11]
	v_mfma_f32_16x16x32_bf16 v[60:63], v[156:159], v[188:191], v[60:63]
	v_mfma_f32_16x16x32_bf16 v[56:59], v[164:167], v[188:191], v[56:59]
	v_mfma_f32_16x16x32_bf16 v[44:47], v[156:159], v[196:199], v[44:47]
	v_mfma_f32_16x16x32_bf16 v[40:43], v[164:167], v[196:199], v[40:43]
	v_mfma_f32_16x16x32_bf16 v[28:31], v[156:159], v[204:207], v[28:31]
	v_mfma_f32_16x16x32_bf16 v[24:27], v[164:167], v[204:207], v[24:27]
	v_mfma_f32_16x16x32_bf16 v[12:15], v[156:159], v[212:215], v[12:15]
	v_mfma_f32_16x16x32_bf16 v[8:11], v[164:167], v[212:215], v[8:11]
	v_mfma_f32_16x16x32_bf16 v[52:55], v[168:171], v[184:187], v[52:55]
	v_mfma_f32_16x16x32_bf16 v[48:51], v[176:179], v[184:187], v[48:51]
	v_mfma_f32_16x16x32_bf16 v[36:39], v[168:171], v[192:195], v[36:39]
	v_mfma_f32_16x16x32_bf16 v[32:35], v[176:179], v[192:195], v[32:35]
	v_mfma_f32_16x16x32_bf16 v[20:23], v[168:171], v[200:203], v[20:23]
	v_mfma_f32_16x16x32_bf16 v[16:19], v[176:179], v[200:203], v[16:19]
	v_mfma_f32_16x16x32_bf16 v[4:7], v[168:171], v[208:211], v[4:7]
	v_mfma_f32_16x16x32_bf16 v[0:3], v[176:179], v[208:211], v[0:3]
	v_mfma_f32_16x16x32_bf16 v[52:55], v[172:175], v[188:191], v[52:55]
	v_mfma_f32_16x16x32_bf16 v[48:51], v[180:183], v[188:191], v[48:51]
	v_mfma_f32_16x16x32_bf16 v[36:39], v[172:175], v[196:199], v[36:39]
	v_mfma_f32_16x16x32_bf16 v[32:35], v[180:183], v[196:199], v[32:35]
	v_mfma_f32_16x16x32_bf16 v[20:23], v[172:175], v[204:207], v[20:23]
	v_mfma_f32_16x16x32_bf16 v[16:19], v[180:183], v[204:207], v[16:19]
	v_mfma_f32_16x16x32_bf16 v[4:7], v[172:175], v[212:215], v[4:7]
	v_mfma_f32_16x16x32_bf16 v[0:3], v[180:183], v[212:215], v[0:3]
	s_barrier
	s_add_i32 s56, s56, 2
	s_add_u32 s54, s54, 0x100
	s_addc_u32 s55, s55, 0
	s_cmp_gt_u32 s56, 41
	s_mov_b64 s[22:23], s[24:25]
	s_cbranch_scc0 .LBB0_1052
	s_and_b64 vcc, exec, s[10:11]
	s_cbranch_vccz .LBB0_1055
	s_barrier
